# SGPR-base K/V prefetch addresses in the 3 attention loops, deferred cross-half row-sum, SGPR-base LDS-DMA addresses in GEMM loops
# speedup vs baseline: 1.0132x; 1.0111x over previous
;     __device__ bool next(int i, Unit& u) const { if (i != 0) return false; u.pm = pm; u.pn = pn; return true; }
; #define PG8_STAGE(bufoff, gbase, voff) do { _Pragma("unroll") for (int _i = 0; _i < 2; ++_i) \
;         __builtin_amdgcn_global_load_lds((const unsigned*)((const char*)(gbase) + (voff)[_i]), (LAS unsigned*)(lds + (bufoff) + ldsw + _i * 8192), 16, 0, 0); } while (0)
; #define PG8_WAIT_V(n) asm volatile("s_waitcnt vmcnt(" #n ")" ::: "memory")
; #define PG8_BAR __builtin_amdgcn_s_barrier()
; template <class Epi, class Sched>
; __device__ __forceinline__ void gemm_phase(LAS unsigned char* lds, const Gemm g, const Sched& S, const Epi& E, int tid_in) {
;     ...
;     const int aoff = lds_byte(wr * 64 + fr, fq * 8), boff = lds_byte(wc * 32 + fr, fq * 8);
;     ...
;     Unit cur, nxt; int ui = 0;
;     if (!S.next(0, cur)) return;
;     f32x4 acc[2][2][4][2];
; #pragma unroll
;     for (int a = 0; a < 2; ++a)
; #pragma unroll
;         for (int b = 0; b < 2; ++b)
; #pragma unroll
;             for (int m = 0; m < 4; ++m)
; #pragma unroll
;                 for (int n = 0; n < 2; ++n) acc[a][b][m][n] = (f32x4){0.f, 0.f, 0.f, 0.f};
;     bf16x8 At[4][2], B0[2][2], B1[2][2];
;     const char* cA = (const char*)g.A + (size_t)cur.pm * tstepA; const char* cB = (const char*)g.Bt + (size_t)cur.pn * tstepB;
;     S.a_ready(cur);
;     PG8_STAGE(PG8_SB(0, 0), cB, voffB); PG8_STAGE(PG8_SA(0, 0), cA, voffA); PG8_STAGE(PG8_SB(0, 1), cB + hstepB, voffB); PG8_STAGE(PG8_SA(0, 1), cA + hstepA, voffA);
;     if (wr == 1) PG8_BAR;
;     PG8_WAIT_V(4); PG8_BAR;
;     PG8_STAGE(PG8_SB(1, 0), cB + kstep, voffB); PG8_STAGE(PG8_SA(1, 0), cA + kstep, voffA); PG8_STAGE(PG8_SB(1, 1), cB + hstepB + kstep, voffB);
;     PG8_WAIT_V(6); PG8_BAR;
.LBB0_1105:
	s_add_u32 s16, s8, s2
	s_addc_u32 s17, s9, s3
	s_lshl_b32 s2, s28, 5
	s_and_b32 s19, s2, 0x60
	s_lshl_b32 s18, s11, 13
	s_lshl_b32 s22, s19, 7
	s_add_u32 s8, s8, 0x24e9c100
	s_addc_u32 s9, s9, 0
	s_add_i32 m0, s21, 0x18000
	v_lshl_add_u64 v[6:7], v[6:7], 0, s[76:77]
	s_waitcnt vmcnt(4)
	s_barrier
	global_load_lds_dwordx4 v[6:7], off
	v_lshl_add_u64 v[4:5], v[4:5], 0, s[76:77]
	s_add_i32 m0, s21, 0x1a000
	s_add_i32 s50, s21, 0x8000
	s_add_i32 s51, s21, 0xa000
	global_load_lds_dwordx4 v[4:5], off
	v_lshl_add_u64 v[2:3], v[2:3], 0, s[76:77]
	s_mov_b32 m0, s50
	s_add_u32 s2, s14, 0x80080
	global_load_lds_dwordx4 v[2:3], off
	v_lshl_add_u64 v[0:1], v[0:1], 0, s[76:77]
	s_mov_b32 m0, s51
	s_addc_u32 s3, s15, 0
	global_load_lds_dwordx4 v[0:1], off
	s_add_i32 m0, s21, 0x1c000
	global_load_lds_dwordx4 v32, s[2:3]
	v_lshl_add_u64 v[0:1], s[2:3], 0, v[134:135]
	s_add_i32 m0, s21, 0x1e000
	s_ashr_i32 s52, s30, 31
	global_load_lds_dwordx4 v134, s[2:3]
	v_lshrrev_b32_e32 v1, 1, v8
	v_and_b32_e32 v1, 24, v1
	v_and_b32_e32 v0, 15, v8
	v_lshlrev_b32_e32 v2, 1, v1
	v_lshl_or_b32 v142, s11, 6, v0
	v_lshl_or_b32 v0, v0, 6, v2
	v_lshlrev_b32_e32 v2, 2, v8
	v_and_b32_e32 v2, 32, v2
	v_bitop3_b32 v3, v0, s18, v2 bitop3:0xde
	v_bitop3_b32 v143, v0, s22, v2 bitop3:0xde
	v_lshlrev_b32_e32 v0, 15, v9
	v_and_b32_e32 v0, 0xffff0000, v0
	v_or_b32_e32 v144, s19, v1
	v_lshl_add_u32 v0, v10, 12, v0
	v_and_b32_e32 v1, 1, v9
	v_lshl_or_b32 v0, v1, 6, v0
	s_lshl_b32 s2, s33, 9
	v_lshl_add_u32 v136, v11, 1, v0
	v_lshlrev_b32_e32 v0, 15, v12
	s_sub_u32 s2, 0, s2
	v_and_b32_e32 v0, 0xffff0000, v0
	s_waitcnt vmcnt(6)
	s_subb_u32 s3, 0, 0
	v_lshl_add_u32 v0, v13, 12, v0
	v_and_b32_e32 v1, 1, v12
	s_add_u32 s53, s16, s2
	v_lshl_or_b32 v0, v1, 6, v0
	s_sext_i32_i16 s56, s10
	s_addc_u32 s54, s17, s3
	v_mov_b32_e32 v137, v33
	v_lshl_add_u32 v138, v14, 1, v0
	v_mov_b32_e32 v139, v33
	s_mov_b32 s55, 0
	v_add_u32_e32 v145, 0, v3
	s_barrier
	s_waitcnt vmcnt(0)
	s_branch .LBB0_1107

; #define PG8_STAGE(bufoff, gbase, voff) do { _Pragma("unroll") for (int _i = 0; _i < 2; ++_i) \
;         __builtin_amdgcn_global_load_lds((const unsigned*)((const char*)(gbase) + (voff)[_i]), (LAS unsigned*)(lds + (bufoff) + ldsw + _i * 8192), 16, 0, 0); } while (0)
; #define PG8_LDA(dst, b, h) do { _Pragma("unroll") for (int m = 0; m < 4; ++m) _Pragma("unroll") for (int k = 0; k < 2; ++k) dst[m][k] = *(const LAS bf16x8*)(lds + PG8_SA(b, h) + aoff + m * 2048 + k * 1024); } while (0)
; #define PG8_LDB(dst, b, h) do { _Pragma("unroll") for (int n = 0; n < 2; ++n) _Pragma("unroll") for (int k = 0; k < 2; ++k) dst[n][k] = *(const LAS bf16x8*)(lds + PG8_SB(b, h) + boff + n * 2048 + k * 1024); } while (0)
; #define PG8_MMA(ai, bj, At, Bt) do { __builtin_amdgcn_s_setprio(1); _Pragma("unroll") for (int m = 0; m < 4; ++m) _Pragma("unroll") for (int n = 0; n < 2; ++n) _Pragma("unroll") for (int k = 0; k < 2; ++k) \
;         acc[ai][bj][m][n] = __builtin_amdgcn_mfma_f32_16x16x32_bf16(Bt[n][k], At[m][k], acc[ai][bj][m][n], 0, 0, 0); __builtin_amdgcn_s_setprio(0); } while (0)
; #define PG8_WAIT_L(n) asm volatile("s_waitcnt lgkmcnt(" #n ")" ::: "memory")
; #define PG8_BAR __builtin_amdgcn_s_barrier()
; #define PG8_SCHED __builtin_amdgcn_sched_barrier(0)
; template <class Epi, class Sched>
; __device__ __forceinline__ void gemm_phase(LAS unsigned char* lds, const Gemm g, const Sched& S, const Epi& E, int tid_in) {
;     ...
;         for (int t = 0; t < nt; t += 2) {
;             const bool last = (t == nt - 2);
;             const char* a1 = cA + (size_t)(t + 1) * kstep;
;             const char* a2 = last ? nA : cA + (size_t)(t + 2) * kstep; const char* b2 = last ? nB : cB + (size_t)(t + 2) * kstep;
;             const char* a3 = a2 + kstep; const char* b3 = b2 + kstep;
;             if (last && has_next) S.a_ready(nxt);
;             PG8_LDB(B0, 0, 0); PG8_SCHED; PG8_LDA(At, 0, 0); PG8_STAGE(PG8_SA(1, 1), a1 + hstepA, voffA);
;             PG8_WAIT_L(8); PG8_BAR; PG8_WAIT_L(0); PG8_MMA(0, 0, At, B0); PG8_BAR; PG8_SCHED;
;             PG8_LDB(B1, 0, 1); PG8_STAGE(PG8_SB(0, 0), b2, voffB);
;             PG8_BAR; PG8_WAIT_L(0); PG8_MMA(0, 1, At, B1); PG8_BAR;
;             PG8_LDA(At, 0, 1); PG8_STAGE(PG8_SA(0, 0), a2, voffA);
;             PG8_BAR; PG8_WAIT_L(0); PG8_MMA(1, 0, At, B0); PG8_BAR; PG8_SCHED;
.LBB0_1114:
	s_add_u32 s14, s24, 0xfff80080
	s_addc_u32 s15, s25, -1
	s_add_i32 s70, 0, 0x10000
	v_add_u32_e32 v140, s70, v143
	ds_read_b128 v[146:149], v140
	ds_read_b128 v[150:153], v140 offset:1024
	ds_read_b128 v[154:157], v140 offset:2048
	ds_read_b128 v[158:161], v140 offset:3072
	s_cmp_eq_u32 s69, 28
	s_cselect_b32 s27, s17, s15
	s_cselect_b32 s26, s63, s14
	s_cselect_b32 s15, s11, s68
	s_cselect_b32 s14, s64, s65
	s_add_i32 m0, s21, 0xc000
	ds_read_b128 v[162:165], v145
	ds_read_b128 v[166:169], v145 offset:1024
	ds_read_b128 v[170:173], v145 offset:2048
	ds_read_b128 v[174:177], v145 offset:3072
	ds_read_b128 v[178:181], v145 offset:4096
	ds_read_b128 v[182:185], v145 offset:5120
	ds_read_b128 v[186:189], v145 offset:6144
	ds_read_b128 v[190:193], v145 offset:7168
	global_load_lds_dwordx4 v136, s[24:25]
	v_lshl_add_u64 v[140:141], s[24:25], 0, v[138:139]
	s_add_i32 m0, s21, 0xe000
	s_nop 0
	global_load_lds_dwordx4 v138, s[24:25]
	s_waitcnt lgkmcnt(8)
	s_barrier
	s_waitcnt lgkmcnt(0)
	s_setprio 1
	s_waitcnt lgkmcnt(0)
	v_mfma_f32_16x16x32_bf16 v[126:129], v[146:149], v[162:165], v[126:129]
	v_mfma_f32_16x16x32_bf16 v[122:125], v[154:157], v[162:165], v[122:125]
	v_mfma_f32_16x16x32_bf16 v[118:121], v[146:149], v[170:173], v[118:121]
	v_mfma_f32_16x16x32_bf16 v[110:113], v[154:157], v[170:173], v[110:113]
	v_mfma_f32_16x16x32_bf16 v[102:105], v[146:149], v[178:181], v[102:105]
	v_mfma_f32_16x16x32_bf16 v[94:97], v[154:157], v[178:181], v[94:97]
	v_mfma_f32_16x16x32_bf16 v[86:89], v[146:149], v[186:189], v[86:89]
	v_mfma_f32_16x16x32_bf16 v[78:81], v[154:157], v[186:189], v[78:81]
	v_mfma_f32_16x16x32_bf16 v[126:129], v[150:153], v[166:169], v[126:129]
	v_mfma_f32_16x16x32_bf16 v[122:125], v[158:161], v[166:169], v[122:125]
	v_mfma_f32_16x16x32_bf16 v[118:121], v[150:153], v[174:177], v[118:121]
	v_mfma_f32_16x16x32_bf16 v[110:113], v[158:161], v[174:177], v[110:113]
	v_mfma_f32_16x16x32_bf16 v[102:105], v[150:153], v[182:185], v[102:105]
	v_mfma_f32_16x16x32_bf16 v[94:97], v[158:161], v[182:185], v[94:97]
	v_mfma_f32_16x16x32_bf16 v[86:89], v[150:153], v[190:193], v[86:89]
	v_mfma_f32_16x16x32_bf16 v[78:81], v[158:161], v[190:193], v[78:81]
	s_setprio 0
	s_barrier
	s_add_i32 s72, 0, 0x14000
	v_add_u32_e32 v140, s72, v143
	s_add_i32 s70, s70, s40
	ds_read_b128 v[194:197], v140
	ds_read_b128 v[198:201], v140 offset:1024
	ds_read_b128 v[202:205], v140 offset:2048
	ds_read_b128 v[206:209], v140 offset:3072
	v_lshl_add_u64 v[140:141], s[14:15], 0, v[32:33]
	s_mov_b32 m0, s70
	v_lshl_add_u64 v[216:217], s[14:15], 0, v[134:135]
	global_load_lds_dwordx4 v32, s[14:15]
	s_add_i32 m0, s70, 0x2000
	s_nop 0
	global_load_lds_dwordx4 v134, s[14:15]
	s_barrier
	s_waitcnt lgkmcnt(0)
	s_setprio 1
	s_waitcnt lgkmcnt(0)
	v_mfma_f32_16x16x32_bf16 v[114:117], v[194:197], v[162:165], v[114:117]
	v_mfma_f32_16x16x32_bf16 v[106:109], v[202:205], v[162:165], v[106:109]
	v_mfma_f32_16x16x32_bf16 v[98:101], v[194:197], v[170:173], v[98:101]
	v_mfma_f32_16x16x32_bf16 v[90:93], v[202:205], v[170:173], v[90:93]
	v_mfma_f32_16x16x32_bf16 v[82:85], v[194:197], v[178:181], v[82:85]
	v_mfma_f32_16x16x32_bf16 v[74:77], v[202:205], v[178:181], v[74:77]
	v_mfma_f32_16x16x32_bf16 v[70:73], v[194:197], v[186:189], v[70:73]
	v_mfma_f32_16x16x32_bf16 v[66:69], v[202:205], v[186:189], v[66:69]
	v_mfma_f32_16x16x32_bf16 v[114:117], v[198:201], v[166:169], v[114:117]
	v_mfma_f32_16x16x32_bf16 v[106:109], v[206:209], v[166:169], v[106:109]
	v_mfma_f32_16x16x32_bf16 v[98:101], v[198:201], v[174:177], v[98:101]
	v_mfma_f32_16x16x32_bf16 v[90:93], v[206:209], v[174:177], v[90:93]
	v_mfma_f32_16x16x32_bf16 v[82:85], v[198:201], v[182:185], v[82:85]
	v_mfma_f32_16x16x32_bf16 v[74:77], v[206:209], v[182:185], v[74:77]
	v_mfma_f32_16x16x32_bf16 v[70:73], v[198:201], v[190:193], v[70:73]
	v_mfma_f32_16x16x32_bf16 v[66:69], v[206:209], v[190:193], v[66:69]
	s_setprio 0
	s_mov_b32 m0, s21
	v_lshl_add_u64 v[218:219], s[26:27], 0, v[130:131]
	s_barrier
	ds_read_b128 v[162:165], v145 offset:16384
	ds_read_b128 v[166:169], v145 offset:17408
	ds_read_b128 v[170:173], v145 offset:18432
	ds_read_b128 v[174:177], v145 offset:19456
	ds_read_b128 v[178:181], v145 offset:20480
	ds_read_b128 v[182:185], v145 offset:21504
	ds_read_b128 v[186:189], v145 offset:22528
	ds_read_b128 v[190:193], v145 offset:23552
	global_load_lds_dwordx4 v130, s[26:27]
	v_lshl_add_u64 v[220:221], s[26:27], 0, v[132:133]
	s_mov_b32 m0, s47
	s_nop 0
	global_load_lds_dwordx4 v132, s[26:27]
	s_barrier
	s_waitcnt lgkmcnt(0)
	s_setprio 1
	s_waitcnt lgkmcnt(0)
	v_mfma_f32_16x16x32_bf16 v[62:65], v[146:149], v[162:165], v[62:65]
	v_mfma_f32_16x16x32_bf16 v[58:61], v[154:157], v[162:165], v[58:61]
	v_mfma_f32_16x16x32_bf16 v[54:57], v[146:149], v[170:173], v[54:57]
	v_mfma_f32_16x16x32_bf16 v[46:49], v[154:157], v[170:173], v[46:49]
	v_mfma_f32_16x16x32_bf16 v[38:41], v[146:149], v[178:181], v[38:41]
	v_mfma_f32_16x16x32_bf16 v[28:31], v[154:157], v[178:181], v[28:31]
	v_mfma_f32_16x16x32_bf16 v[20:23], v[146:149], v[186:189], v[20:23]
	v_mfma_f32_16x16x32_bf16 v[12:15], v[154:157], v[186:189], v[12:15]
	v_mfma_f32_16x16x32_bf16 v[62:65], v[150:153], v[166:169], v[62:65]
	v_mfma_f32_16x16x32_bf16 v[58:61], v[158:161], v[166:169], v[58:61]
	v_mfma_f32_16x16x32_bf16 v[54:57], v[150:153], v[174:177], v[54:57]
	v_mfma_f32_16x16x32_bf16 v[46:49], v[158:161], v[174:177], v[46:49]
	v_mfma_f32_16x16x32_bf16 v[38:41], v[150:153], v[182:185], v[38:41]
	v_mfma_f32_16x16x32_bf16 v[28:31], v[158:161], v[182:185], v[28:31]
	v_mfma_f32_16x16x32_bf16 v[20:23], v[150:153], v[190:193], v[20:23]
	v_mfma_f32_16x16x32_bf16 v[12:15], v[158:161], v[190:193], v[12:15]
	s_setprio 0
	s_barrier
; #define PG8_STAGE(bufoff, gbase, voff) do { _Pragma("unroll") for (int _i = 0; _i < 2; ++_i) \
;         __builtin_amdgcn_global_load_lds((const unsigned*)((const char*)(gbase) + (voff)[_i]), (LAS unsigned*)(lds + (bufoff) + ldsw + _i * 8192), 16, 0, 0); } while (0)
; #define PG8_LDA(dst, b, h) do { _Pragma("unroll") for (int m = 0; m < 4; ++m) _Pragma("unroll") for (int k = 0; k < 2; ++k) dst[m][k] = *(const LAS bf16x8*)(lds + PG8_SA(b, h) + aoff + m * 2048 + k * 1024); } while (0)
; #define PG8_LDB(dst, b, h) do { _Pragma("unroll") for (int n = 0; n < 2; ++n) _Pragma("unroll") for (int k = 0; k < 2; ++k) dst[n][k] = *(const LAS bf16x8*)(lds + PG8_SB(b, h) + boff + n * 2048 + k * 1024); } while (0)
; #define PG8_MMA(ai, bj, At, Bt) do { __builtin_amdgcn_s_setprio(1); _Pragma("unroll") for (int m = 0; m < 4; ++m) _Pragma("unroll") for (int n = 0; n < 2; ++n) _Pragma("unroll") for (int k = 0; k < 2; ++k) \
;         acc[ai][bj][m][n] = __builtin_amdgcn_mfma_f32_16x16x32_bf16(Bt[n][k], At[m][k], acc[ai][bj][m][n], 0, 0, 0); __builtin_amdgcn_s_setprio(0); } while (0)
; #define PG8_WAIT_V(n) asm volatile("s_waitcnt vmcnt(" #n ")" ::: "memory")
; #define PG8_WAIT_L(n) asm volatile("s_waitcnt lgkmcnt(" #n ")" ::: "memory")
; #define PG8_BAR __builtin_amdgcn_s_barrier()
; #define PG8_SCHED __builtin_amdgcn_sched_barrier(0)
; template <class Epi, class Sched>
; __device__ __forceinline__ void gemm_phase(LAS unsigned char* lds, const Gemm g, const Sched& S, const Epi& E, int tid_in) {
;     ...
;             PG8_STAGE(PG8_SB(0, 1), b2 + hstepB, voffB);
;             PG8_WAIT_V(6); PG8_BAR; PG8_MMA(1, 1, At, B1); PG8_BAR;
;             PG8_LDB(B0, 1, 0); PG8_SCHED; PG8_LDA(At, 1, 0); PG8_STAGE(PG8_SA(0, 1), a2 + hstepA, voffA);
;             PG8_WAIT_L(8); PG8_BAR; PG8_WAIT_L(0); PG8_MMA(0, 0, At, B0); PG8_BAR; PG8_SCHED;
;             PG8_LDB(B1, 1, 1); PG8_STAGE(PG8_SB(1, 0), b3, voffB);
	s_add_u32 s70, s14, 0x80000
	s_addc_u32 s71, s15, 0
	s_add_i32 s72, s72, s40
	s_mov_b32 m0, s72
	s_nop 0
	global_load_lds_dwordx4 v32, s[70:71]
	s_add_i32 m0, s72, 0x2000
	s_nop 0
	global_load_lds_dwordx4 v134, s[70:71]
	s_waitcnt vmcnt(6)
	s_barrier
	s_setprio 1
	v_mfma_f32_16x16x32_bf16 v[50:53], v[194:197], v[162:165], v[50:53]
	v_mfma_f32_16x16x32_bf16 v[42:45], v[202:205], v[162:165], v[42:45]
	v_mfma_f32_16x16x32_bf16 v[34:37], v[194:197], v[170:173], v[34:37]
	v_mfma_f32_16x16x32_bf16 v[24:27], v[202:205], v[170:173], v[24:27]
	v_mfma_f32_16x16x32_bf16 v[16:19], v[194:197], v[178:181], v[16:19]
	v_mfma_f32_16x16x32_bf16 v[8:11], v[202:205], v[178:181], v[8:11]
	v_mfma_f32_16x16x32_bf16 v[4:7], v[194:197], v[186:189], v[4:7]
	v_mfma_f32_16x16x32_bf16 v[0:3], v[202:205], v[186:189], v[0:3]
	v_mfma_f32_16x16x32_bf16 v[50:53], v[198:201], v[166:169], v[50:53]
	v_mfma_f32_16x16x32_bf16 v[42:45], v[206:209], v[166:169], v[42:45]
	v_mfma_f32_16x16x32_bf16 v[34:37], v[198:201], v[174:177], v[34:37]
	v_mfma_f32_16x16x32_bf16 v[24:27], v[206:209], v[174:177], v[24:27]
	v_mfma_f32_16x16x32_bf16 v[16:19], v[198:201], v[182:185], v[16:19]
	v_mfma_f32_16x16x32_bf16 v[8:11], v[206:209], v[182:185], v[8:11]
	v_mfma_f32_16x16x32_bf16 v[4:7], v[198:201], v[190:193], v[4:7]
	v_mfma_f32_16x16x32_bf16 v[0:3], v[206:209], v[190:193], v[0:3]
	s_setprio 0
	s_add_i32 s70, 0, 0x18000
	v_add_u32_e32 v158, s70, v143
	s_barrier
	ds_read_b128 v[146:149], v158
	ds_read_b128 v[150:153], v158 offset:1024
	ds_read_b128 v[154:157], v158 offset:2048
	ds_read_b128 v[158:161], v158 offset:3072
	s_add_u32 s26, s26, 0x80000
	s_addc_u32 s27, s27, 0
	s_mov_b32 m0, s48
	ds_read_b128 v[162:165], v145 offset:32768
	ds_read_b128 v[166:169], v145 offset:33792
	ds_read_b128 v[170:173], v145 offset:34816
	ds_read_b128 v[174:177], v145 offset:35840
	ds_read_b128 v[178:181], v145 offset:36864
	ds_read_b128 v[182:185], v145 offset:37888
	ds_read_b128 v[186:189], v145 offset:38912
	ds_read_b128 v[190:193], v145 offset:39936
	global_load_lds_dwordx4 v130, s[26:27]
	s_mov_b32 m0, s49
	s_nop 0
	global_load_lds_dwordx4 v132, s[26:27]
	s_waitcnt lgkmcnt(8)
	s_barrier
	s_waitcnt lgkmcnt(0)
	s_setprio 1
	s_waitcnt lgkmcnt(0)
	v_mfma_f32_16x16x32_bf16 v[126:129], v[146:149], v[162:165], v[126:129]
	v_mfma_f32_16x16x32_bf16 v[122:125], v[154:157], v[162:165], v[122:125]
	v_mfma_f32_16x16x32_bf16 v[118:121], v[146:149], v[170:173], v[118:121]
	v_mfma_f32_16x16x32_bf16 v[110:113], v[154:157], v[170:173], v[110:113]
	v_mfma_f32_16x16x32_bf16 v[102:105], v[146:149], v[178:181], v[102:105]
	v_mfma_f32_16x16x32_bf16 v[94:97], v[154:157], v[178:181], v[94:97]
	v_mfma_f32_16x16x32_bf16 v[86:89], v[146:149], v[186:189], v[86:89]
	v_mfma_f32_16x16x32_bf16 v[78:81], v[154:157], v[186:189], v[78:81]
	v_mfma_f32_16x16x32_bf16 v[126:129], v[150:153], v[166:169], v[126:129]
	v_mfma_f32_16x16x32_bf16 v[122:125], v[158:161], v[166:169], v[122:125]
	v_mfma_f32_16x16x32_bf16 v[118:121], v[150:153], v[174:177], v[118:121]
	v_mfma_f32_16x16x32_bf16 v[110:113], v[158:161], v[174:177], v[110:113]
	v_mfma_f32_16x16x32_bf16 v[102:105], v[150:153], v[182:185], v[102:105]
	v_mfma_f32_16x16x32_bf16 v[94:97], v[158:161], v[182:185], v[94:97]
	v_mfma_f32_16x16x32_bf16 v[86:89], v[150:153], v[190:193], v[86:89]
	v_mfma_f32_16x16x32_bf16 v[78:81], v[158:161], v[190:193], v[78:81]
	s_setprio 0
	s_barrier
	s_add_i32 s26, 0, 0x1c000
	s_add_i32 s27, s70, s40
	v_add_u32_e32 v206, s26, v143
	v_lshl_add_u64 v[140:141], v[140:141], 0, s[76:77]
	s_mov_b32 m0, s27
	ds_read_b128 v[194:197], v206
	ds_read_b128 v[198:201], v206 offset:1024
	ds_read_b128 v[202:205], v206 offset:2048
	ds_read_b128 v[206:209], v206 offset:3072
	global_load_lds_dwordx4 v[140:141], off
	v_lshl_add_u64 v[140:141], v[216:217], 0, s[76:77]
	s_add_i32 m0, s27, 0x2000
	s_nop 0
	global_load_lds_dwordx4 v[140:141], off
	s_barrier
; #define PG8_STAGE(bufoff, gbase, voff) do { _Pragma("unroll") for (int _i = 0; _i < 2; ++_i) \
;         __builtin_amdgcn_global_load_lds((const unsigned*)((const char*)(gbase) + (voff)[_i]), (LAS unsigned*)(lds + (bufoff) + ldsw + _i * 8192), 16, 0, 0); } while (0)
; #define PG8_LDA(dst, b, h) do { _Pragma("unroll") for (int m = 0; m < 4; ++m) _Pragma("unroll") for (int k = 0; k < 2; ++k) dst[m][k] = *(const LAS bf16x8*)(lds + PG8_SA(b, h) + aoff + m * 2048 + k * 1024); } while (0)
; #define PG8_MMA(ai, bj, At, Bt) do { __builtin_amdgcn_s_setprio(1); _Pragma("unroll") for (int m = 0; m < 4; ++m) _Pragma("unroll") for (int n = 0; n < 2; ++n) _Pragma("unroll") for (int k = 0; k < 2; ++k) \
;         acc[ai][bj][m][n] = __builtin_amdgcn_mfma_f32_16x16x32_bf16(Bt[n][k], At[m][k], acc[ai][bj][m][n], 0, 0, 0); __builtin_amdgcn_s_setprio(0); } while (0)
; #define PG8_WAIT_V(n) asm volatile("s_waitcnt vmcnt(" #n ")" ::: "memory")
; #define PG8_WAIT_L(n) asm volatile("s_waitcnt lgkmcnt(" #n ")" ::: "memory")
; #define PG8_BAR __builtin_amdgcn_s_barrier()
; #define PG8_SCHED __builtin_amdgcn_sched_barrier(0)
; template <class Epi, class Sched>
; __device__ __forceinline__ void gemm_phase(LAS unsigned char* lds, const Gemm g, const Sched& S, const Epi& E, int tid_in) {
;     ...
;             PG8_BAR; PG8_WAIT_L(0); PG8_MMA(0, 1, At, B1); PG8_BAR;
;             PG8_LDA(At, 1, 1); PG8_STAGE(PG8_SA(1, 0), a3, voffA);
;             PG8_BAR; PG8_WAIT_L(0); PG8_MMA(1, 0, At, B0); PG8_BAR; PG8_SCHED;
;             PG8_STAGE(PG8_SB(1, 1), b3 + hstepB, voffB);
;             PG8_WAIT_V(6); PG8_BAR; PG8_MMA(1, 1, At, B1); PG8_BAR;
;         }
;         E(acc, cur, wr, wc, fr, fq); S.done(cur);
;         if (!has_next) break;
; #pragma unroll
;         for (int a = 0; a < 2; ++a)
; #pragma unroll
;             for (int b = 0; b < 2; ++b)
; #pragma unroll
;                 for (int m = 0; m < 4; ++m)
; #pragma unroll
;                     for (int n = 0; n < 2; ++n) acc[a][b][m][n] = (f32x4){0.f, 0.f, 0.f, 0.f};
;         cur = nxt; cA = nA; cB = nB; ++ui;
	s_waitcnt lgkmcnt(0)
	s_setprio 1
	s_waitcnt lgkmcnt(0)
	v_mfma_f32_16x16x32_bf16 v[114:117], v[194:197], v[162:165], v[114:117]
	v_mfma_f32_16x16x32_bf16 v[106:109], v[202:205], v[162:165], v[106:109]
	v_mfma_f32_16x16x32_bf16 v[98:101], v[194:197], v[170:173], v[98:101]
	v_mfma_f32_16x16x32_bf16 v[90:93], v[202:205], v[170:173], v[90:93]
	v_mfma_f32_16x16x32_bf16 v[82:85], v[194:197], v[178:181], v[82:85]
	v_mfma_f32_16x16x32_bf16 v[74:77], v[202:205], v[178:181], v[74:77]
	v_mfma_f32_16x16x32_bf16 v[70:73], v[194:197], v[186:189], v[70:73]
	v_mfma_f32_16x16x32_bf16 v[66:69], v[202:205], v[186:189], v[66:69]
	v_mfma_f32_16x16x32_bf16 v[114:117], v[198:201], v[166:169], v[114:117]
	v_mfma_f32_16x16x32_bf16 v[106:109], v[206:209], v[166:169], v[106:109]
	v_mfma_f32_16x16x32_bf16 v[98:101], v[198:201], v[174:177], v[98:101]
	v_mfma_f32_16x16x32_bf16 v[90:93], v[206:209], v[174:177], v[90:93]
	v_mfma_f32_16x16x32_bf16 v[82:85], v[198:201], v[182:185], v[82:85]
	v_mfma_f32_16x16x32_bf16 v[74:77], v[206:209], v[182:185], v[74:77]
	v_mfma_f32_16x16x32_bf16 v[70:73], v[198:201], v[190:193], v[70:73]
	v_mfma_f32_16x16x32_bf16 v[66:69], v[206:209], v[190:193], v[66:69]
	s_setprio 0
	s_mov_b32 m0, s50
	v_lshl_add_u64 v[140:141], v[218:219], 0, s[76:77]
	s_barrier
	ds_read_b128 v[162:165], v145 offset:49152
	ds_read_b128 v[166:169], v145 offset:50176
	ds_read_b128 v[170:173], v145 offset:51200
	ds_read_b128 v[174:177], v145 offset:52224
	ds_read_b128 v[178:181], v145 offset:53248
	ds_read_b128 v[182:185], v145 offset:54272
	ds_read_b128 v[186:189], v145 offset:55296
	ds_read_b128 v[190:193], v145 offset:56320
	global_load_lds_dwordx4 v[140:141], off
	v_lshl_add_u64 v[140:141], v[220:221], 0, s[76:77]
	s_mov_b32 m0, s51
	s_nop 0
	global_load_lds_dwordx4 v[140:141], off
	s_barrier
	s_waitcnt lgkmcnt(0)
	s_setprio 1
	s_waitcnt lgkmcnt(0)
	v_mfma_f32_16x16x32_bf16 v[62:65], v[146:149], v[162:165], v[62:65]
	v_mfma_f32_16x16x32_bf16 v[58:61], v[154:157], v[162:165], v[58:61]
	v_mfma_f32_16x16x32_bf16 v[54:57], v[146:149], v[170:173], v[54:57]
	v_mfma_f32_16x16x32_bf16 v[46:49], v[154:157], v[170:173], v[46:49]
	v_mfma_f32_16x16x32_bf16 v[38:41], v[146:149], v[178:181], v[38:41]
	v_mfma_f32_16x16x32_bf16 v[28:31], v[154:157], v[178:181], v[28:31]
	v_mfma_f32_16x16x32_bf16 v[20:23], v[146:149], v[186:189], v[20:23]
	v_mfma_f32_16x16x32_bf16 v[12:15], v[154:157], v[186:189], v[12:15]
	v_mfma_f32_16x16x32_bf16 v[62:65], v[150:153], v[166:169], v[62:65]
	v_mfma_f32_16x16x32_bf16 v[58:61], v[158:161], v[166:169], v[58:61]
	v_mfma_f32_16x16x32_bf16 v[54:57], v[150:153], v[174:177], v[54:57]
	v_mfma_f32_16x16x32_bf16 v[46:49], v[158:161], v[174:177], v[46:49]
	v_mfma_f32_16x16x32_bf16 v[38:41], v[150:153], v[182:185], v[38:41]
	v_mfma_f32_16x16x32_bf16 v[28:31], v[158:161], v[182:185], v[28:31]
	v_mfma_f32_16x16x32_bf16 v[20:23], v[150:153], v[190:193], v[20:23]
	v_mfma_f32_16x16x32_bf16 v[12:15], v[158:161], v[190:193], v[12:15]
	s_setprio 0
	s_barrier
	s_add_u32 s14, s14, 0x80080
	s_addc_u32 s15, s15, 0
	s_add_i32 s26, s26, s40
	s_mov_b32 m0, s26
	s_nop 0
	global_load_lds_dwordx4 v32, s[14:15]
	v_lshl_add_u64 v[140:141], s[14:15], 0, v[134:135]
	s_add_i32 m0, s26, 0x2000
	s_nop 0
	global_load_lds_dwordx4 v134, s[14:15]
	s_waitcnt vmcnt(6)
	s_barrier
	s_setprio 1
	v_mfma_f32_16x16x32_bf16 v[50:53], v[194:197], v[162:165], v[50:53]
	v_mfma_f32_16x16x32_bf16 v[42:45], v[202:205], v[162:165], v[42:45]
	v_mfma_f32_16x16x32_bf16 v[34:37], v[194:197], v[170:173], v[34:37]
	v_mfma_f32_16x16x32_bf16 v[24:27], v[202:205], v[170:173], v[24:27]
	v_mfma_f32_16x16x32_bf16 v[16:19], v[194:197], v[178:181], v[16:19]
	v_mfma_f32_16x16x32_bf16 v[8:11], v[202:205], v[178:181], v[8:11]
	v_mfma_f32_16x16x32_bf16 v[4:7], v[194:197], v[186:189], v[4:7]
	v_mfma_f32_16x16x32_bf16 v[0:3], v[202:205], v[186:189], v[0:3]
	v_mfma_f32_16x16x32_bf16 v[50:53], v[198:201], v[166:169], v[50:53]
	v_mfma_f32_16x16x32_bf16 v[42:45], v[206:209], v[166:169], v[42:45]
	v_mfma_f32_16x16x32_bf16 v[34:37], v[198:201], v[174:177], v[34:37]
	v_mfma_f32_16x16x32_bf16 v[24:27], v[206:209], v[174:177], v[24:27]
	v_mfma_f32_16x16x32_bf16 v[16:19], v[198:201], v[182:185], v[16:19]
	v_mfma_f32_16x16x32_bf16 v[8:11], v[206:209], v[182:185], v[8:11]
	v_mfma_f32_16x16x32_bf16 v[4:7], v[198:201], v[190:193], v[4:7]
	v_mfma_f32_16x16x32_bf16 v[0:3], v[206:209], v[190:193], v[0:3]
	s_setprio 0
	s_add_i32 s69, s69, 2
	s_add_u32 s24, s24, 0x100
	s_addc_u32 s25, s25, 0
	s_add_u32 s65, s65, 0x100
	s_addc_u32 s68, s68, 0
	s_cmp_gt_u32 s69, 29
	s_barrier
	s_cbranch_scc0 .LBB0_1114
	s_cmp_lt_i32 s56, s33
	s_mov_b64 s[14:15], s[6:7]
	s_mov_b64 s[24:25], s[8:9]
	s_cbranch_scc1 .LBB0_1106
	s_cmp_eq_u32 s20, 64
	s_cselect_b32 s11, 0xffffe000, 0
	s_cmp_gt_u32 s20, 63
	s_cselect_b32 s11, s11, 0x100
	s_cmp_gt_i32 s20, 31
	s_cselect_b32 s11, s11, 0
	s_mul_hi_i32 s15, s11, s4
	s_mul_i32 s14, s11, s4
	s_lshl_b64 s[14:15], s[14:15], 1
	s_add_u32 s24, s53, s14
	s_addc_u32 s25, s54, s15
	s_mov_b64 s[14:15], s[4:5]
	s_branch .LBB0_1106

; __device__ __forceinline__ int v_st(int k, int c) { const int kk = (k & ~0xC) | ((k & 4) << 1) | ((k & 8) >> 1); return ((kk >> 3) * 4 + (c >> 5)) * 512 + ((kk & 7) * 32 + (c & 31)) * 2; }
; __device__ __forceinline__ int v_rd_base(int lane) { return ((lane & 3) << 3) | (((lane >> 2) & 3) << 6) | (((lane >> 4) & 1) << 5) | (((lane >> 5) & 1) << 8); }
; #define SLOAD(i, k0) do { sv0[i] = *reinterpret_cast<const bf16x8*>(&Vh[(size_t)((k0) + sr) * ldv + sc]); sv1[i] = *reinterpret_cast<const bf16x8*>(&Vh[(size_t)((k0) + 32 + sr) * ldv + sc]); \
;     _Pragma("unroll") for (int _q = 0; _q < NKP; ++_q) sk[i][_q] = *reinterpret_cast<const bf16x8*>(&Kh[(size_t)(k0) * ldk + koff[_q]]); } while (0)
; #define SWRITE(b, i) do { *(bf16x8*)(V_lds + (b) * SHM_V + vst0) = sv0[i]; *(bf16x8*)(V_lds + (b) * SHM_V + vst1) = sv1[i]; \
;     _Pragma("unroll") for (int _q = 0; _q < NKP; ++_q) *(bf16x8*)(K_lds + (b) * SHM_K + klds[_q]) = sk[i][_q]; } while (0)
; #define SLOAD(k0) do { sv0 = *reinterpret_cast<const bf16x8*>(&Vh[(size_t)((k0) + sr) * ldv + sc]); sv1 = *reinterpret_cast<const bf16x8*>(&Vh[(size_t)((k0) + 32 + sr) * ldv + sc]); \
;     _Pragma("unroll") for (int _q = 0; _q < NKP; ++_q) sk[_q] = *reinterpret_cast<const bf16x8*>(&Kh[(size_t)(k0) * ldk + koff[_q]]); } while (0)
; template <int DQK, int SDEPTH, int QL, bool NOMAX, int ldq, int ldk, int ldv, int ldo> ...
;     ...
;     const int sr = tid >> 4, sc = (tid & 15) * 8, vst0 = v_st(sr, sc), vst1 = v_st(32 + sr, sc);
;     int koff[NKP], klds[NKP];
; #pragma unroll
;     for (int i = 0; i < NKP; ++i) { const int row = tid >> 3, c8 = (tid & 7) + 8 * i; koff[i] = row * ldk + c8 * 8; klds[i] = row * RS + c8 * 16; }
;     const int vb0 = (int)(uintptr_t)V_lds + v_rd_base(lane);
;     bf16x8 sv0[SDEPTH], sv1[SDEPTH], sk[SDEPTH][NKP];
;     ...
;     f32x16 pA0, pA1, pB0, pB1; float mnA, mnB, alA, alB; bf16x8 pa0, pa1, pa2, pa3; const int NT = seq / KVBLK;
;     if (ATT_PRIO && wid >= 4) __builtin_amdgcn_s_setprio(1);
;     constexpr int SE = 0, SO = SDEPTH - 1;
;     SLOAD(SE, 0); asm volatile("s_waitcnt vmcnt(0)" ::: "memory"); SWRITE(0, SE); __syncthreads();
;     qkt<DQK, QL>(pA0, pA1, K_lds, qr, qpark, r32, hi); if constexpr (NOMAX) { partialSM_nm(pA0); alA = 1.f; } else partialSM(pA0, pA1, m_reg, mnA, alA, C, thr_raw);
;     SLOAD(SO, KVBLK); if constexpr (SDEPTH == 2) { if (2 < NT) SLOAD(SE, 2 * KVBLK); }
.LBB0_1467:
	v_add_u32_e32 v0, s48, v190
	v_ashrrev_i32_e32 v28, 4, v0
	v_lshlrev_b32_e32 v34, 3, v190
	v_ashrrev_i32_e32 v35, 3, v0
	v_and_b32_e32 v36, 7, v190
	v_ashrrev_i32_e32 v29, 31, v28
	v_and_b32_e32 v2, 0x78, v34
	v_add_u32_e32 v30, 32, v28
	v_lshlrev_b32_e32 v0, 9, v35
	v_or_b32_e32 v37, 8, v36
	v_lshlrev_b64 v[16:17], 10, v[28:29]
	v_lshl_or_b32 v8, v36, 3, v0
	v_lshl_or_b32 v10, v37, 3, v0
	v_lshl_add_u64 v[0:1], s[26:27], 0, v[16:17]
	v_lshlrev_b32_e32 v2, 1, v2
	v_mov_b32_e32 v3, v33
	v_ashrrev_i32_e32 v31, 31, v30
	v_lshl_add_u64 v[22:23], v[0:1], 0, v[2:3]
	v_lshlrev_b64 v[0:1], 10, v[30:31]
	v_ashrrev_i32_e32 v9, 31, v8
	v_lshl_add_u64 v[0:1], s[26:27], 0, v[0:1]
	v_lshlrev_b64 v[18:19], 1, v[8:9]
	v_ashrrev_i32_e32 v11, 31, v10
	v_lshl_add_u64 v[4:5], v[0:1], 0, v[2:3]
	v_lshl_add_u64 v[26:27], s[24:25], 0, v[18:19]
	v_lshlrev_b64 v[20:21], 1, v[10:11]
	global_load_dwordx4 v[0:3], v[22:23], off
	s_nop 0
	global_load_dwordx4 v[4:7], v[4:5], off
	v_lshl_add_u64 v[24:25], s[24:25], 0, v[20:21]
	global_load_dwordx4 v[8:11], v[26:27], off
	global_load_dwordx4 v[12:15], v[24:25], off
	s_movk_i32 s6, 0x110
	v_mad_u32_u24 v31, v192, s6, 0
	v_add_u32_e32 v196, v31, v32
	v_and_b32_e32 v31, 0xfffff0, v28
	v_lshlrev_b32_e32 v32, 1, v28
	v_and_or_b32 v31, v32, 8, v31
	v_and_b32_e32 v32, 0xfffff0, v30
	v_lshlrev_b32_e32 v30, 1, v30
	v_bfe_u32 v34, v34, 5, 2
	v_lshrrev_b32_e32 v38, 1, v28
	v_and_b32_e32 v28, 3, v28
	v_lshrrev_b32_e32 v31, 1, v31
	v_and_or_b32 v30, v30, 8, v32
	v_lshlrev_b32_e32 v29, 4, v190
	v_and_or_b32 v28, v38, 4, v28
	v_or_b32_e32 v31, v31, v34
	v_lshrrev_b32_e32 v30, 1, v30
	v_and_b32_e32 v29, 48, v29
	v_lshlrev_b32_e32 v28, 6, v28
	v_lshlrev_b32_e32 v31, 9, v31
	v_or_b32_e32 v30, v30, v34
	v_mul_lo_u32 v35, v35, s6
	v_lshlrev_b32_e32 v30, 9, v30
	v_or3_b32 v31, v31, v28, v29
	v_lshl_add_u32 v36, v36, 4, v35
	v_lshl_add_u32 v35, v37, 4, v35
	v_or3_b32 v28, v30, v28, v29
	v_add_u32_e32 v199, 0, v31
	v_add_u32_e32 v197, 0, v36
	v_add_u32_e32 v198, 0, v35
	s_waitcnt vmcnt(0)
	v_add_u32_e32 v200, 0, v28
	s_mov_b32 s7, 0x10000
	v_add_co_u32_e32 v42, vcc, s7, v22
	s_mov_b32 s6, 0x18000
	s_nop 0
	v_addc_co_u32_e32 v43, vcc, 0, v23, vcc
	v_add_co_u32_e32 v46, vcc, s6, v22
	v_and_b32_e32 v32, 63, v190
	s_nop 0
	v_addc_co_u32_e32 v47, vcc, 0, v23, vcc
	v_add_co_u32_e32 v50, vcc, s7, v26
	v_lshlrev_b32_e32 v55, 4, v32
	s_nop 0
	v_addc_co_u32_e32 v51, vcc, 0, v27, vcc
	v_add_co_u32_e32 v52, vcc, s7, v24
	v_lshlrev_b32_e32 v54, 3, v32
	s_nop 0
	v_addc_co_u32_e32 v53, vcc, 0, v25, vcc
	v_lshlrev_b32_e32 v56, 1, v32
	v_and_b32_e32 v58, 32, v56
	v_and_b32_e32 v59, 0x100, v54
	s_mov_b32 s7, 0x28000
	s_cmp_lg_u32 0, -1
	s_cselect_b32 s6, 0, 0
	s_waitcnt vmcnt(3)
	ds_write_b128 v199, v[0:3]
	s_waitcnt vmcnt(2)
	ds_write_b128 v200, v[4:7]
	s_waitcnt vmcnt(1)
	ds_write_b128 v197, v[8:11] offset:32768
	s_waitcnt vmcnt(0)
	ds_write_b128 v198, v[12:15] offset:32768
	s_waitcnt lgkmcnt(0)
	s_barrier
	ds_read_b128 v[0:3], v196 offset:32768
	ds_read_b128 v[28:31], v196 offset:32800
	s_waitcnt lgkmcnt(1)
	v_mfma_f32_32x32x16_bf16 v[0:15], v[0:3], v[142:145], 0
	ds_read_b128 v[34:37], v196 offset:41472
	ds_read_b128 v[38:41], v196 offset:41504
	s_add_i32 s15, s53, -3
	s_lshl_b64 s[8:9], s[20:21], 10
	v_mov_b32_e32 v193, 0
	s_mov_b32 s14, 1
	v_mov_b32_e32 v61, v193
	v_mov_b32_e32 v62, v193
	s_waitcnt lgkmcnt(1)
	v_mfma_f32_32x32x16_bf16 v[66:81], v[34:37], v[142:145], 0
	v_mov_b32_e32 v63, v193
	v_mov_b32_e32 v64, v193
	v_mov_b32_e32 v65, v193
	v_mfma_f32_32x32x16_bf16 v[0:15], v[28:31], v[138:141], v[0:15]
	ds_read_b128 v[28:31], v196 offset:32832
	ds_read_b128 v[34:37], v196 offset:32864
	s_waitcnt lgkmcnt(2)
	v_mfma_f32_32x32x16_bf16 v[66:81], v[38:41], v[138:141], v[66:81]
	s_waitcnt lgkmcnt(1)
	v_mfma_f32_32x32x16_bf16 v[0:15], v[28:31], v[134:137], v[0:15]
	ds_read_b128 v[28:31], v196 offset:41536
	ds_read_b128 v[38:41], v196 offset:41568
	s_waitcnt lgkmcnt(1)
	v_mfma_f32_32x32x16_bf16 v[66:81], v[28:31], v[134:137], v[66:81]
	ds_read_b128 v[28:31], v196 offset:32896
	v_mfma_f32_32x32x16_bf16 v[0:15], v[34:37], v[130:133], v[0:15]
	s_waitcnt lgkmcnt(1)
	v_mfma_f32_32x32x16_bf16 v[66:81], v[38:41], v[130:133], v[66:81]
	ds_read_b128 v[34:37], v196 offset:41600
	ds_read_b128 v[38:41], v196 offset:32928
	s_waitcnt lgkmcnt(2)
	v_mfma_f32_32x32x16_bf16 v[0:15], v[28:31], v[126:129], v[0:15]
	ds_read_b128 v[28:31], v196 offset:41632
	global_load_dwordx4 v[42:45], v[42:43], off
	s_nop 0
	global_load_dwordx4 v[46:49], v[46:47], off
	s_waitcnt lgkmcnt(2)
	v_mfma_f32_32x32x16_bf16 v[66:81], v[34:37], v[126:129], v[66:81]
	global_load_dwordx4 v[34:37], v[50:51], off
	s_nop 0
	global_load_dwordx4 v[50:53], v[52:53], off
	s_waitcnt lgkmcnt(1)
	v_mfma_f32_32x32x16_bf16 v[0:15], v[38:41], v[122:125], v[0:15]
	ds_read_b128 v[38:41], v196 offset:32960
	s_waitcnt lgkmcnt(1)
	v_mfma_f32_32x32x16_bf16 v[66:81], v[28:31], v[122:125], v[66:81]
	v_and_b32_e32 v28, 0xc0, v55
	v_and_or_b32 v60, v54, 24, v28
	v_or3_b32 v60, v60, v58, v59
	v_add_co_u32_e32 v58, vcc, s66, v22
	ds_read_b128 v[28:31], v196 offset:41664
	ds_read_b128 v[54:57], v196 offset:32992
	v_addc_co_u32_e32 v59, vcc, 0, v23, vcc
	v_add_co_u32_e32 v22, vcc, s7, v22
	s_waitcnt lgkmcnt(2)
	v_mfma_f32_32x32x16_bf16 v[0:15], v[38:41], v[118:121], v[0:15]
	v_addc_co_u32_e32 v23, vcc, 0, v23, vcc
	v_add_co_u32_e32 v26, vcc, s66, v26
	ds_read_b128 v[38:41], v196 offset:41696
	s_nop 0
	v_addc_co_u32_e32 v27, vcc, 0, v27, vcc
	v_add_co_u32_e32 v24, vcc, s66, v24
	s_waitcnt lgkmcnt(2)
; #define SBAR() __builtin_amdgcn_sched_barrier(0)
; #define SLOAD(i, k0) do { sv0[i] = *reinterpret_cast<const bf16x8*>(&Vh[(size_t)((k0) + sr) * ldv + sc]); sv1[i] = *reinterpret_cast<const bf16x8*>(&Vh[(size_t)((k0) + 32 + sr) * ldv + sc]); \
;     _Pragma("unroll") for (int _q = 0; _q < NKP; ++_q) sk[i][_q] = *reinterpret_cast<const bf16x8*>(&Kh[(size_t)(k0) * ldk + koff[_q]]); } while (0)
; #define SWRITE(b, i) do { *(bf16x8*)(V_lds + (b) * SHM_V + vst0) = sv0[i]; *(bf16x8*)(V_lds + (b) * SHM_V + vst1) = sv1[i]; \
;     _Pragma("unroll") for (int _q = 0; _q < NKP; ++_q) *(bf16x8*)(K_lds + (b) * SHM_K + klds[_q]) = sk[i][_q]; } while (0)
; #define PVD0(...) do { if constexpr (PV_PIPE != 0) pv_d0_pipe(__VA_ARGS__); else pv_d0(__VA_ARGS__); } while (0)
; template <int DQK, int SDEPTH, int QL, bool NOMAX, int ldq, int ldk, int ldv, int ldo> ...
;     ...
;     SLOAD(SE, 0); asm volatile("s_waitcnt vmcnt(0)" ::: "memory"); SWRITE(0, SE); __syncthreads();
;     qkt<DQK, QL>(pA0, pA1, K_lds, qr, qpark, r32, hi); if constexpr (NOMAX) { partialSM_nm(pA0); alA = 1.f; } else partialSM(pA0, pA1, m_reg, mnA, alA, C, thr_raw);
;     SLOAD(SO, KVBLK); if constexpr (SDEPTH == 2) { if (2 < NT) SLOAD(SE, 2 * KVBLK); }
;     SWAIT(); SWRITE(1, SO); __syncthreads();
;     for (int j = 1; j + 1 < NT; j += 2) {
;         SBAR(); qkt<DQK, QL>(pB0, pB1, K_lds + SHM_K, qr, qpark, r32, hi);
;         finishSM(pA0, pA1, alA, l_reg, pa0, pa1, pa2, pa3); SBAR();
;         SLOAD(SO, (j + SDEPTH) * KVBLK); SBAR();
;         PVD0(o, vb0, pa0, pa1, pa2, pa3); if constexpr (NOMAX) { partialSM_nm(pB0); alB = 1.f; } else partialSM(pB0, pB1, m_reg, mnB, alB, C, thr_raw);
;         __syncthreads(); SWAIT(); SWRITE(0, SE);
;         RESC(alB); __syncthreads();
;         SBAR(); qkt<DQK, QL>(pA0, pA1, K_lds, qr, qpark, r32, hi);
;         finishSM(pB0, pB1, alB, l_reg, pa0, pa1, pa2, pa3); SBAR();
;         if (SDEPTH == 1 || j + 3 < NT) SLOAD(SE, (j + 1 + SDEPTH) * KVBLK); SBAR();
;         PVD0(o, vb0 + SHM_V, pa0, pa1, pa2, pa3); if constexpr (NOMAX) { partialSM_nm(pA0); alA = 1.f; } else partialSM(pA0, pA1, m_reg, mnA, alA, C, thr_raw);
;         __syncthreads(); SWAIT(); SWRITE(1, SO);
	v_mfma_f32_32x32x16_bf16 v[66:81], v[28:31], v[118:121], v[66:81]
	v_addc_co_u32_e32 v25, vcc, 0, v25, vcc
	global_load_dwordx4 v[146:149], v[58:59], off
	global_load_dwordx4 v[150:153], v[22:23], off
	global_load_dwordx4 v[154:157], v[26:27], off
	global_load_dwordx4 v[158:161], v[24:25], off
	v_add_u32_e32 v195, s6, v60
	s_addk_i32 s6, 0x4000
	v_add_u32_e32 v194, s6, v60
	s_lshl_b64 s[6:7], s[22:23], 8
	s_waitcnt lgkmcnt(1)
	v_mfma_f32_32x32x16_bf16 v[0:15], v[54:57], v[114:117], v[0:15]
	s_waitcnt vmcnt(4)
	s_waitcnt vmcnt(7)
	ds_write_b128 v199, v[42:45] offset:16384
	s_waitcnt vmcnt(6)
	ds_write_b128 v200, v[46:49] offset:16384
	s_waitcnt vmcnt(5)
	ds_write_b128 v197, v[34:37] offset:50176
	s_waitcnt vmcnt(4)
	ds_write_b128 v198, v[50:53] offset:50176
	s_waitcnt lgkmcnt(4)
	v_mfma_f32_32x32x16_bf16 v[66:81], v[38:41], v[114:117], v[66:81]
	s_nop 1
	v_exp_f32_e32 v206, v0
	v_exp_f32_e32 v209, v1
	v_exp_f32_e32 v204, v2
	v_exp_f32_e32 v207, v3
	v_exp_f32_e32 v203, v4
	v_exp_f32_e32 v205, v5
	v_exp_f32_e32 v208, v6
	v_exp_f32_e32 v216, v7
	v_exp_f32_e32 v189, v8
	v_exp_f32_e32 v202, v9
	v_exp_f32_e32 v187, v10
	v_exp_f32_e32 v201, v11
	v_exp_f32_e32 v184, v12
	v_exp_f32_e32 v188, v13
	v_exp_f32_e32 v185, v14
	v_exp_f32_e32 v186, v15
	v_lshl_add_u64 v[0:1], s[8:9], 0, v[16:17]
	v_and_b32_e32 v2, 15, v190
	s_add_u32 s8, s0, s8
	v_lshl_or_b32 v0, v2, 4, v0
	s_addc_u32 s9, s1, s9
	v_lshl_add_u64 v[178:179], s[0:1], 0, v[0:1]
	v_lshl_add_u64 v[180:181], s[8:9], 0, v[18:19]
	v_lshl_add_u64 v[182:183], s[8:9], 0, v[20:21]
	s_nop 0
	v_readfirstlane_b32 s98, v178
	v_readfirstlane_b32 s99, v179
	v_readfirstlane_b32 s100, v180
	v_readfirstlane_b32 s101, v181
	s_nop 1
	v_subrev_u32_e32 v240, s98, v178
	v_subrev_u32_e32 v242, s100, v180
	v_add_u32_e32 v241, 0x8000, v240
	s_add_u32 s98, s98, s6
	s_addc_u32 s99, s99, s7
	s_add_u32 s100, s100, s6
	s_addc_u32 s101, s101, s7
	s_add_u32 s98, s98, 0x3ca4c000
	s_addc_u32 s99, s99, 0
	s_add_u32 s100, s100, 0x398cc000
	s_addc_u32 s101, s101, 0
	v_mov_b32_e32 v50, 0
	v_mov_b32_e32 v51, v193
	v_mov_b32_e32 v52, v193
	v_mov_b32_e32 v53, v193
	v_mov_b32_e32 v54, v193
	v_mov_b32_e32 v55, v193
	v_mov_b32_e32 v56, v193
	v_mov_b32_e32 v57, v193
	v_mov_b32_e32 v58, v193
	v_mov_b32_e32 v59, v193
	v_mov_b32_e32 v60, v193
	v_mov_b32_e32 v34, 0
	v_mov_b32_e32 v35, v193
	v_mov_b32_e32 v36, v193
	v_mov_b32_e32 v37, v193
	v_mov_b32_e32 v38, v193
	v_mov_b32_e32 v39, v193
	v_mov_b32_e32 v40, v193
	v_mov_b32_e32 v41, v193
	v_mov_b32_e32 v42, v193
	v_mov_b32_e32 v43, v193
	v_mov_b32_e32 v44, v193
	v_mov_b32_e32 v45, v193
	v_mov_b32_e32 v46, v193
	v_mov_b32_e32 v47, v193
	v_mov_b32_e32 v48, v193
	v_mov_b32_e32 v49, v193
	v_mov_b32_e32 v16, 0
	v_mov_b32_e32 v17, v193
	v_mov_b32_e32 v18, v193
	v_mov_b32_e32 v19, v193
	v_mov_b32_e32 v20, v193
	v_mov_b32_e32 v21, v193
	v_mov_b32_e32 v22, v193
	v_mov_b32_e32 v23, v193
	v_mov_b32_e32 v24, v193
	v_mov_b32_e32 v25, v193
	v_mov_b32_e32 v26, v193
	v_mov_b32_e32 v27, v193
	v_mov_b32_e32 v28, v193
	v_mov_b32_e32 v29, v193
	v_mov_b32_e32 v30, v193
	v_mov_b32_e32 v31, v193
	v_mov_b32_e32 v0, 0
	v_mov_b32_e32 v1, v193
	v_mov_b32_e32 v2, v193
	v_mov_b32_e32 v3, v193
	v_mov_b32_e32 v4, v193
	v_mov_b32_e32 v5, v193
	v_mov_b32_e32 v6, v193
	v_mov_b32_e32 v7, v193
	v_mov_b32_e32 v8, v193
	v_mov_b32_e32 v9, v193
	v_mov_b32_e32 v10, v193
	v_mov_b32_e32 v11, v193
	v_mov_b32_e32 v12, v193
	v_mov_b32_e32 v13, v193
	v_mov_b32_e32 v14, v193
	v_mov_b32_e32 v15, v193
	s_waitcnt lgkmcnt(0)
	s_barrier
	s_branch .LBB0_1469
.LBB0_1468:
	v_add_f32_e32 v184, v193, v217
	s_add_i32 s14, s14, 2
	v_add_f32_e32 v193, v184, v201
	ds_read_b64_tr_b16 v[184:185], v194 offset:0
	ds_read_b64_tr_b16 v[186:187], v194 offset:0x800
	ds_read_b64_tr_b16 v[202:203], v194 offset:0x1000
	ds_read_b64_tr_b16 v[204:205], v194 offset:0x1800
	ds_read_b64_tr_b16 v[206:207], v194 offset:0x2000
	ds_read_b64_tr_b16 v[208:209], v194 offset:0x2800
	ds_read_b64_tr_b16 v[216:217], v194 offset:0x3000
	ds_read_b64_tr_b16 v[218:219], v194 offset:0x3800
	s_waitcnt lgkmcnt(6)
	s_nop 0
	v_mfma_f32_32x32x16_bf16 v[50:65], v[98:101], v[184:187], v[50:65]
	ds_read_b64_tr_b16 v[184:185], v194 offset:0x200
	ds_read_b64_tr_b16 v[186:187], v194 offset:0xa00
	s_waitcnt lgkmcnt(6)
	v_mfma_f32_32x32x16_bf16 v[50:65], v[102:105], v[202:205], v[50:65]
	ds_read_b64_tr_b16 v[202:203], v194 offset:0x1200
	ds_read_b64_tr_b16 v[204:205], v194 offset:0x1a00
	s_waitcnt lgkmcnt(6)
	v_mfma_f32_32x32x16_bf16 v[50:65], v[106:109], v[206:209], v[50:65]
	ds_read_b64_tr_b16 v[206:207], v194 offset:0x2200
	ds_read_b64_tr_b16 v[208:209], v194 offset:0x2a00
	s_waitcnt lgkmcnt(6)
	v_mfma_f32_32x32x16_bf16 v[50:65], v[110:113], v[216:219], v[50:65]
	ds_read_b64_tr_b16 v[216:217], v194 offset:0x3200
	ds_read_b64_tr_b16 v[218:219], v194 offset:0x3a00
	s_waitcnt lgkmcnt(6)
	v_mfma_f32_32x32x16_bf16 v[34:49], v[98:101], v[184:187], v[34:49]
	ds_read_b64_tr_b16 v[184:185], v194 offset:0x400
	ds_read_b64_tr_b16 v[186:187], v194 offset:0xc00
	s_waitcnt lgkmcnt(6)
	v_mfma_f32_32x32x16_bf16 v[34:49], v[102:105], v[202:205], v[34:49]
	ds_read_b64_tr_b16 v[202:203], v194 offset:0x1400
	ds_read_b64_tr_b16 v[204:205], v194 offset:0x1c00
	s_waitcnt lgkmcnt(6)
	v_mfma_f32_32x32x16_bf16 v[34:49], v[106:109], v[206:209], v[34:49]
	ds_read_b64_tr_b16 v[206:207], v194 offset:0x2400
	ds_read_b64_tr_b16 v[208:209], v194 offset:0x2c00
	s_waitcnt lgkmcnt(6)
	v_mfma_f32_32x32x16_bf16 v[34:49], v[110:113], v[216:219], v[34:49]
	ds_read_b64_tr_b16 v[216:217], v194 offset:0x3400
	ds_read_b64_tr_b16 v[218:219], v194 offset:0x3c00
	s_waitcnt lgkmcnt(6)
	v_mfma_f32_32x32x16_bf16 v[16:31], v[98:101], v[184:187], v[16:31]
	ds_read_b64_tr_b16 v[184:185], v194 offset:0x600
	ds_read_b64_tr_b16 v[186:187], v194 offset:0xe00
	s_waitcnt lgkmcnt(6)
	v_mfma_f32_32x32x16_bf16 v[16:31], v[102:105], v[202:205], v[16:31]
	ds_read_b64_tr_b16 v[202:203], v194 offset:0x1600
	ds_read_b64_tr_b16 v[204:205], v194 offset:0x1e00
	s_waitcnt lgkmcnt(6)
	v_mfma_f32_32x32x16_bf16 v[16:31], v[106:109], v[206:209], v[16:31]
	ds_read_b64_tr_b16 v[206:207], v194 offset:0x2600
	ds_read_b64_tr_b16 v[208:209], v194 offset:0x2e00
	s_waitcnt lgkmcnt(6)
	v_mfma_f32_32x32x16_bf16 v[16:31], v[110:113], v[216:219], v[16:31]
	ds_read_b64_tr_b16 v[216:217], v194 offset:0x3600
	ds_read_b64_tr_b16 v[218:219], v194 offset:0x3e00
	s_waitcnt lgkmcnt(0)
	v_mfma_f32_32x32x16_bf16 v[0:15], v[98:101], v[184:187], v[0:15]
	v_exp_f32_e32 v189, v90
	v_exp_f32_e32 v187, v92
	v_exp_f32_e32 v201, v93
	v_exp_f32_e32 v184, v94
	v_exp_f32_e32 v188, v95
	v_exp_f32_e32 v185, v96
	v_exp_f32_e32 v186, v97
	v_mfma_f32_32x32x16_bf16 v[0:15], v[102:105], v[202:205], v[0:15]
	v_exp_f32_e32 v204, v84
	v_exp_f32_e32 v203, v86
	v_exp_f32_e32 v205, v87
	v_exp_f32_e32 v202, v91
	s_barrier
; #define SBAR() __builtin_amdgcn_sched_barrier(0)
; #define SLOAD(i, k0) do { sv0[i] = *reinterpret_cast<const bf16x8*>(&Vh[(size_t)((k0) + sr) * ldv + sc]); sv1[i] = *reinterpret_cast<const bf16x8*>(&Vh[(size_t)((k0) + 32 + sr) * ldv + sc]); \
;     _Pragma("unroll") for (int _q = 0; _q < NKP; ++_q) sk[i][_q] = *reinterpret_cast<const bf16x8*>(&Kh[(size_t)(k0) * ldk + koff[_q]]); } while (0)
; #define SWRITE(b, i) do { *(bf16x8*)(V_lds + (b) * SHM_V + vst0) = sv0[i]; *(bf16x8*)(V_lds + (b) * SHM_V + vst1) = sv1[i]; \
;     _Pragma("unroll") for (int _q = 0; _q < NKP; ++_q) *(bf16x8*)(K_lds + (b) * SHM_K + klds[_q]) = sk[i][_q]; } while (0)
; #define SWAIT() do { if constexpr (SDEPTH == 2) { if constexpr (NKP == 1) asm volatile("s_waitcnt vmcnt(3)" ::: "memory"); else if constexpr (NKP == 2) asm volatile("s_waitcnt vmcnt(4)" ::: "memory"); else asm volatile("s_waitcnt vmcnt(5)" ::: "memory"); } \
;     else asm volatile("s_waitcnt vmcnt(0)" ::: "memory"); } while (0)
; #define PVD0(...) do { if constexpr (PV_PIPE != 0) pv_d0_pipe(__VA_ARGS__); else pv_d0(__VA_ARGS__); } while (0)
; #define SWRITE(b) do { *(bf16x8*)(V_lds + (b) * SHM_V + vst0) = sv0; *(bf16x8*)(V_lds + (b) * SHM_V + vst1) = sv1; \
;     _Pragma("unroll") for (int _q = 0; _q < NKP; ++_q) *(bf16x8*)(K_lds + (b) * SHM_K + klds[_q]) = sk[_q]; } while (0)
; template <int DQK, int SDEPTH, int QL, bool NOMAX, int ldq, int ldk, int ldv, int ldo> ...
;     ...
;         SBAR(); qkt<DQK, QL>(pB0, pB1, K_lds + SHM_K, qr, qpark, r32, hi);
;         finishSM(pA0, pA1, alA, l_reg, pa0, pa1, pa2, pa3); SBAR();
;         SLOAD(SO, (j + SDEPTH) * KVBLK); SBAR();
;         PVD0(o, vb0, pa0, pa1, pa2, pa3); if constexpr (NOMAX) { partialSM_nm(pB0); alB = 1.f; } else partialSM(pB0, pB1, m_reg, mnB, alB, C, thr_raw);
;         __syncthreads(); SWAIT(); SWRITE(0, SE);
;         RESC(alB); __syncthreads();
;         SBAR(); qkt<DQK, QL>(pA0, pA1, K_lds, qr, qpark, r32, hi);
;         finishSM(pB0, pB1, alB, l_reg, pa0, pa1, pa2, pa3); SBAR();
;         if (SDEPTH == 1 || j + 3 < NT) SLOAD(SE, (j + 1 + SDEPTH) * KVBLK); SBAR();
;         PVD0(o, vb0 + SHM_V, pa0, pa1, pa2, pa3); if constexpr (NOMAX) { partialSM_nm(pA0); alA = 1.f; } else partialSM(pA0, pA1, m_reg, mnA, alA, C, thr_raw);
;         __syncthreads(); SWAIT(); SWRITE(1, SO);
;         RESC(alA); __syncthreads();
	v_mfma_f32_32x32x16_bf16 v[0:15], v[106:109], v[206:209], v[0:15]
	v_exp_f32_e32 v206, v82
	v_exp_f32_e32 v209, v83
	v_exp_f32_e32 v207, v85
	v_exp_f32_e32 v208, v88
	s_waitcnt vmcnt(4)
	v_mfma_f32_32x32x16_bf16 v[0:15], v[110:113], v[216:219], v[0:15]
	v_exp_f32_e32 v216, v89
	s_and_b64 vcc, exec, s[8:9]
	s_waitcnt vmcnt(3)
	ds_write_b128 v199, v[162:165] offset:16384
	s_waitcnt vmcnt(2)
	ds_write_b128 v200, v[166:169] offset:16384
	s_waitcnt vmcnt(1)
	ds_write_b128 v197, v[170:173] offset:50176
	s_waitcnt vmcnt(0)
	ds_write_b128 v198, v[174:177] offset:50176
	s_waitcnt lgkmcnt(0)
	s_barrier
	s_cbranch_vccnz .LBB0_1471
.LBB0_1469:
	ds_read_b128 v[98:101], v196 offset:58880
	ds_read_b128 v[82:85], v196 offset:50176
	ds_read_b128 v[102:105], v196 offset:50208
	ds_read_b128 v[162:165], v196 offset:58912
	v_exp_f32_e32 v106, v70
	v_exp_f32_e32 v107, v71
	s_waitcnt lgkmcnt(2)
	v_mfma_f32_32x32x16_bf16 v[82:97], v[82:85], v[142:145], 0
	v_exp_f32_e32 v108, v72
	v_exp_f32_e32 v109, v73
	v_exp_f32_e32 v110, v74
	v_exp_f32_e32 v111, v75
	v_exp_f32_e32 v112, v76
	v_exp_f32_e32 v113, v77
	v_exp_f32_e32 v210, v78
	s_waitcnt lgkmcnt(1)
	v_mfma_f32_32x32x16_bf16 v[82:97], v[102:105], v[138:141], v[82:97]
	ds_read_b128 v[102:105], v196 offset:50240
	ds_read_b128 v[166:169], v196 offset:58944
	v_exp_f32_e32 v211, v79
	v_exp_f32_e32 v212, v80
	v_exp_f32_e32 v81, v81
	s_waitcnt lgkmcnt(1)
	v_mfma_f32_32x32x16_bf16 v[82:97], v[102:105], v[134:137], v[82:97]
	ds_read_b128 v[102:105], v196 offset:50272
	ds_read_b128 v[170:173], v196 offset:58976
	s_waitcnt lgkmcnt(1)
	v_mfma_f32_32x32x16_bf16 v[82:97], v[102:105], v[130:133], v[82:97]
	ds_read_b128 v[102:105], v196 offset:50304
	ds_read_b128 v[174:177], v196 offset:59008
	s_waitcnt lgkmcnt(1)
	v_mfma_f32_32x32x16_bf16 v[82:97], v[102:105], v[126:129], v[82:97]
	ds_read_b128 v[102:105], v196 offset:50336
	ds_read_b128 v[220:223], v196 offset:59040
	s_waitcnt lgkmcnt(1)
	v_mfma_f32_32x32x16_bf16 v[82:97], v[102:105], v[122:125], v[82:97]
	ds_read_b128 v[102:105], v196 offset:50368
	ds_read_b128 v[224:227], v196 offset:59072
	s_waitcnt lgkmcnt(1)
	v_mfma_f32_32x32x16_bf16 v[82:97], v[102:105], v[118:121], v[82:97]
	ds_read_b128 v[102:105], v196 offset:50400
	ds_read_b128 v[228:231], v196 offset:59104
	s_waitcnt lgkmcnt(1)
	v_mfma_f32_32x32x16_bf16 v[82:97], v[102:105], v[114:117], v[82:97]
	v_exp_f32_e32 v102, v66
	v_add_f32_e32 v66, 0, v206
	v_add_f32_e32 v66, v209, v66
	v_add_f32_e32 v66, v204, v66
	v_add_f32_e32 v66, v207, v66
	v_add_f32_e32 v66, v203, v66
	v_add_f32_e32 v66, v205, v66
	v_add_f32_e32 v66, v208, v66
	v_add_f32_e32 v66, v216, v66
	v_add_f32_e32 v66, v189, v66
	v_add_f32_e32 v66, v202, v66
	v_add_f32_e32 v66, v187, v66
	v_add_f32_e32 v66, v201, v66
	v_add_f32_e32 v66, v184, v66
	v_exp_f32_e32 v103, v67
	v_add_f32_e32 v66, v188, v66
	v_exp_f32_e32 v104, v68
	v_add_f32_e32 v66, v185, v66
	v_exp_f32_e32 v105, v69
	v_add_f32_e32 v66, v186, v66
	v_add_f32_e32 v66, v102, v66
	v_add_f32_e32 v66, v103, v66
	v_add_f32_e32 v66, v104, v66
	v_add_f32_e32 v66, v105, v66
	v_add_f32_e32 v66, v106, v66
	v_add_f32_e32 v66, v107, v66
	v_add_f32_e32 v66, v108, v66
	v_add_f32_e32 v66, v109, v66
	v_add_f32_e32 v66, v110, v66
	v_add_f32_e32 v66, v111, v66
	v_add_f32_e32 v66, v112, v66
	v_add_f32_e32 v66, v113, v66
	v_add_f32_e32 v66, v210, v66
	v_add_f32_e32 v66, v211, v66
	v_add_f32_e32 v66, v212, v66
	v_add_f32_e32 v217, v81, v66
	v_cvt_pk_bf16_f32 v66, v206, v209
	v_cvt_pk_bf16_f32 v67, v204, v207
	v_cvt_pk_bf16_f32 v68, v203, v205
	v_cvt_pk_bf16_f32 v69, v208, v216
	v_cvt_pk_bf16_f32 v70, v189, v202
	v_cvt_pk_bf16_f32 v71, v187, v201
	v_cvt_pk_bf16_f32 v72, v184, v188
	v_cvt_pk_bf16_f32 v73, v185, v186
	v_cvt_pk_bf16_f32 v74, v102, v103
	v_cvt_pk_bf16_f32 v75, v104, v105
	v_cvt_pk_bf16_f32 v76, v106, v107
	v_cvt_pk_bf16_f32 v77, v108, v109
	v_cvt_pk_bf16_f32 v78, v110, v111
	v_cvt_pk_bf16_f32 v79, v112, v113
	v_cvt_pk_bf16_f32 v80, v210, v211
	v_cvt_pk_bf16_f32 v81, v212, v81
	s_nop 1
	v_permlane32_swap_b32_e32 v66, v68
	v_permlane32_swap_b32_e32 v67, v69
	v_permlane32_swap_b32_e32 v70, v72
	v_permlane32_swap_b32_e32 v71, v73
	v_permlane32_swap_b32_e32 v74, v76
	v_permlane32_swap_b32_e32 v75, v77
	v_permlane32_swap_b32_e32 v78, v80
	v_permlane32_swap_b32_e32 v79, v81
	v_mfma_f32_32x32x16_bf16 v[98:113], v[98:101], v[142:145], 0
	v_mfma_f32_32x32x16_bf16 v[98:113], v[162:165], v[138:141], v[98:113]
	v_mfma_f32_32x32x16_bf16 v[98:113], v[166:169], v[134:137], v[98:113]
	global_load_dwordx4 v[162:165], v240, s[98:99] offset:256
	global_load_dwordx4 v[166:169], v241, s[98:99] offset:256
	v_mfma_f32_32x32x16_bf16 v[98:113], v[170:173], v[130:133], v[98:113]
	global_load_dwordx4 v[170:173], v242, s[100:101] offset:256
	v_mfma_f32_32x32x16_bf16 v[98:113], v[174:177], v[126:129], v[98:113]
	global_load_dwordx4 v[174:177], v242, s[100:101] offset:384
	s_add_u32 s98, s98, 0x10000
	s_addc_u32 s99, s99, 0
	s_add_u32 s100, s100, 0x10000
	s_addc_u32 s101, s101, 0
	v_mfma_f32_32x32x16_bf16 v[98:113], v[220:223], v[122:125], v[98:113]
	v_mfma_f32_32x32x16_bf16 v[98:113], v[224:227], v[118:121], v[98:113]
	s_waitcnt lgkmcnt(0)
	v_mfma_f32_32x32x16_bf16 v[98:113], v[228:231], v[114:117], v[98:113]
	ds_read_b64_tr_b16 v[202:203], v195 offset:0
	ds_read_b64_tr_b16 v[204:205], v195 offset:0x800
	ds_read_b64_tr_b16 v[206:207], v195 offset:0x1000
	ds_read_b64_tr_b16 v[208:209], v195 offset:0x1800
	ds_read_b64_tr_b16 v[220:221], v195 offset:0x2000
	ds_read_b64_tr_b16 v[222:223], v195 offset:0x2800
	ds_read_b64_tr_b16 v[224:225], v195 offset:0x3000
	ds_read_b64_tr_b16 v[226:227], v195 offset:0x3800
	s_waitcnt lgkmcnt(6)
; #define SBAR() __builtin_amdgcn_sched_barrier(0)
; #define SWRITE(b, i) do { *(bf16x8*)(V_lds + (b) * SHM_V + vst0) = sv0[i]; *(bf16x8*)(V_lds + (b) * SHM_V + vst1) = sv1[i]; \
;     _Pragma("unroll") for (int _q = 0; _q < NKP; ++_q) *(bf16x8*)(K_lds + (b) * SHM_K + klds[_q]) = sk[i][_q]; } while (0)
; #define SWAIT() do { if constexpr (SDEPTH == 2) { if constexpr (NKP == 1) asm volatile("s_waitcnt vmcnt(3)" ::: "memory"); else if constexpr (NKP == 2) asm volatile("s_waitcnt vmcnt(4)" ::: "memory"); else asm volatile("s_waitcnt vmcnt(5)" ::: "memory"); } \
;     else asm volatile("s_waitcnt vmcnt(0)" ::: "memory"); } while (0)
; #define PVD0(...) do { if constexpr (PV_PIPE != 0) pv_d0_pipe(__VA_ARGS__); else pv_d0(__VA_ARGS__); } while (0)
; #define RESC(a) do { if constexpr (!NOMAX) if (__any((a) < 1.f)) { if (hi == 0) al_l[r32] = (a); asm volatile("s_waitcnt lgkmcnt(0)" ::: "memory"); \
;     _Pragma("unroll") for (int d = 0; d < 4; ++d) _Pragma("unroll") for (int r = 0; r < 16; ++r) o[d][r] *= al_l[crow(r, hi)]; } } while (0)
; #define SWRITE(b) do { *(bf16x8*)(V_lds + (b) * SHM_V + vst0) = sv0; *(bf16x8*)(V_lds + (b) * SHM_V + vst1) = sv1; \
;     _Pragma("unroll") for (int _q = 0; _q < NKP; ++_q) *(bf16x8*)(K_lds + (b) * SHM_K + klds[_q]) = sk[_q]; } while (0)
; #define RESC(a) do { if (__any((a) < 1.f)) { if (hi == 0) al_l[r32] = (a); asm volatile("s_waitcnt lgkmcnt(0)" ::: "memory"); \
;     _Pragma("unroll") for (int d = 0; d < 4; ++d) _Pragma("unroll") for (int r = 0; r < 16; ++r) o[d][r] *= al_l[crow(r, hi)]; } } while (0)
; template <int DQK, int SDEPTH, int QL, bool NOMAX, int ldq, int ldk, int ldv, int ldo> ...
;     ...
;         PVD0(o, vb0, pa0, pa1, pa2, pa3); if constexpr (NOMAX) { partialSM_nm(pB0); alB = 1.f; } else partialSM(pB0, pB1, m_reg, mnB, alB, C, thr_raw);
;         __syncthreads(); SWAIT(); SWRITE(0, SE);
;         RESC(alB); __syncthreads();
;         SBAR(); qkt<DQK, QL>(pA0, pA1, K_lds, qr, qpark, r32, hi);
;         finishSM(pB0, pB1, alB, l_reg, pa0, pa1, pa2, pa3); SBAR();
	s_nop 0
	v_mfma_f32_32x32x16_bf16 v[50:65], v[66:69], v[202:205], v[50:65]
	ds_read_b64_tr_b16 v[202:203], v195 offset:0x200
	ds_read_b64_tr_b16 v[204:205], v195 offset:0xa00
	s_waitcnt lgkmcnt(6)
	v_mfma_f32_32x32x16_bf16 v[50:65], v[70:73], v[206:209], v[50:65]
	ds_read_b64_tr_b16 v[206:207], v195 offset:0x1200
	ds_read_b64_tr_b16 v[208:209], v195 offset:0x1a00
	s_waitcnt lgkmcnt(6)
	v_mfma_f32_32x32x16_bf16 v[50:65], v[74:77], v[220:223], v[50:65]
	ds_read_b64_tr_b16 v[220:221], v195 offset:0x2200
	ds_read_b64_tr_b16 v[222:223], v195 offset:0x2a00
	s_waitcnt lgkmcnt(6)
	v_mfma_f32_32x32x16_bf16 v[50:65], v[78:81], v[224:227], v[50:65]
	ds_read_b64_tr_b16 v[224:225], v195 offset:0x3200
	ds_read_b64_tr_b16 v[226:227], v195 offset:0x3a00
	s_waitcnt lgkmcnt(6)
	v_mfma_f32_32x32x16_bf16 v[34:49], v[66:69], v[202:205], v[34:49]
	ds_read_b64_tr_b16 v[202:203], v195 offset:0x400
	ds_read_b64_tr_b16 v[204:205], v195 offset:0xc00
	s_waitcnt lgkmcnt(6)
	v_mfma_f32_32x32x16_bf16 v[34:49], v[70:73], v[206:209], v[34:49]
	ds_read_b64_tr_b16 v[206:207], v195 offset:0x1400
	ds_read_b64_tr_b16 v[208:209], v195 offset:0x1c00
	s_waitcnt lgkmcnt(6)
	v_mfma_f32_32x32x16_bf16 v[34:49], v[74:77], v[220:223], v[34:49]
	ds_read_b64_tr_b16 v[220:221], v195 offset:0x2400
	ds_read_b64_tr_b16 v[222:223], v195 offset:0x2c00
	s_waitcnt lgkmcnt(6)
	v_mfma_f32_32x32x16_bf16 v[34:49], v[78:81], v[224:227], v[34:49]
	ds_read_b64_tr_b16 v[224:225], v195 offset:0x3400
	ds_read_b64_tr_b16 v[226:227], v195 offset:0x3c00
	s_waitcnt lgkmcnt(6)
	v_mfma_f32_32x32x16_bf16 v[16:31], v[66:69], v[202:205], v[16:31]
	ds_read_b64_tr_b16 v[202:203], v195 offset:0x600
	ds_read_b64_tr_b16 v[204:205], v195 offset:0xe00
	s_waitcnt lgkmcnt(6)
	v_mfma_f32_32x32x16_bf16 v[16:31], v[70:73], v[206:209], v[16:31]
	ds_read_b64_tr_b16 v[206:207], v195 offset:0x1600
	ds_read_b64_tr_b16 v[208:209], v195 offset:0x1e00
	s_waitcnt lgkmcnt(6)
	v_mfma_f32_32x32x16_bf16 v[16:31], v[74:77], v[220:223], v[16:31]
	ds_read_b64_tr_b16 v[220:221], v195 offset:0x2600
	ds_read_b64_tr_b16 v[222:223], v195 offset:0x2e00
	s_waitcnt lgkmcnt(6)
	v_mfma_f32_32x32x16_bf16 v[16:31], v[78:81], v[224:227], v[16:31]
	ds_read_b64_tr_b16 v[224:225], v195 offset:0x3600
	ds_read_b64_tr_b16 v[226:227], v195 offset:0x3e00
	s_waitcnt lgkmcnt(0)
	v_mfma_f32_32x32x16_bf16 v[0:15], v[66:69], v[202:205], v[0:15]
	s_barrier
	s_waitcnt vmcnt(4)
	s_waitcnt vmcnt(7)
	ds_write_b128 v199, v[146:149]
	s_waitcnt vmcnt(6)
	ds_write_b128 v200, v[150:153]
	s_waitcnt vmcnt(5)
	ds_write_b128 v197, v[154:157] offset:32768
	s_waitcnt vmcnt(4)
	ds_write_b128 v198, v[158:161] offset:32768
	v_exp_f32_e32 v210, v82
	v_mfma_f32_32x32x16_bf16 v[0:15], v[70:73], v[206:209], v[0:15]
	v_exp_f32_e32 v211, v83
	v_exp_f32_e32 v212, v84
	v_exp_f32_e32 v213, v85
	v_exp_f32_e32 v214, v86
	v_exp_f32_e32 v215, v87
	v_exp_f32_e32 v216, v88
	v_exp_f32_e32 v219, v89
	v_mfma_f32_32x32x16_bf16 v[0:15], v[74:77], v[220:223], v[0:15]
	v_exp_f32_e32 v228, v90
	v_exp_f32_e32 v229, v91
	v_exp_f32_e32 v230, v92
	v_exp_f32_e32 v220, v93
	v_exp_f32_e32 v221, v94
	v_exp_f32_e32 v222, v95
	v_exp_f32_e32 v223, v96
	v_mfma_f32_32x32x16_bf16 v[0:15], v[78:81], v[224:227], v[0:15]
	v_exp_f32_e32 v231, v97
	s_waitcnt lgkmcnt(0)
	s_barrier
	ds_read_b128 v[66:69], v196 offset:41472
	ds_read_b128 v[70:73], v196 offset:32768
	ds_read_b128 v[202:205], v196 offset:32800
	ds_read_b128 v[206:209], v196 offset:41504
	v_exp_f32_e32 v224, v105
	v_exp_f32_e32 v225, v106
	s_waitcnt lgkmcnt(2)
	v_mfma_f32_32x32x16_bf16 v[82:97], v[70:73], v[142:145], 0
	v_exp_f32_e32 v226, v107
	v_exp_f32_e32 v227, v108
	v_exp_f32_e32 v232, v109
	v_exp_f32_e32 v233, v110
	v_exp_f32_e32 v236, v111
	v_exp_f32_e32 v237, v112
	v_exp_f32_e32 v113, v113
	v_mfma_f32_32x32x16_bf16 v[66:81], v[66:69], v[142:145], 0
	s_waitcnt lgkmcnt(1)
	v_mfma_f32_32x32x16_bf16 v[82:97], v[202:205], v[138:141], v[82:97]
	s_waitcnt lgkmcnt(0)
	v_mfma_f32_32x32x16_bf16 v[66:81], v[206:209], v[138:141], v[66:81]
	ds_read_b128 v[202:205], v196 offset:32832
	ds_read_b128 v[206:209], v196 offset:41536
	s_waitcnt lgkmcnt(1)
	v_mfma_f32_32x32x16_bf16 v[82:97], v[202:205], v[134:137], v[82:97]
	s_waitcnt lgkmcnt(0)
	v_mfma_f32_32x32x16_bf16 v[66:81], v[206:209], v[134:137], v[66:81]
	ds_read_b128 v[202:205], v196 offset:32864
	ds_read_b128 v[206:209], v196 offset:41568
	s_waitcnt lgkmcnt(1)
	v_mfma_f32_32x32x16_bf16 v[82:97], v[202:205], v[130:133], v[82:97]
	s_waitcnt lgkmcnt(0)
	v_mfma_f32_32x32x16_bf16 v[66:81], v[206:209], v[130:133], v[66:81]
	ds_read_b128 v[202:205], v196 offset:32896
	ds_read_b128 v[206:209], v196 offset:41600
	s_waitcnt lgkmcnt(1)
	v_mfma_f32_32x32x16_bf16 v[82:97], v[202:205], v[126:129], v[82:97]
	s_waitcnt lgkmcnt(0)
	v_mfma_f32_32x32x16_bf16 v[66:81], v[206:209], v[126:129], v[66:81]
	ds_read_b128 v[202:205], v196 offset:32928
	ds_read_b128 v[206:209], v196 offset:41632
	s_waitcnt lgkmcnt(1)
	v_mfma_f32_32x32x16_bf16 v[82:97], v[202:205], v[122:125], v[82:97]
	s_waitcnt lgkmcnt(0)
	v_mfma_f32_32x32x16_bf16 v[66:81], v[206:209], v[122:125], v[66:81]
	ds_read_b128 v[202:205], v196 offset:32960
	ds_read_b128 v[206:209], v196 offset:41664
	s_waitcnt lgkmcnt(1)
	v_mfma_f32_32x32x16_bf16 v[82:97], v[202:205], v[118:121], v[82:97]
	s_waitcnt lgkmcnt(0)
	v_mfma_f32_32x32x16_bf16 v[66:81], v[206:209], v[118:121], v[66:81]
	ds_read_b128 v[202:205], v196 offset:32992
	ds_read_b128 v[206:209], v196 offset:41696
	s_waitcnt lgkmcnt(1)
; #define SBAR() __builtin_amdgcn_sched_barrier(0)
; #define SLOAD(i, k0) do { sv0[i] = *reinterpret_cast<const bf16x8*>(&Vh[(size_t)((k0) + sr) * ldv + sc]); sv1[i] = *reinterpret_cast<const bf16x8*>(&Vh[(size_t)((k0) + 32 + sr) * ldv + sc]); \
;     _Pragma("unroll") for (int _q = 0; _q < NKP; ++_q) sk[i][_q] = *reinterpret_cast<const bf16x8*>(&Kh[(size_t)(k0) * ldk + koff[_q]]); } while (0)
; #define SWRITE(b, i) do { *(bf16x8*)(V_lds + (b) * SHM_V + vst0) = sv0[i]; *(bf16x8*)(V_lds + (b) * SHM_V + vst1) = sv1[i]; \
;     _Pragma("unroll") for (int _q = 0; _q < NKP; ++_q) *(bf16x8*)(K_lds + (b) * SHM_K + klds[_q]) = sk[i][_q]; } while (0)
; #define SWAIT() do { if constexpr (SDEPTH == 2) { if constexpr (NKP == 1) asm volatile("s_waitcnt vmcnt(3)" ::: "memory"); else if constexpr (NKP == 2) asm volatile("s_waitcnt vmcnt(4)" ::: "memory"); else asm volatile("s_waitcnt vmcnt(5)" ::: "memory"); } \
;     else asm volatile("s_waitcnt vmcnt(0)" ::: "memory"); } while (0)
; #define PVD0(...) do { if constexpr (PV_PIPE != 0) pv_d0_pipe(__VA_ARGS__); else pv_d0(__VA_ARGS__); } while (0)
; #define RESC(a) do { if constexpr (!NOMAX) if (__any((a) < 1.f)) { if (hi == 0) al_l[r32] = (a); asm volatile("s_waitcnt lgkmcnt(0)" ::: "memory"); \
;     _Pragma("unroll") for (int d = 0; d < 4; ++d) _Pragma("unroll") for (int r = 0; r < 16; ++r) o[d][r] *= al_l[crow(r, hi)]; } } while (0)
; #define SWRITE(b) do { *(bf16x8*)(V_lds + (b) * SHM_V + vst0) = sv0; *(bf16x8*)(V_lds + (b) * SHM_V + vst1) = sv1; \
;     _Pragma("unroll") for (int _q = 0; _q < NKP; ++_q) *(bf16x8*)(K_lds + (b) * SHM_K + klds[_q]) = sk[_q]; } while (0)
; template <int DQK, int SDEPTH, int QL, bool NOMAX, int ldq, int ldk, int ldv, int ldo> ...
;     ...
;         SBAR(); qkt<DQK, QL>(pA0, pA1, K_lds, qr, qpark, r32, hi);
;         finishSM(pB0, pB1, alB, l_reg, pa0, pa1, pa2, pa3); SBAR();
;         if (SDEPTH == 1 || j + 3 < NT) SLOAD(SE, (j + 1 + SDEPTH) * KVBLK); SBAR();
;         PVD0(o, vb0 + SHM_V, pa0, pa1, pa2, pa3); if constexpr (NOMAX) { partialSM_nm(pA0); alA = 1.f; } else partialSM(pA0, pA1, m_reg, mnA, alA, C, thr_raw);
;         __syncthreads(); SWAIT(); SWRITE(1, SO);
;         RESC(alA); __syncthreads();
;     }
;     SBAR(); qkt<DQK, QL>(pB0, pB1, K_lds + SHM_K, qr, qpark, r32, hi);
;     finishSM(pA0, pA1, alA, l_reg, pa0, pa1, pa2, pa3); SBAR();
	v_mfma_f32_32x32x16_bf16 v[82:97], v[202:205], v[114:117], v[82:97]
	v_exp_f32_e32 v203, v98
	v_add_f32_e32 v98, 0, v210
	v_add_f32_e32 v98, v211, v98
	v_add_f32_e32 v98, v212, v98
	v_add_f32_e32 v98, v213, v98
	v_add_f32_e32 v98, v214, v98
	v_add_f32_e32 v98, v215, v98
	v_add_f32_e32 v98, v216, v98
	v_add_f32_e32 v98, v219, v98
	v_add_f32_e32 v98, v228, v98
	v_add_f32_e32 v98, v229, v98
	v_add_f32_e32 v98, v230, v98
	v_add_f32_e32 v98, v220, v98
	v_add_f32_e32 v98, v221, v98
	v_exp_f32_e32 v204, v99
	v_add_f32_e32 v98, v222, v98
	v_exp_f32_e32 v205, v100
	v_add_f32_e32 v98, v223, v98
	s_waitcnt lgkmcnt(0)
	v_mfma_f32_32x32x16_bf16 v[66:81], v[206:209], v[114:117], v[66:81]
	v_exp_f32_e32 v206, v101
	v_add_f32_e32 v98, v231, v98
	v_exp_f32_e32 v207, v102
	v_add_f32_e32 v98, v98, v203
	v_exp_f32_e32 v208, v103
	v_add_f32_e32 v98, v204, v98
	v_exp_f32_e32 v209, v104
	v_add_f32_e32 v98, v205, v98
	v_add_f32_e32 v98, v206, v98
	v_add_f32_e32 v98, v207, v98
	v_add_f32_e32 v98, v208, v98
	v_add_f32_e32 v98, v209, v98
	v_add_f32_e32 v98, v224, v98
	v_add_f32_e32 v98, v225, v98
	v_add_f32_e32 v98, v226, v98
	v_add_f32_e32 v98, v227, v98
	v_add_f32_e32 v98, v232, v98
	v_add_f32_e32 v98, v233, v98
	v_add_f32_e32 v98, v236, v98
	v_add_f32_e32 v98, v237, v98
	v_add_f32_e32 v201, v113, v98
	v_cvt_pk_bf16_f32 v98, v210, v211
	v_cvt_pk_bf16_f32 v99, v212, v213
	v_cvt_pk_bf16_f32 v100, v214, v215
	v_cvt_pk_bf16_f32 v101, v216, v219
	v_cvt_pk_bf16_f32 v102, v228, v229
	v_cvt_pk_bf16_f32 v103, v230, v220
	v_cvt_pk_bf16_f32 v104, v221, v222
	v_cvt_pk_bf16_f32 v105, v223, v231
	v_cvt_pk_bf16_f32 v106, v203, v204
	v_cvt_pk_bf16_f32 v107, v205, v206
	v_cvt_pk_bf16_f32 v108, v207, v208
	v_cvt_pk_bf16_f32 v109, v209, v224
	v_cvt_pk_bf16_f32 v110, v225, v226
	v_cvt_pk_bf16_f32 v111, v227, v232
	v_cvt_pk_bf16_f32 v112, v233, v236
	v_cvt_pk_bf16_f32 v113, v237, v113
	s_nop 1
	v_permlane32_swap_b32_e32 v98, v100
	v_permlane32_swap_b32_e32 v99, v101
	v_permlane32_swap_b32_e32 v102, v104
	v_permlane32_swap_b32_e32 v103, v105
	v_permlane32_swap_b32_e32 v106, v108
	v_permlane32_swap_b32_e32 v107, v109
	v_permlane32_swap_b32_e32 v110, v112
	v_permlane32_swap_b32_e32 v111, v113
	s_cmp_ge_u32 s14, s15
	s_cselect_b64 s[8:9], -1, 0
	s_and_b64 vcc, exec, s[8:9]
	s_cbranch_vccnz .LBB0_1468
	global_load_dwordx4 v[146:149], v240, s[98:99] offset:256
	global_load_dwordx4 v[150:153], v241, s[98:99] offset:256
	global_load_dwordx4 v[154:157], v242, s[100:101] offset:256
	global_load_dwordx4 v[158:161], v242, s[100:101] offset:384
	s_add_u32 s98, s98, 0x10000
	s_addc_u32 s99, s99, 0
	s_add_u32 s100, s100, 0x10000
	s_addc_u32 s101, s101, 0
	s_branch .LBB0_1468
.LBB0_1471:
	v_mov_b32_e32 v238, v193
	s_nop 1
	v_permlane32_swap_b32_e32 v193, v238
	v_add_f32_e32 v193, v193, v238
	ds_read_b128 v[82:85], v196 offset:58880
	ds_read_b128 v[86:89], v196 offset:50176
	ds_read_b128 v[146:149], v196 offset:50208
	v_exp_f32_e32 v67, v67
	v_exp_f32_e32 v69, v69
	s_waitcnt lgkmcnt(1)
	v_mfma_f32_32x32x16_bf16 v[98:113], v[86:89], v[142:145], 0
	v_mfma_f32_32x32x16_bf16 v[82:97], v[82:85], v[142:145], 0
	ds_read_b128 v[142:145], v196 offset:58912
	s_waitcnt lgkmcnt(1)
	v_mfma_f32_32x32x16_bf16 v[98:113], v[146:149], v[138:141], v[98:113]
	s_waitcnt lgkmcnt(0)
	v_mfma_f32_32x32x16_bf16 v[82:97], v[142:145], v[138:141], v[82:97]
	ds_read_b128 v[138:141], v196 offset:50240
	ds_read_b128 v[142:145], v196 offset:58944
	s_waitcnt lgkmcnt(1)
	v_mfma_f32_32x32x16_bf16 v[98:113], v[138:141], v[134:137], v[98:113]
	s_waitcnt lgkmcnt(0)
	v_mfma_f32_32x32x16_bf16 v[82:97], v[142:145], v[134:137], v[82:97]
	ds_read_b128 v[134:137], v196 offset:50272
	ds_read_b128 v[138:141], v196 offset:58976
	s_waitcnt lgkmcnt(1)
	v_mfma_f32_32x32x16_bf16 v[98:113], v[134:137], v[130:133], v[98:113]
	s_waitcnt lgkmcnt(0)
	v_mfma_f32_32x32x16_bf16 v[82:97], v[138:141], v[130:133], v[82:97]
	ds_read_b128 v[130:133], v196 offset:50304
	ds_read_b128 v[134:137], v196 offset:59008
	s_waitcnt lgkmcnt(1)
	v_mfma_f32_32x32x16_bf16 v[98:113], v[130:133], v[126:129], v[98:113]
	s_waitcnt lgkmcnt(0)
	v_mfma_f32_32x32x16_bf16 v[82:97], v[134:137], v[126:129], v[82:97]
	ds_read_b128 v[126:129], v196 offset:50336
	ds_read_b128 v[130:133], v196 offset:59040
	s_waitcnt lgkmcnt(1)
	v_mfma_f32_32x32x16_bf16 v[98:113], v[126:129], v[122:125], v[98:113]
	s_waitcnt lgkmcnt(0)
	v_mfma_f32_32x32x16_bf16 v[82:97], v[130:133], v[122:125], v[82:97]
	ds_read_b128 v[122:125], v196 offset:50368
	ds_read_b128 v[126:129], v196 offset:59072
	s_waitcnt lgkmcnt(1)
	v_mfma_f32_32x32x16_bf16 v[98:113], v[122:125], v[118:121], v[98:113]
	s_waitcnt lgkmcnt(0)
	v_mfma_f32_32x32x16_bf16 v[82:97], v[126:129], v[118:121], v[82:97]
	ds_read_b128 v[118:121], v196 offset:50400
	ds_read_b128 v[122:125], v196 offset:59104
	v_exp_f32_e32 v126, v80
	v_exp_f32_e32 v127, v81
	s_waitcnt lgkmcnt(1)
	v_mfma_f32_32x32x16_bf16 v[98:113], v[118:121], v[114:117], v[98:113]
	v_exp_f32_e32 v118, v72
	v_exp_f32_e32 v119, v73
	v_exp_f32_e32 v120, v74
	v_exp_f32_e32 v121, v75
	s_waitcnt lgkmcnt(0)
; #define SBAR() __builtin_amdgcn_sched_barrier(0)
; #define PVD0(...) do { if constexpr (PV_PIPE != 0) pv_d0_pipe(__VA_ARGS__); else pv_d0(__VA_ARGS__); } while (0)
; #define RESC(a) do { if constexpr (!NOMAX) if (__any((a) < 1.f)) { if (hi == 0) al_l[r32] = (a); asm volatile("s_waitcnt lgkmcnt(0)" ::: "memory"); \
;     _Pragma("unroll") for (int d = 0; d < 4; ++d) _Pragma("unroll") for (int r = 0; r < 16; ++r) o[d][r] *= al_l[crow(r, hi)]; } } while (0)
; #define RESC(a) do { if (__any((a) < 1.f)) { if (hi == 0) al_l[r32] = (a); asm volatile("s_waitcnt lgkmcnt(0)" ::: "memory"); \
;     _Pragma("unroll") for (int d = 0; d < 4; ++d) _Pragma("unroll") for (int r = 0; r < 16; ++r) o[d][r] *= al_l[crow(r, hi)]; } } while (0)
; template <int DQK, int SDEPTH, int QL, bool NOMAX, int ldq, int ldk, int ldv, int ldo> ...
;     ...
;     SBAR(); qkt<DQK, QL>(pB0, pB1, K_lds + SHM_K, qr, qpark, r32, hi);
;     finishSM(pA0, pA1, alA, l_reg, pa0, pa1, pa2, pa3); SBAR();
;     PVD0(o, vb0, pa0, pa1, pa2, pa3); if constexpr (NOMAX) { partialSM_nm(pB0); alB = 1.f; } else partialSM(pB0, pB1, m_reg, mnB, alB, C, thr_raw);
;     __syncthreads(); RESC(alB);
;     finishSM(pB0, pB1, alB, l_reg, pa0, pa1, pa2, pa3); SBAR();
	v_mfma_f32_32x32x16_bf16 v[82:97], v[122:125], v[114:117], v[82:97]
	v_exp_f32_e32 v114, v66
	v_add_f32_e32 v66, 0, v206
	v_add_f32_e32 v66, v209, v66
	v_add_f32_e32 v66, v204, v66
	v_add_f32_e32 v66, v207, v66
	v_add_f32_e32 v66, v203, v66
	v_add_f32_e32 v66, v205, v66
	v_add_f32_e32 v66, v208, v66
	v_add_f32_e32 v66, v216, v66
	v_add_f32_e32 v66, v189, v66
	v_add_f32_e32 v66, v202, v66
	v_add_f32_e32 v66, v187, v66
	v_add_f32_e32 v66, v201, v66
	v_add_f32_e32 v66, v184, v66
	v_add_f32_e32 v66, v188, v66
	v_exp_f32_e32 v115, v68
	v_add_f32_e32 v66, v185, v66
	v_add_f32_e32 v66, v186, v66
	v_exp_f32_e32 v116, v70
	v_add_f32_e32 v66, v114, v66
	v_exp_f32_e32 v117, v71
	v_add_f32_e32 v66, v67, v66
	v_add_f32_e32 v66, v115, v66
	v_add_f32_e32 v66, v69, v66
	v_add_f32_e32 v66, v116, v66
	v_add_f32_e32 v66, v117, v66
	v_exp_f32_e32 v122, v76
	v_add_f32_e32 v66, v118, v66
	v_exp_f32_e32 v123, v77
	v_add_f32_e32 v66, v119, v66
	v_exp_f32_e32 v124, v78
	v_add_f32_e32 v66, v120, v66
	v_exp_f32_e32 v125, v79
	v_add_f32_e32 v66, v121, v66
	v_add_f32_e32 v66, v122, v66
	v_add_f32_e32 v66, v123, v66
	v_add_f32_e32 v66, v124, v66
	v_add_f32_e32 v66, v125, v66
	v_add_f32_e32 v66, v126, v66
	v_add_f32_e32 v66, v127, v66
	v_mov_b32_e32 v68, v66
	s_nop 1
	v_permlane32_swap_b32_e32 v66, v68
	v_cvt_pk_bf16_f32 v70, v206, v209
	v_cvt_pk_bf16_f32 v71, v204, v207
	v_cvt_pk_bf16_f32 v72, v203, v205
	v_cvt_pk_bf16_f32 v73, v208, v216
	v_cvt_pk_bf16_f32 v74, v189, v202
	v_cvt_pk_bf16_f32 v75, v187, v201
	v_cvt_pk_bf16_f32 v76, v184, v188
	v_cvt_pk_bf16_f32 v77, v185, v186
	v_cvt_pk_bf16_f32 v78, v114, v67
	v_cvt_pk_bf16_f32 v79, v115, v69
	v_cvt_pk_bf16_f32 v80, v116, v117
	v_cvt_pk_bf16_f32 v81, v118, v119
	v_cvt_pk_bf16_f32 v114, v120, v121
	v_cvt_pk_bf16_f32 v115, v122, v123
	v_cvt_pk_bf16_f32 v116, v124, v125
	v_cvt_pk_bf16_f32 v117, v126, v127
	s_nop 0
	v_permlane32_swap_b32_e32 v70, v72
	v_permlane32_swap_b32_e32 v71, v73
	v_permlane32_swap_b32_e32 v74, v76
	v_permlane32_swap_b32_e32 v75, v77
	v_permlane32_swap_b32_e32 v78, v80
	v_permlane32_swap_b32_e32 v79, v81
	v_permlane32_swap_b32_e32 v114, v116
	v_permlane32_swap_b32_e32 v115, v117
	ds_read_b64_tr_b16 v[118:119], v195 offset:0
	ds_read_b64_tr_b16 v[120:121], v195 offset:0x800
	ds_read_b64_tr_b16 v[122:123], v195 offset:0x1000
	ds_read_b64_tr_b16 v[124:125], v195 offset:0x1800
	ds_read_b64_tr_b16 v[126:127], v195 offset:0x2000
	ds_read_b64_tr_b16 v[128:129], v195 offset:0x2800
	ds_read_b64_tr_b16 v[130:131], v195 offset:0x3000
	ds_read_b64_tr_b16 v[132:133], v195 offset:0x3800
	s_waitcnt lgkmcnt(0)
	s_nop 0
	v_mfma_f32_32x32x16_bf16 v[50:65], v[70:73], v[118:121], v[50:65]
	ds_read_b64_tr_b16 v[118:119], v195 offset:0x200
	ds_read_b64_tr_b16 v[120:121], v195 offset:0xa00
	v_mfma_f32_32x32x16_bf16 v[50:65], v[74:77], v[122:125], v[50:65]
	ds_read_b64_tr_b16 v[122:123], v195 offset:0x1200
	ds_read_b64_tr_b16 v[124:125], v195 offset:0x1a00
	v_mfma_f32_32x32x16_bf16 v[50:65], v[78:81], v[126:129], v[50:65]
	ds_read_b64_tr_b16 v[126:127], v195 offset:0x2200
	ds_read_b64_tr_b16 v[128:129], v195 offset:0x2a00
	v_mfma_f32_32x32x16_bf16 v[50:65], v[114:117], v[130:133], v[50:65]
	ds_read_b64_tr_b16 v[130:131], v195 offset:0x3200
	ds_read_b64_tr_b16 v[132:133], v195 offset:0x3a00
	s_waitcnt lgkmcnt(0)
	v_mfma_f32_32x32x16_bf16 v[34:49], v[70:73], v[118:121], v[34:49]
	ds_read_b64_tr_b16 v[118:119], v195 offset:0x400
	ds_read_b64_tr_b16 v[120:121], v195 offset:0xc00
	v_mfma_f32_32x32x16_bf16 v[34:49], v[74:77], v[122:125], v[34:49]
	ds_read_b64_tr_b16 v[122:123], v195 offset:0x1400
	ds_read_b64_tr_b16 v[124:125], v195 offset:0x1c00
	v_mfma_f32_32x32x16_bf16 v[34:49], v[78:81], v[126:129], v[34:49]
	ds_read_b64_tr_b16 v[126:127], v195 offset:0x2400
	ds_read_b64_tr_b16 v[128:129], v195 offset:0x2c00
	v_mfma_f32_32x32x16_bf16 v[34:49], v[114:117], v[130:133], v[34:49]
	ds_read_b64_tr_b16 v[130:131], v195 offset:0x3400
	ds_read_b64_tr_b16 v[132:133], v195 offset:0x3c00
	s_waitcnt lgkmcnt(0)
	v_mfma_f32_32x32x16_bf16 v[16:31], v[70:73], v[118:121], v[16:31]
	ds_read_b64_tr_b16 v[118:119], v195 offset:0x600
	ds_read_b64_tr_b16 v[120:121], v195 offset:0xe00
	v_mfma_f32_32x32x16_bf16 v[16:31], v[74:77], v[122:125], v[16:31]
	ds_read_b64_tr_b16 v[122:123], v195 offset:0x1600
	ds_read_b64_tr_b16 v[124:125], v195 offset:0x1e00
	v_mfma_f32_32x32x16_bf16 v[16:31], v[78:81], v[126:129], v[16:31]
	ds_read_b64_tr_b16 v[126:127], v195 offset:0x2600
	ds_read_b64_tr_b16 v[128:129], v195 offset:0x2e00
	v_mfma_f32_32x32x16_bf16 v[16:31], v[114:117], v[130:133], v[16:31]
	ds_read_b64_tr_b16 v[130:131], v195 offset:0x3600
	ds_read_b64_tr_b16 v[132:133], v195 offset:0x3e00
	s_waitcnt lgkmcnt(0)
	v_mfma_f32_32x32x16_bf16 v[0:15], v[70:73], v[118:121], v[0:15]
	v_exp_f32_e32 v70, v98
	v_exp_f32_e32 v71, v99
	v_exp_f32_e32 v72, v100
	v_exp_f32_e32 v73, v101
	v_add_f32_e32 v67, 0, v70
	v_add_f32_e32 v67, v71, v67
	v_add_f32_e32 v67, v72, v67
	v_mfma_f32_32x32x16_bf16 v[0:15], v[74:77], v[122:125], v[0:15]
	v_exp_f32_e32 v74, v102
	v_exp_f32_e32 v75, v103
	v_exp_f32_e32 v76, v104
	v_exp_f32_e32 v77, v105
	v_add_f32_e32 v67, v73, v67
	v_add_f32_e32 v67, v74, v67
	v_add_f32_e32 v67, v75, v67
	v_mfma_f32_32x32x16_bf16 v[0:15], v[78:81], v[126:129], v[0:15]
	v_exp_f32_e32 v78, v106
	v_exp_f32_e32 v79, v107
	v_exp_f32_e32 v80, v108
	v_add_f32_e32 v67, v76, v67
	v_exp_f32_e32 v81, v109
	v_add_f32_e32 v67, v77, v67
	v_exp_f32_e32 v98, v110
	v_add_f32_e32 v67, v78, v67
	v_exp_f32_e32 v99, v111
	v_add_f32_e32 v67, v79, v67
	v_exp_f32_e32 v100, v112
	v_add_f32_e32 v67, v80, v67
	v_exp_f32_e32 v101, v113
	v_add_f32_e32 v67, v81, v67
	v_exp_f32_e32 v82, v82
	v_add_f32_e32 v67, v98, v67
	v_exp_f32_e32 v83, v83
	v_add_f32_e32 v67, v99, v67
	v_exp_f32_e32 v84, v84
	v_add_f32_e32 v67, v100, v67
	v_exp_f32_e32 v85, v85
	v_add_f32_e32 v67, v101, v67
	v_exp_f32_e32 v86, v86
	v_add_f32_e32 v67, v82, v67
	v_exp_f32_e32 v87, v87
	v_add_f32_e32 v67, v83, v67
	v_exp_f32_e32 v88, v88
	v_add_f32_e32 v67, v84, v67
	v_exp_f32_e32 v89, v89
	v_add_f32_e32 v67, v85, v67
	v_exp_f32_e32 v90, v90
	v_add_f32_e32 v67, v86, v67
	v_exp_f32_e32 v91, v91
	v_add_f32_e32 v67, v87, v67
	v_exp_f32_e32 v92, v92
	v_add_f32_e32 v67, v88, v67
	v_exp_f32_e32 v93, v93
	v_add_f32_e32 v67, v89, v67
	v_exp_f32_e32 v94, v94
	v_add_f32_e32 v67, v90, v67
	v_exp_f32_e32 v95, v95
	v_add_f32_e32 v67, v91, v67
	v_mfma_f32_32x32x16_bf16 v[0:15], v[114:117], v[130:133], v[0:15]
	v_exp_f32_e32 v96, v96
	v_add_f32_e32 v67, v92, v67
	v_exp_f32_e32 v97, v97
	v_add_f32_e32 v67, v93, v67
	v_add_f32_e32 v67, v94, v67
	v_add_f32_e32 v67, v95, v67
	v_add_f32_e32 v67, v96, v67
	v_add_f32_e32 v67, v97, v67
	v_mov_b32_e32 v69, v67
	s_barrier
; template <int M> __device__ __forceinline__ float swz_xor(float v) { return __int_as_float(__builtin_amdgcn_ds_swizzle(__float_as_int(v), (M << 10) | 0x1f)); }
; #define SBAR() __builtin_amdgcn_sched_barrier(0)
; __device__ __forceinline__ int crow(int r, int hi) { return (r & 3) + 8 * (r >> 2) + 4 * hi; }
; __device__ __forceinline__ unsigned cvtpk(float lo, float hi) { unsigned r; asm volatile("v_cvt_pk_bf16_f32 %0, %1, %2" : "=v"(r) : "v"(lo), "v"(hi)); return r; }
; #define PVD0(...) do { if constexpr (PV_PIPE != 0) pv_d0_pipe(__VA_ARGS__); else pv_d0(__VA_ARGS__); } while (0)
; template <int DQK, int SDEPTH, int QL, bool NOMAX, int ldq, int ldk, int ldv, int ldo> ...
;     ...
;     finishSM(pB0, pB1, alB, l_reg, pa0, pa1, pa2, pa3); SBAR();
;     PVD0(o, vb0 + SHM_V, pa0, pa1, pa2, pa3);
;     if (ATT_PRIO) __builtin_amdgcn_s_setprio(0);
;     if (hi == 0) li_l[r32] = l_reg; asm volatile("s_waitcnt lgkmcnt(0)" ::: "memory");
;     float rli[16];
; #pragma unroll
;     for (int r = 0; r < 16; ++r) rli[r] = __builtin_amdgcn_rcpf(li_l[crow(r, hi)]);
;     bf16_t* Ow = Ob + (size_t)(wid * QBLK) * ldo + (r32 & ~1);
;     const bool odd = (r32 & 1) != 0;
; #pragma unroll
;     for (int r = 0; r < 16; r += 2) { const int orow = crow(r, hi) + (odd ? 1 : 0);
; #pragma unroll
;         for (int d0 = 0; d0 < 4; ++d0) { const float a = o[d0][r] * rli[r], b = o[d0][r + 1] * rli[r + 1];
;             const float recv = swz_xor<1>(odd ? a : b);
;             const unsigned w = odd ? cvtpk(recv, b) : cvtpk(a, recv);
;             *(unsigned*)(Ow + (size_t)orow * ldo + d0 * 32) = w; } }
	s_nop 0
	v_permlane32_swap_b32_e32 v67, v69
	v_cvt_pk_bf16_f32 v70, v70, v71
	v_cvt_pk_bf16_f32 v71, v72, v73
	v_cvt_pk_bf16_f32 v72, v74, v75
	v_cvt_pk_bf16_f32 v73, v76, v77
	v_cvt_pk_bf16_f32 v74, v78, v79
	v_cvt_pk_bf16_f32 v75, v80, v81
	v_cvt_pk_bf16_f32 v76, v98, v99
	v_cvt_pk_bf16_f32 v77, v100, v101
	v_cvt_pk_bf16_f32 v78, v82, v83
	v_cvt_pk_bf16_f32 v79, v84, v85
	v_cvt_pk_bf16_f32 v80, v86, v87
	v_cvt_pk_bf16_f32 v81, v88, v89
	v_cvt_pk_bf16_f32 v82, v90, v91
	v_cvt_pk_bf16_f32 v83, v92, v93
	v_cvt_pk_bf16_f32 v84, v94, v95
	v_cvt_pk_bf16_f32 v85, v96, v97
	s_nop 0
	v_permlane32_swap_b32_e32 v70, v72
	v_permlane32_swap_b32_e32 v71, v73
	v_permlane32_swap_b32_e32 v74, v76
	v_permlane32_swap_b32_e32 v75, v77
	v_permlane32_swap_b32_e32 v78, v80
	v_permlane32_swap_b32_e32 v79, v81
	v_permlane32_swap_b32_e32 v82, v84
	v_permlane32_swap_b32_e32 v83, v85
	ds_read_b64_tr_b16 v[86:87], v194 offset:0
	ds_read_b64_tr_b16 v[88:89], v194 offset:0x800
	ds_read_b64_tr_b16 v[90:91], v194 offset:0x1000
	ds_read_b64_tr_b16 v[92:93], v194 offset:0x1800
	ds_read_b64_tr_b16 v[94:95], v194 offset:0x2000
	ds_read_b64_tr_b16 v[96:97], v194 offset:0x2800
	ds_read_b64_tr_b16 v[98:99], v194 offset:0x3000
	ds_read_b64_tr_b16 v[100:101], v194 offset:0x3800
	s_waitcnt lgkmcnt(0)
	s_nop 0
	v_mfma_f32_32x32x16_bf16 v[50:65], v[70:73], v[86:89], v[50:65]
	ds_read_b64_tr_b16 v[86:87], v194 offset:0x200
	ds_read_b64_tr_b16 v[88:89], v194 offset:0xa00
	v_mfma_f32_32x32x16_bf16 v[50:65], v[74:77], v[90:93], v[50:65]
	ds_read_b64_tr_b16 v[90:91], v194 offset:0x1200
	ds_read_b64_tr_b16 v[92:93], v194 offset:0x1a00
	v_mfma_f32_32x32x16_bf16 v[50:65], v[78:81], v[94:97], v[50:65]
	ds_read_b64_tr_b16 v[94:95], v194 offset:0x2200
	ds_read_b64_tr_b16 v[96:97], v194 offset:0x2a00
	v_mfma_f32_32x32x16_bf16 v[50:65], v[82:85], v[98:101], v[50:65]
	ds_read_b64_tr_b16 v[98:99], v194 offset:0x3200
	ds_read_b64_tr_b16 v[100:101], v194 offset:0x3a00
	s_waitcnt lgkmcnt(0)
	v_mfma_f32_32x32x16_bf16 v[34:49], v[70:73], v[86:89], v[34:49]
	ds_read_b64_tr_b16 v[86:87], v194 offset:0x400
	ds_read_b64_tr_b16 v[88:89], v194 offset:0xc00
	v_mfma_f32_32x32x16_bf16 v[34:49], v[74:77], v[90:93], v[34:49]
	ds_read_b64_tr_b16 v[90:91], v194 offset:0x1400
	ds_read_b64_tr_b16 v[92:93], v194 offset:0x1c00
	v_mfma_f32_32x32x16_bf16 v[34:49], v[78:81], v[94:97], v[34:49]
	ds_read_b64_tr_b16 v[94:95], v194 offset:0x2400
	ds_read_b64_tr_b16 v[96:97], v194 offset:0x2c00
	v_mfma_f32_32x32x16_bf16 v[34:49], v[82:85], v[98:101], v[34:49]
	ds_read_b64_tr_b16 v[98:99], v194 offset:0x3400
	ds_read_b64_tr_b16 v[100:101], v194 offset:0x3c00
	s_waitcnt lgkmcnt(0)
	v_mfma_f32_32x32x16_bf16 v[16:31], v[70:73], v[86:89], v[16:31]
	ds_read_b64_tr_b16 v[86:87], v194 offset:0x600
	ds_read_b64_tr_b16 v[88:89], v194 offset:0xe00
	v_mfma_f32_32x32x16_bf16 v[16:31], v[74:77], v[90:93], v[16:31]
	ds_read_b64_tr_b16 v[90:91], v194 offset:0x1600
	ds_read_b64_tr_b16 v[92:93], v194 offset:0x1e00
	v_mfma_f32_32x32x16_bf16 v[16:31], v[78:81], v[94:97], v[16:31]
	ds_read_b64_tr_b16 v[94:95], v194 offset:0x2600
	ds_read_b64_tr_b16 v[96:97], v194 offset:0x2e00
	v_mfma_f32_32x32x16_bf16 v[16:31], v[82:85], v[98:101], v[16:31]
	ds_read_b64_tr_b16 v[98:99], v194 offset:0x3600
	ds_read_b64_tr_b16 v[100:101], v194 offset:0x3e00
	s_waitcnt lgkmcnt(0)
	v_mfma_f32_32x32x16_bf16 v[0:15], v[70:73], v[86:89], v[0:15]
	v_mfma_f32_32x32x16_bf16 v[0:15], v[74:77], v[90:93], v[0:15]
	v_mfma_f32_32x32x16_bf16 v[0:15], v[78:81], v[94:97], v[0:15]
	v_mfma_f32_32x32x16_bf16 v[0:15], v[82:85], v[98:101], v[0:15]
	s_setprio 0
	v_cmp_gt_u32_e32 vcc, 32, v32
	s_and_saveexec_b64 s[6:7], vcc
	v_pk_add_f32 v[66:67], v[66:67], v[68:69]
	v_lshl_add_u32 v32, v192, 2, s49
	v_add_f32_e32 v66, v193, v66
	v_add_f32_e32 v66, v66, v67
	ds_write_b32 v32, v66
	s_or_b64 exec, exec, s[6:7]
	s_waitcnt lgkmcnt(0)
	v_lshl_add_u32 v32, v191, 4, s49
	ds_read_b128 v[78:81], v32
	ds_read_b128 v[74:77], v32 offset:32
	v_and_b32_e32 v82, 1, v190
	ds_read_b128 v[70:73], v32 offset:64
	ds_read_b128 v[66:69], v32 offset:96
	v_cmp_eq_u32_e64 s[8:9], 0, v82
	s_waitcnt lgkmcnt(3)
	v_rcp_f32_e32 v78, v78
	v_rcp_f32_e32 v79, v79
	v_cmp_eq_u32_e64 s[6:7], 1, v82
	v_mul_f32_e32 v32, v50, v78
	v_mul_f32_e32 v51, v51, v79
	v_cndmask_b32_e64 v50, v32, v51, s[8:9]
	ds_swizzle_b32 v50, v50 offset:swizzle(SWAP,1)
	s_and_saveexec_b64 s[14:15], s[6:7]
	s_xor_b64 s[14:15], exec, s[14:15]
	s_cbranch_execz .LBB0_1475
	s_waitcnt lgkmcnt(0)
	v_cvt_pk_bf16_f32 v83, v50, v51

; __device__ __forceinline__ int v_st(int k, int c) { const int kk = (k & ~0xC) | ((k & 4) << 1) | ((k & 8) >> 1); return ((kk >> 3) * 4 + (c >> 5)) * 512 + ((kk & 7) * 32 + (c & 31)) * 2; }
; __device__ __forceinline__ int v_rd_base(int lane) { return ((lane & 3) << 3) | (((lane >> 2) & 3) << 6) | (((lane >> 4) & 1) << 5) | (((lane >> 5) & 1) << 8); }
; #define SLOAD(i, k0) do { sv0[i] = *reinterpret_cast<const bf16x8*>(&Vh[(size_t)((k0) + sr) * ldv + sc]); sv1[i] = *reinterpret_cast<const bf16x8*>(&Vh[(size_t)((k0) + 32 + sr) * ldv + sc]); \
;     _Pragma("unroll") for (int _q = 0; _q < NKP; ++_q) sk[i][_q] = *reinterpret_cast<const bf16x8*>(&Kh[(size_t)(k0) * ldk + koff[_q]]); } while (0)
; #define SWRITE(b, i) do { *(bf16x8*)(V_lds + (b) * SHM_V + vst0) = sv0[i]; *(bf16x8*)(V_lds + (b) * SHM_V + vst1) = sv1[i]; \
;     _Pragma("unroll") for (int _q = 0; _q < NKP; ++_q) *(bf16x8*)(K_lds + (b) * SHM_K + klds[_q]) = sk[i][_q]; } while (0)
; #define SLOAD(k0) do { sv0 = *reinterpret_cast<const bf16x8*>(&Vh[(size_t)((k0) + sr) * ldv + sc]); sv1 = *reinterpret_cast<const bf16x8*>(&Vh[(size_t)((k0) + 32 + sr) * ldv + sc]); \
;     _Pragma("unroll") for (int _q = 0; _q < NKP; ++_q) sk[_q] = *reinterpret_cast<const bf16x8*>(&Kh[(size_t)(k0) * ldk + koff[_q]]); } while (0)
; template <int DQK, int SDEPTH, int QL, bool NOMAX, int ldq, int ldk, int ldv, int ldo> ...
;     ...
;     const int sr = tid >> 4, sc = (tid & 15) * 8, vst0 = v_st(sr, sc), vst1 = v_st(32 + sr, sc);
;     int koff[NKP], klds[NKP];
; #pragma unroll
;     for (int i = 0; i < NKP; ++i) { const int row = tid >> 3, c8 = (tid & 7) + 8 * i; koff[i] = row * ldk + c8 * 8; klds[i] = row * RS + c8 * 16; }
;     const int vb0 = (int)(uintptr_t)V_lds + v_rd_base(lane);
;     bf16x8 sv0[SDEPTH], sv1[SDEPTH], sk[SDEPTH][NKP];
;     ...
;     f32x16 pA0, pA1, pB0, pB1; float mnA, mnB, alA, alB; bf16x8 pa0, pa1, pa2, pa3; const int NT = seq / KVBLK;
;     if (ATT_PRIO && wid >= 4) __builtin_amdgcn_s_setprio(1);
;     constexpr int SE = 0, SO = SDEPTH - 1;
;     SLOAD(SE, 0); asm volatile("s_waitcnt vmcnt(0)" ::: "memory"); SWRITE(0, SE); __syncthreads();
;     qkt<DQK, QL>(pA0, pA1, K_lds, qr, qpark, r32, hi); if constexpr (NOMAX) { partialSM_nm(pA0); alA = 1.f; } else partialSM(pA0, pA1, m_reg, mnA, alA, C, thr_raw);
;     SLOAD(SO, KVBLK); if constexpr (SDEPTH == 2) { if (2 < NT) SLOAD(SE, 2 * KVBLK); }
.LBB0_2011:
	v_add_u32_e32 v0, s39, v232
	v_ashrrev_i32_e32 v28, 4, v0
	v_lshlrev_b32_e32 v34, 3, v232
	v_ashrrev_i32_e32 v35, 3, v0
	v_and_b32_e32 v36, 7, v232
	s_movk_i32 s4, 0x600
	v_ashrrev_i32_e32 v29, 31, v28
	v_and_b32_e32 v2, 0x78, v34
	v_add_u32_e32 v30, 32, v28
	v_mul_lo_u32 v0, v35, s4
	v_or_b32_e32 v37, 8, v36
	v_or_b32_e32 v46, 16, v36
	v_lshlrev_b64 v[16:17], 11, v[28:29]
	v_lshl_or_b32 v8, v36, 3, v0
	v_lshl_or_b32 v10, v37, 3, v0
	v_lshl_or_b32 v22, v46, 3, v0
	v_lshl_add_u64 v[0:1], s[26:27], 0, v[16:17]
	v_lshlrev_b32_e32 v2, 1, v2
	v_mov_b32_e32 v3, v33
	v_ashrrev_i32_e32 v31, 31, v30
	v_lshl_add_u64 v[38:39], v[0:1], 0, v[2:3]
	v_lshlrev_b64 v[0:1], 11, v[30:31]
	v_ashrrev_i32_e32 v9, 31, v8
	v_lshl_add_u64 v[0:1], s[26:27], 0, v[0:1]
	v_lshlrev_b64 v[18:19], 1, v[8:9]
	v_ashrrev_i32_e32 v11, 31, v10
	v_lshl_add_u64 v[4:5], v[0:1], 0, v[2:3]
	v_lshl_add_u64 v[40:41], s[24:25], 0, v[18:19]
	v_lshlrev_b64 v[20:21], 1, v[10:11]
	global_load_dwordx4 v[0:3], v[38:39], off
	s_nop 0
	global_load_dwordx4 v[4:7], v[4:5], off
	v_lshl_add_u64 v[42:43], s[24:25], 0, v[20:21]
	global_load_dwordx4 v[8:11], v[40:41], off
	global_load_dwordx4 v[12:15], v[42:43], off
	v_ashrrev_i32_e32 v23, 31, v22
	v_lshlrev_b64 v[22:23], 1, v[22:23]
	v_lshl_add_u64 v[44:45], s[24:25], 0, v[22:23]
	global_load_dwordx4 v[24:27], v[44:45], off
	v_bfe_u32 v31, v34, 5, 2
	v_and_b32_e32 v34, 0xfffff0, v28
	v_lshlrev_b32_e32 v47, 1, v28
	v_and_or_b32 v34, v47, 8, v34
	v_and_b32_e32 v47, 0xfffff0, v30
	v_lshlrev_b32_e32 v30, 1, v30
	v_lshrrev_b32_e32 v48, 1, v28
	v_and_b32_e32 v28, 3, v28
	v_lshrrev_b32_e32 v34, 1, v34
	v_and_or_b32 v30, v30, 8, v47
	v_lshlrev_b32_e32 v29, 4, v232
	v_and_or_b32 v28, v48, 4, v28
	v_or_b32_e32 v34, v34, v31
	v_lshrrev_b32_e32 v30, 1, v30
	s_movk_i32 s4, 0x190
	v_and_b32_e32 v29, 48, v29
	v_lshlrev_b32_e32 v28, 6, v28
	v_lshlrev_b32_e32 v34, 9, v34
	v_or_b32_e32 v30, v30, v31
	v_mad_u32_u24 v58, v240, s4, 0
	v_mul_lo_u32 v35, v35, s4
	v_lshlrev_b32_e32 v30, 9, v30
	v_or3_b32 v31, v34, v28, v29
	v_add_u32_e32 v245, v58, v32
	v_lshl_add_u32 v36, v36, 4, v35
	v_lshl_add_u32 v37, v37, 4, v35
	v_lshl_add_u32 v35, v46, 4, v35
	v_or3_b32 v28, v30, v28, v29
	v_add_u32_e32 v249, 0, v31
	v_add_u32_e32 v246, 0, v36
	v_add_u32_e32 v247, 0, v37
	v_add_u32_e32 v248, 0, v35
	s_waitcnt vmcnt(0)
	v_add_u32_e32 v250, 0, v28
	v_add_co_u32_e32 v46, vcc, s66, v38
	s_mov_b32 s4, 0x30000
	s_nop 0
	v_addc_co_u32_e32 v47, vcc, 0, v39, vcc
	v_add_co_u32_e32 v38, vcc, s4, v38
	v_and_b32_e32 v241, 63, v232
	s_nop 0
	v_addc_co_u32_e32 v39, vcc, 0, v39, vcc
	v_add_co_u32_e32 v48, vcc, s4, v40
	v_lshlrev_b32_e32 v59, 4, v241
	s_nop 0
	v_addc_co_u32_e32 v49, vcc, 0, v41, vcc
	v_add_co_u32_e32 v50, vcc, s4, v42
	v_lshlrev_b32_e32 v60, 3, v241
	s_waitcnt vmcnt(4)
	ds_write_b128 v249, v[0:3]
	s_waitcnt vmcnt(3)
	ds_write_b128 v250, v[4:7]
	s_waitcnt vmcnt(2)
	ds_write_b128 v246, v[8:11] offset:32768
	s_waitcnt vmcnt(1)
	ds_write_b128 v247, v[12:15] offset:32768
	s_waitcnt vmcnt(0)
	ds_write_b128 v248, v[24:27] offset:32768
	s_waitcnt lgkmcnt(0)
	s_barrier
	ds_read_b128 v[0:3], v245 offset:32768
	ds_read_b128 v[24:27], v245 offset:32800
	s_waitcnt lgkmcnt(1)
	v_mfma_f32_32x32x16_bf16 v[0:15], v[0:3], v[158:161], 0
	ds_read_b128 v[28:31], v245 offset:45568
	ds_read_b128 v[34:37], v245 offset:45600
	v_addc_co_u32_e32 v51, vcc, 0, v43, vcc
	v_add_co_u32_e32 v52, vcc, s4, v44
	v_lshlrev_b32_e32 v61, 1, v241
	s_nop 0
	v_addc_co_u32_e32 v53, vcc, 0, v45, vcc
	s_waitcnt lgkmcnt(1)
	v_mfma_f32_32x32x16_bf16 v[66:81], v[28:31], v[158:161], 0
	s_cmp_lg_u32 0, -1
	s_cselect_b32 s6, 0, 0
	s_add_i32 s7, s6, 0x4000
	s_add_u32 s4, s54, s55
	s_addc_u32 s5, s52, s53
	v_lshl_add_u64 v[216:217], s[4:5], 0, v[18:19]
	v_lshl_add_u64 v[218:219], s[4:5], 0, v[20:21]
	v_mfma_f32_32x32x16_bf16 v[0:15], v[24:27], v[154:157], v[0:15]
	ds_read_b128 v[24:27], v245 offset:32832
	ds_read_b128 v[28:31], v245 offset:32864
	v_lshl_add_u64 v[220:221], s[4:5], 0, v[22:23]
	s_lshl_b64 s[4:5], s[22:23], 11
	v_add_u32_e32 v58, 0xe400, v58
	v_mov_b32_e32 v243, 0
	v_add_u32_e32 v32, v58, v32
	v_mov_b32_e32 v58, v243
	s_waitcnt lgkmcnt(2)
	v_mfma_f32_32x32x16_bf16 v[66:81], v[34:37], v[154:157], v[66:81]
	v_mov_b32_e32 v62, v243
	v_mov_b32_e32 v63, v243
	v_mov_b32_e32 v64, v243
	v_mov_b32_e32 v65, v243
	v_mov_b32_e32 v18, v243
	v_mov_b32_e32 v19, v243
	v_mov_b32_e32 v20, v243
	s_waitcnt lgkmcnt(1)
	v_mfma_f32_32x32x16_bf16 v[0:15], v[24:27], v[150:153], v[0:15]
	ds_read_b128 v[24:27], v245 offset:45632
	ds_read_b128 v[34:37], v245 offset:45664
	v_mov_b32_e32 v21, v243
	v_mov_b32_e32 v22, v243
	v_mov_b32_e32 v23, v243
	s_mov_b64 s[14:15], 0x40000
	s_waitcnt lgkmcnt(1)
	v_mfma_f32_32x32x16_bf16 v[66:81], v[24:27], v[150:153], v[66:81]
	v_mfma_f32_32x32x16_bf16 v[0:15], v[28:31], v[146:149], v[0:15]
	ds_read_b128 v[24:27], v245 offset:32896
	ds_read_b128 v[28:31], v245 offset:32928
	s_waitcnt lgkmcnt(2)
	v_mfma_f32_32x32x16_bf16 v[66:81], v[34:37], v[146:149], v[66:81]
	s_waitcnt lgkmcnt(1)
	v_mfma_f32_32x32x16_bf16 v[0:15], v[24:27], v[142:145], v[0:15]
	ds_read_b128 v[24:27], v245 offset:45696
	ds_read_b128 v[34:37], v245 offset:45728
	s_waitcnt lgkmcnt(1)
	v_mfma_f32_32x32x16_bf16 v[66:81], v[24:27], v[142:145], v[66:81]
	v_mfma_f32_32x32x16_bf16 v[0:15], v[28:31], v[138:141], v[0:15]
	ds_read_b128 v[24:27], v245 offset:32960
	ds_read_b128 v[28:31], v245 offset:32992
	s_waitcnt lgkmcnt(2)
	v_mfma_f32_32x32x16_bf16 v[66:81], v[34:37], v[138:141], v[66:81]
	s_waitcnt lgkmcnt(1)
	v_mfma_f32_32x32x16_bf16 v[0:15], v[24:27], v[134:137], v[0:15]
	ds_read_b128 v[24:27], v245 offset:45760
	ds_read_b128 v[34:37], v245 offset:45792
	s_waitcnt lgkmcnt(1)
; #define SLOAD(i, k0) do { sv0[i] = *reinterpret_cast<const bf16x8*>(&Vh[(size_t)((k0) + sr) * ldv + sc]); sv1[i] = *reinterpret_cast<const bf16x8*>(&Vh[(size_t)((k0) + 32 + sr) * ldv + sc]); \
;     _Pragma("unroll") for (int _q = 0; _q < NKP; ++_q) sk[i][_q] = *reinterpret_cast<const bf16x8*>(&Kh[(size_t)(k0) * ldk + koff[_q]]); } while (0)
; #define SWRITE(b, i) do { *(bf16x8*)(V_lds + (b) * SHM_V + vst0) = sv0[i]; *(bf16x8*)(V_lds + (b) * SHM_V + vst1) = sv1[i]; \
;     _Pragma("unroll") for (int _q = 0; _q < NKP; ++_q) *(bf16x8*)(K_lds + (b) * SHM_K + klds[_q]) = sk[i][_q]; } while (0)
; #define SWAIT() do { if constexpr (SDEPTH == 2) { if constexpr (NKP == 1) asm volatile("s_waitcnt vmcnt(3)" ::: "memory"); else if constexpr (NKP == 2) asm volatile("s_waitcnt vmcnt(4)" ::: "memory"); else asm volatile("s_waitcnt vmcnt(5)" ::: "memory"); } \
;     else asm volatile("s_waitcnt vmcnt(0)" ::: "memory"); } while (0)
; #define SLOAD(k0) do { sv0 = *reinterpret_cast<const bf16x8*>(&Vh[(size_t)((k0) + sr) * ldv + sc]); sv1 = *reinterpret_cast<const bf16x8*>(&Vh[(size_t)((k0) + 32 + sr) * ldv + sc]); \
;     _Pragma("unroll") for (int _q = 0; _q < NKP; ++_q) sk[_q] = *reinterpret_cast<const bf16x8*>(&Kh[(size_t)(k0) * ldk + koff[_q]]); } while (0)
; #define SWRITE(b) do { *(bf16x8*)(V_lds + (b) * SHM_V + vst0) = sv0; *(bf16x8*)(V_lds + (b) * SHM_V + vst1) = sv1; \
;     _Pragma("unroll") for (int _q = 0; _q < NKP; ++_q) *(bf16x8*)(K_lds + (b) * SHM_K + klds[_q]) = sk[_q]; } while (0)
; template <int DQK, int SDEPTH, int QL, bool NOMAX, int ldq, int ldk, int ldv, int ldo> ...
;     ...
;     SLOAD(SE, 0); asm volatile("s_waitcnt vmcnt(0)" ::: "memory"); SWRITE(0, SE); __syncthreads();
;     qkt<DQK, QL>(pA0, pA1, K_lds, qr, qpark, r32, hi); if constexpr (NOMAX) { partialSM_nm(pA0); alA = 1.f; } else partialSM(pA0, pA1, m_reg, mnA, alA, C, thr_raw);
;     SLOAD(SO, KVBLK); if constexpr (SDEPTH == 2) { if (2 < NT) SLOAD(SE, 2 * KVBLK); }
;     SWAIT(); SWRITE(1, SO); __syncthreads();
;     for (int j = 1; j + 1 < NT; j += 2) {
	v_mfma_f32_32x32x16_bf16 v[66:81], v[24:27], v[134:137], v[66:81]
	ds_read_b128 v[24:27], v245 offset:33024
	v_mfma_f32_32x32x16_bf16 v[0:15], v[28:31], v[130:133], v[0:15]
	s_waitcnt lgkmcnt(1)
	v_mfma_f32_32x32x16_bf16 v[66:81], v[34:37], v[130:133], v[66:81]
	ds_read_b128 v[28:31], v245 offset:45824
	ds_read_b128 v[34:37], v245 offset:33056
	s_waitcnt lgkmcnt(2)
	v_mfma_f32_32x32x16_bf16 v[0:15], v[24:27], v[126:129], v[0:15]
	ds_read_b128 v[24:27], v245 offset:45856
	s_waitcnt lgkmcnt(2)
	v_mfma_f32_32x32x16_bf16 v[66:81], v[28:31], v[126:129], v[66:81]
	global_load_dwordx4 v[28:31], v[46:47], off
	s_nop 0
	global_load_dwordx4 v[38:41], v[38:39], off
	s_nop 0
	global_load_dwordx4 v[42:45], v[48:49], off
	s_nop 0
	global_load_dwordx4 v[46:49], v[50:51], off
	s_waitcnt lgkmcnt(1)
	v_mfma_f32_32x32x16_bf16 v[0:15], v[34:37], v[122:125], v[0:15]
	global_load_dwordx4 v[34:37], v[52:53], off
	ds_read_b128 v[50:53], v245 offset:33088
	s_waitcnt lgkmcnt(1)
	v_mfma_f32_32x32x16_bf16 v[66:81], v[24:27], v[122:125], v[66:81]
	ds_read_b128 v[24:27], v245 offset:45888
	ds_read_b128 v[54:57], v245 offset:33120
	s_waitcnt lgkmcnt(2)
	v_mfma_f32_32x32x16_bf16 v[0:15], v[50:53], v[118:121], v[0:15]
	v_and_b32_e32 v50, 0xc0, v59
	v_and_b32_e32 v59, 32, v61
	v_and_b32_e32 v61, 0x100, v60
	v_and_or_b32 v60, v60, 24, v50
	ds_read_b128 v[50:53], v245 offset:45920
	s_waitcnt vmcnt(0)
	s_waitcnt vmcnt(4)
	ds_write_b128 v249, v[28:31] offset:16384
	s_waitcnt lgkmcnt(3)
	v_mfma_f32_32x32x16_bf16 v[66:81], v[24:27], v[118:121], v[66:81]
	v_or3_b32 v24, v60, v59, v61
	v_add_u32_e32 v244, s6, v24
	v_add_u32_e32 v242, s7, v24
	s_lshl_b64 s[6:7], s[20:21], 8
	s_add_u32 s4, s6, s4
	s_addc_u32 s5, s7, s5
	v_lshl_add_u64 v[222:223], s[4:5], 0, v[16:17]
	s_waitcnt lgkmcnt(2)
	v_mfma_f32_32x32x16_bf16 v[0:15], v[54:57], v[114:117], v[0:15]
	s_waitcnt vmcnt(3)
	ds_write_b128 v250, v[38:41] offset:16384
	s_waitcnt vmcnt(2)
	ds_write_b128 v246, v[42:45] offset:58368
	s_waitcnt vmcnt(1)
	ds_write_b128 v247, v[46:49] offset:58368
	s_waitcnt vmcnt(0)
	ds_write_b128 v248, v[34:37] offset:58368
	s_mov_b32 s4, 2
	v_mov_b32_e32 v54, v243
	v_mov_b32_e32 v55, v243
	v_mov_b32_e32 v56, v243
	v_mov_b32_e32 v57, v243
	v_mov_b32_e32 v59, v243
	s_waitcnt lgkmcnt(5)
	v_mfma_f32_32x32x16_bf16 v[66:81], v[50:53], v[114:117], v[66:81]
	v_exp_f32_e32 v190, v0
	v_exp_f32_e32 v209, v1
	v_exp_f32_e32 v191, v2
	v_exp_f32_e32 v208, v3
	v_exp_f32_e32 v192, v4
	v_exp_f32_e32 v207, v5
	v_exp_f32_e32 v193, v6
	v_exp_f32_e32 v206, v7
	v_exp_f32_e32 v198, v8
	v_exp_f32_e32 v205, v9
	v_exp_f32_e32 v199, v10
	v_exp_f32_e32 v204, v11
	v_exp_f32_e32 v200, v12
	v_exp_f32_e32 v202, v13
	v_exp_f32_e32 v201, v14
	v_exp_f32_e32 v203, v15
	v_and_b32_e32 v0, 15, v232
	v_lshl_or_b32 v222, v0, 4, v222
	v_mov_b32_e32 v50, 0
	v_mov_b32_e32 v51, v243
	v_mov_b32_e32 v52, v243
	v_mov_b32_e32 v53, v243
	v_mov_b32_e32 v60, v243
	v_mov_b32_e32 v61, v243
	v_mov_b32_e32 v34, 0
	v_mov_b32_e32 v35, v243
	v_mov_b32_e32 v36, v243
	v_mov_b32_e32 v37, v243
	v_mov_b32_e32 v38, v243
	v_mov_b32_e32 v39, v243
	v_mov_b32_e32 v40, v243
	v_mov_b32_e32 v41, v243
	v_mov_b32_e32 v42, v243
	v_mov_b32_e32 v43, v243
	v_mov_b32_e32 v44, v243
	v_mov_b32_e32 v45, v243
	v_mov_b32_e32 v46, v243
	v_mov_b32_e32 v47, v243
	v_mov_b32_e32 v48, v243
	v_mov_b32_e32 v49, v243
	v_mov_b32_e32 v16, 0
	v_mov_b32_e32 v17, v243
	v_mov_b32_e32 v24, v243
	v_mov_b32_e32 v25, v243
	v_mov_b32_e32 v26, v243
	v_mov_b32_e32 v27, v243
	v_mov_b32_e32 v28, v243
	v_mov_b32_e32 v29, v243
	v_mov_b32_e32 v30, v243
	v_mov_b32_e32 v31, v243
	v_mov_b32_e32 v0, 0
	v_mov_b32_e32 v1, v243
	v_mov_b32_e32 v2, v243
	v_mov_b32_e32 v3, v243
	v_mov_b32_e32 v4, v243
	v_mov_b32_e32 v5, v243
	v_mov_b32_e32 v6, v243
	v_mov_b32_e32 v7, v243
	v_mov_b32_e32 v8, v243
	v_mov_b32_e32 v9, v243
	v_mov_b32_e32 v10, v243
	v_mov_b32_e32 v11, v243
	v_mov_b32_e32 v12, v243
	v_mov_b32_e32 v13, v243
	v_mov_b32_e32 v14, v243
	v_mov_b32_e32 v15, v243
	s_mov_b64 s[6:7], 0x60000
	v_readfirstlane_b32 s98, v222
	v_readfirstlane_b32 s99, v223
	v_readfirstlane_b32 s100, v216
	v_readfirstlane_b32 s101, v217
	s_nop 1
	v_subrev_u32_e32 v219, s98, v222
	v_subrev_u32_e32 v216, s100, v216
	v_add_u32_e32 v217, 0x10000, v219
	s_add_u32 s98, s98, s0
	s_addc_u32 s99, s99, s1
	s_add_u32 s100, s100, s0
	s_addc_u32 s101, s101, s1
	s_add_u32 s98, s98, 0x3ca5c000
	s_addc_u32 s99, s99, 0
	s_add_u32 s100, s100, 0x398fc000
	s_addc_u32 s101, s101, 0
	s_waitcnt lgkmcnt(0)
	s_barrier
; #define SBAR() __builtin_amdgcn_sched_barrier(0)
; #define SLOAD(i, k0) do { sv0[i] = *reinterpret_cast<const bf16x8*>(&Vh[(size_t)((k0) + sr) * ldv + sc]); sv1[i] = *reinterpret_cast<const bf16x8*>(&Vh[(size_t)((k0) + 32 + sr) * ldv + sc]); \
;     _Pragma("unroll") for (int _q = 0; _q < NKP; ++_q) sk[i][_q] = *reinterpret_cast<const bf16x8*>(&Kh[(size_t)(k0) * ldk + koff[_q]]); } while (0)
; #define SLOAD(k0) do { sv0 = *reinterpret_cast<const bf16x8*>(&Vh[(size_t)((k0) + sr) * ldv + sc]); sv1 = *reinterpret_cast<const bf16x8*>(&Vh[(size_t)((k0) + 32 + sr) * ldv + sc]); \
;     _Pragma("unroll") for (int _q = 0; _q < NKP; ++_q) sk[_q] = *reinterpret_cast<const bf16x8*>(&Kh[(size_t)(k0) * ldk + koff[_q]]); } while (0)
; template <int DQK, int SDEPTH, int QL, bool NOMAX, int ldq, int ldk, int ldv, int ldo> ...
;     ...
;         SBAR(); qkt<DQK, QL>(pB0, pB1, K_lds + SHM_K, qr, qpark, r32, hi);
;         finishSM(pA0, pA1, alA, l_reg, pa0, pa1, pa2, pa3); SBAR();
;         SLOAD(SO, (j + SDEPTH) * KVBLK); SBAR();
.LBB0_2012:
	ds_read_b128 v[82:85], v245 offset:58368
	ds_read_b128 v[106:109], v245 offset:58400
	ds_read_b128 v[102:105], v32 offset:12800
	ds_read_b128 v[98:101], v32 offset:12832
	v_exp_f32_e32 v66, v66
	v_exp_f32_e32 v67, v67
	s_waitcnt lgkmcnt(3)
	v_mfma_f32_32x32x16_bf16 v[82:97], v[82:85], v[158:161], 0
	v_exp_f32_e32 v68, v68
	v_exp_f32_e32 v69, v69
	v_exp_f32_e32 v70, v70
	v_exp_f32_e32 v71, v71
	v_exp_f32_e32 v72, v72
	v_exp_f32_e32 v73, v73
	v_exp_f32_e32 v74, v74
	s_waitcnt lgkmcnt(2)
	v_mfma_f32_32x32x16_bf16 v[82:97], v[106:109], v[154:157], v[82:97]
	ds_read_b128 v[110:113], v245 offset:58432
	ds_read_b128 v[106:109], v32 offset:12864
	v_exp_f32_e32 v75, v75
	v_exp_f32_e32 v76, v76
	v_exp_f32_e32 v77, v77
	v_exp_f32_e32 v78, v78
	v_exp_f32_e32 v79, v79
	v_exp_f32_e32 v80, v80
	s_waitcnt lgkmcnt(1)
	v_mfma_f32_32x32x16_bf16 v[82:97], v[110:113], v[150:153], v[82:97]
	ds_read_b128 v[162:165], v245 offset:58464
	ds_read_b128 v[110:113], v32 offset:12896
	v_exp_f32_e32 v81, v81
	s_waitcnt lgkmcnt(1)
	v_mfma_f32_32x32x16_bf16 v[82:97], v[162:165], v[146:149], v[82:97]
	ds_read_b128 v[166:169], v245 offset:58496
	ds_read_b128 v[162:165], v32 offset:12928
	s_waitcnt lgkmcnt(1)
	v_mfma_f32_32x32x16_bf16 v[82:97], v[166:169], v[142:145], v[82:97]
	ds_read_b128 v[170:173], v245 offset:58528
	ds_read_b128 v[166:169], v32 offset:12960
	s_waitcnt lgkmcnt(1)
	v_mfma_f32_32x32x16_bf16 v[82:97], v[170:173], v[138:141], v[82:97]
	ds_read_b128 v[174:177], v245 offset:58560
	ds_read_b128 v[170:173], v32 offset:12992
	s_waitcnt lgkmcnt(1)
	v_mfma_f32_32x32x16_bf16 v[82:97], v[174:177], v[134:137], v[82:97]
	ds_read_b128 v[178:181], v245 offset:58592
	ds_read_b128 v[174:177], v32 offset:13024
	s_waitcnt lgkmcnt(1)
	v_mfma_f32_32x32x16_bf16 v[82:97], v[178:181], v[130:133], v[82:97]
	ds_read_b128 v[182:185], v245 offset:58624
	ds_read_b128 v[178:181], v32 offset:13056
	s_waitcnt lgkmcnt(1)
	v_mfma_f32_32x32x16_bf16 v[82:97], v[182:185], v[126:129], v[82:97]
	ds_read_b128 v[186:189], v245 offset:58656
	ds_read_b128 v[182:185], v32 offset:13088
	s_waitcnt lgkmcnt(1)
	v_mfma_f32_32x32x16_bf16 v[82:97], v[186:189], v[122:125], v[82:97]
	ds_read_b128 v[194:197], v245 offset:58688
	ds_read_b128 v[186:189], v32 offset:13120
	s_waitcnt lgkmcnt(1)
	v_mfma_f32_32x32x16_bf16 v[82:97], v[194:197], v[118:121], v[82:97]
	ds_read_b128 v[224:227], v245 offset:58720
	ds_read_b128 v[194:197], v32 offset:13152
	s_waitcnt lgkmcnt(1)
	v_mfma_f32_32x32x16_bf16 v[82:97], v[224:227], v[114:117], v[82:97]
	v_add_f32_e32 v224, 0, v190
	v_add_f32_e32 v224, v209, v224
	v_add_f32_e32 v224, v191, v224
	v_add_f32_e32 v224, v208, v224
	v_add_f32_e32 v224, v192, v224
	v_add_f32_e32 v224, v207, v224
	v_add_f32_e32 v224, v193, v224
	v_add_f32_e32 v224, v206, v224
	v_add_f32_e32 v224, v198, v224
	v_add_f32_e32 v224, v205, v224
	v_add_f32_e32 v224, v199, v224
	v_add_f32_e32 v224, v204, v224
	v_add_f32_e32 v224, v200, v224
	v_add_f32_e32 v224, v202, v224
	v_add_f32_e32 v224, v201, v224
	v_add_f32_e32 v224, v203, v224
	v_add_f32_e32 v224, v66, v224
	v_add_f32_e32 v224, v67, v224
	v_add_f32_e32 v224, v68, v224
	v_add_f32_e32 v224, v69, v224
	v_add_f32_e32 v224, v70, v224
	v_add_f32_e32 v224, v71, v224
	v_add_f32_e32 v224, v72, v224
	v_add_f32_e32 v224, v73, v224
	v_add_f32_e32 v224, v74, v224
	v_add_f32_e32 v224, v75, v224
	v_add_f32_e32 v224, v76, v224
	v_add_f32_e32 v224, v77, v224
	v_add_f32_e32 v224, v78, v224
	v_add_f32_e32 v224, v79, v224
	v_add_f32_e32 v224, v80, v224
	v_add_f32_e32 v251, v81, v224
	v_cvt_pk_bf16_f32 v190, v190, v209
	v_cvt_pk_bf16_f32 v191, v191, v208
	v_cvt_pk_bf16_f32 v192, v192, v207
	v_cvt_pk_bf16_f32 v193, v193, v206
	v_cvt_pk_bf16_f32 v198, v198, v205
	v_cvt_pk_bf16_f32 v199, v199, v204
	v_cvt_pk_bf16_f32 v200, v200, v202
	v_cvt_pk_bf16_f32 v201, v201, v203
	v_cvt_pk_bf16_f32 v202, v66, v67
	v_cvt_pk_bf16_f32 v203, v68, v69
	v_cvt_pk_bf16_f32 v204, v70, v71
	v_cvt_pk_bf16_f32 v205, v72, v73
	v_cvt_pk_bf16_f32 v206, v74, v75
	v_cvt_pk_bf16_f32 v207, v76, v77
	v_cvt_pk_bf16_f32 v208, v78, v79
	v_cvt_pk_bf16_f32 v209, v80, v81
	s_nop 1
	v_permlane32_swap_b32_e32 v190, v192
	v_permlane32_swap_b32_e32 v191, v193
	v_permlane32_swap_b32_e32 v198, v200
	v_permlane32_swap_b32_e32 v199, v201
	v_permlane32_swap_b32_e32 v202, v204
	v_permlane32_swap_b32_e32 v203, v205
	v_permlane32_swap_b32_e32 v206, v208
	v_permlane32_swap_b32_e32 v207, v209
	v_mfma_f32_32x32x16_bf16 v[66:81], v[102:105], v[158:161], 0
	v_mfma_f32_32x32x16_bf16 v[66:81], v[98:101], v[154:157], v[66:81]
	v_mfma_f32_32x32x16_bf16 v[66:81], v[106:109], v[150:153], v[66:81]
	global_load_dwordx4 v[98:101], v219, s[98:99] offset:256
	global_load_dwordx4 v[102:105], v217, s[98:99] offset:256
	v_mfma_f32_32x32x16_bf16 v[66:81], v[110:113], v[146:149], v[66:81]
	global_load_dwordx4 v[106:109], v216, s[100:101] offset:256
	global_load_dwordx4 v[110:113], v216, s[100:101] offset:384
	v_mfma_f32_32x32x16_bf16 v[66:81], v[162:165], v[142:145], v[66:81]
	global_load_dwordx4 v[162:165], v216, s[100:101] offset:512
	s_add_u32 s98, s98, 0x20000
	s_addc_u32 s99, s99, 0
	s_add_u32 s100, s100, 0x30000
	s_addc_u32 s101, s101, 0
	v_mfma_f32_32x32x16_bf16 v[66:81], v[166:169], v[138:141], v[66:81]
	v_mfma_f32_32x32x16_bf16 v[66:81], v[170:173], v[134:137], v[66:81]
	v_mfma_f32_32x32x16_bf16 v[66:81], v[174:177], v[130:133], v[66:81]
	v_mfma_f32_32x32x16_bf16 v[66:81], v[178:181], v[126:129], v[66:81]
	v_mfma_f32_32x32x16_bf16 v[66:81], v[182:185], v[122:125], v[66:81]
	v_mfma_f32_32x32x16_bf16 v[66:81], v[186:189], v[118:121], v[66:81]
	s_waitcnt lgkmcnt(0)
; #define SBAR() __builtin_amdgcn_sched_barrier(0)
; #define SWRITE(b, i) do { *(bf16x8*)(V_lds + (b) * SHM_V + vst0) = sv0[i]; *(bf16x8*)(V_lds + (b) * SHM_V + vst1) = sv1[i]; \
;     _Pragma("unroll") for (int _q = 0; _q < NKP; ++_q) *(bf16x8*)(K_lds + (b) * SHM_K + klds[_q]) = sk[i][_q]; } while (0)
; #define SWAIT() do { if constexpr (SDEPTH == 2) { if constexpr (NKP == 1) asm volatile("s_waitcnt vmcnt(3)" ::: "memory"); else if constexpr (NKP == 2) asm volatile("s_waitcnt vmcnt(4)" ::: "memory"); else asm volatile("s_waitcnt vmcnt(5)" ::: "memory"); } \
;     else asm volatile("s_waitcnt vmcnt(0)" ::: "memory"); } while (0)
; #define PVD0(...) do { if constexpr (PV_PIPE != 0) pv_d0_pipe(__VA_ARGS__); else pv_d0(__VA_ARGS__); } while (0)
; #define RESC(a) do { if constexpr (!NOMAX) if (__any((a) < 1.f)) { if (hi == 0) al_l[r32] = (a); asm volatile("s_waitcnt lgkmcnt(0)" ::: "memory"); \
;     _Pragma("unroll") for (int d = 0; d < 4; ++d) _Pragma("unroll") for (int r = 0; r < 16; ++r) o[d][r] *= al_l[crow(r, hi)]; } } while (0)
; #define SWRITE(b) do { *(bf16x8*)(V_lds + (b) * SHM_V + vst0) = sv0; *(bf16x8*)(V_lds + (b) * SHM_V + vst1) = sv1; \
;     _Pragma("unroll") for (int _q = 0; _q < NKP; ++_q) *(bf16x8*)(K_lds + (b) * SHM_K + klds[_q]) = sk[_q]; } while (0)
; #define RESC(a) do { if (__any((a) < 1.f)) { if (hi == 0) al_l[r32] = (a); asm volatile("s_waitcnt lgkmcnt(0)" ::: "memory"); \
;     _Pragma("unroll") for (int d = 0; d < 4; ++d) _Pragma("unroll") for (int r = 0; r < 16; ++r) o[d][r] *= al_l[crow(r, hi)]; } } while (0)
; template <int DQK, int SDEPTH, int QL, bool NOMAX, int ldq, int ldk, int ldv, int ldo> ...
;     ...
;         PVD0(o, vb0, pa0, pa1, pa2, pa3); if constexpr (NOMAX) { partialSM_nm(pB0); alB = 1.f; } else partialSM(pB0, pB1, m_reg, mnB, alB, C, thr_raw);
;         __syncthreads(); SWAIT(); SWRITE(0, SE);
;         RESC(alB); __syncthreads();
;         SBAR(); qkt<DQK, QL>(pA0, pA1, K_lds, qr, qpark, r32, hi);
	v_mfma_f32_32x32x16_bf16 v[66:81], v[194:197], v[114:117], v[66:81]
	ds_read_b64_tr_b16 v[166:167], v244 offset:0
	ds_read_b64_tr_b16 v[168:169], v244 offset:0x800
	ds_read_b64_tr_b16 v[170:171], v244 offset:0x1000
	ds_read_b64_tr_b16 v[172:173], v244 offset:0x1800
	ds_read_b64_tr_b16 v[174:175], v244 offset:0x2000
	ds_read_b64_tr_b16 v[176:177], v244 offset:0x2800
	ds_read_b64_tr_b16 v[178:179], v244 offset:0x3000
	ds_read_b64_tr_b16 v[180:181], v244 offset:0x3800
	s_waitcnt lgkmcnt(6)
	s_nop 0
	v_mfma_f32_32x32x16_bf16 v[50:65], v[190:193], v[166:169], v[50:65]
	ds_read_b64_tr_b16 v[166:167], v244 offset:0x200
	ds_read_b64_tr_b16 v[168:169], v244 offset:0xa00
	s_waitcnt lgkmcnt(6)
	v_mfma_f32_32x32x16_bf16 v[50:65], v[198:201], v[170:173], v[50:65]
	ds_read_b64_tr_b16 v[170:171], v244 offset:0x1200
	ds_read_b64_tr_b16 v[172:173], v244 offset:0x1a00
	s_waitcnt lgkmcnt(6)
	v_mfma_f32_32x32x16_bf16 v[50:65], v[202:205], v[174:177], v[50:65]
	ds_read_b64_tr_b16 v[174:175], v244 offset:0x2200
	ds_read_b64_tr_b16 v[176:177], v244 offset:0x2a00
	s_waitcnt lgkmcnt(6)
	v_mfma_f32_32x32x16_bf16 v[50:65], v[206:209], v[178:181], v[50:65]
	ds_read_b64_tr_b16 v[178:179], v244 offset:0x3200
	ds_read_b64_tr_b16 v[180:181], v244 offset:0x3a00
	s_waitcnt lgkmcnt(6)
	v_mfma_f32_32x32x16_bf16 v[34:49], v[190:193], v[166:169], v[34:49]
	ds_read_b64_tr_b16 v[166:167], v244 offset:0x400
	ds_read_b64_tr_b16 v[168:169], v244 offset:0xc00
	s_waitcnt lgkmcnt(6)
	v_mfma_f32_32x32x16_bf16 v[34:49], v[198:201], v[170:173], v[34:49]
	ds_read_b64_tr_b16 v[170:171], v244 offset:0x1400
	ds_read_b64_tr_b16 v[172:173], v244 offset:0x1c00
	s_waitcnt lgkmcnt(6)
	v_mfma_f32_32x32x16_bf16 v[34:49], v[202:205], v[174:177], v[34:49]
	ds_read_b64_tr_b16 v[174:175], v244 offset:0x2400
	ds_read_b64_tr_b16 v[176:177], v244 offset:0x2c00
	s_waitcnt lgkmcnt(6)
	v_mfma_f32_32x32x16_bf16 v[34:49], v[206:209], v[178:181], v[34:49]
	ds_read_b64_tr_b16 v[178:179], v244 offset:0x3400
	ds_read_b64_tr_b16 v[180:181], v244 offset:0x3c00
	s_waitcnt lgkmcnt(6)
	v_mfma_f32_32x32x16_bf16 v[16:31], v[190:193], v[166:169], v[16:31]
	ds_read_b64_tr_b16 v[166:167], v244 offset:0x600
	ds_read_b64_tr_b16 v[168:169], v244 offset:0xe00
	s_waitcnt lgkmcnt(6)
	v_mfma_f32_32x32x16_bf16 v[16:31], v[198:201], v[170:173], v[16:31]
	ds_read_b64_tr_b16 v[170:171], v244 offset:0x1600
	ds_read_b64_tr_b16 v[172:173], v244 offset:0x1e00
	s_waitcnt lgkmcnt(6)
	v_mfma_f32_32x32x16_bf16 v[16:31], v[202:205], v[174:177], v[16:31]
	ds_read_b64_tr_b16 v[174:175], v244 offset:0x2600
	ds_read_b64_tr_b16 v[176:177], v244 offset:0x2e00
	s_waitcnt lgkmcnt(6)
	v_mfma_f32_32x32x16_bf16 v[16:31], v[206:209], v[178:181], v[16:31]
	ds_read_b64_tr_b16 v[178:179], v244 offset:0x3600
	ds_read_b64_tr_b16 v[180:181], v244 offset:0x3e00
	s_waitcnt lgkmcnt(0)
	v_mfma_f32_32x32x16_bf16 v[0:15], v[190:193], v[166:169], v[0:15]
	s_barrier
	s_waitcnt vmcnt(0)
	s_waitcnt vmcnt(4)
	ds_write_b128 v249, v[98:101]
	s_waitcnt vmcnt(3)
	ds_write_b128 v250, v[102:105]
	s_waitcnt vmcnt(2)
	ds_write_b128 v246, v[106:109] offset:32768
	s_waitcnt vmcnt(1)
	ds_write_b128 v247, v[110:113] offset:32768
	s_waitcnt vmcnt(0)
	ds_write_b128 v248, v[162:165] offset:32768
	v_exp_f32_e32 v253, v82
	v_mfma_f32_32x32x16_bf16 v[0:15], v[198:201], v[170:173], v[0:15]
	v_exp_f32_e32 v198, v86
	v_exp_f32_e32 v199, v87
	v_exp_f32_e32 v200, v94
	v_exp_f32_e32 v201, v95
	v_exp_f32_e32 v237, v83
	v_exp_f32_e32 v238, v84
	v_exp_f32_e32 v236, v85
	v_mfma_f32_32x32x16_bf16 v[0:15], v[202:205], v[174:177], v[0:15]
	v_exp_f32_e32 v204, v93
	v_exp_f32_e32 v202, v96
	v_exp_f32_e32 v203, v97
	v_exp_f32_e32 v214, v88
	v_exp_f32_e32 v215, v89
	v_exp_f32_e32 v210, v90
	v_exp_f32_e32 v211, v91
	v_mfma_f32_32x32x16_bf16 v[0:15], v[206:209], v[178:181], v[0:15]
	v_exp_f32_e32 v212, v92
	s_waitcnt lgkmcnt(0)
	s_barrier
	ds_read_b128 v[98:101], v245 offset:45568
	ds_read_b128 v[82:85], v245 offset:32768
	ds_read_b128 v[106:109], v245 offset:32800
	ds_read_b128 v[102:105], v245 offset:45600
	v_exp_f32_e32 v66, v66
	v_exp_f32_e32 v67, v67
	s_waitcnt lgkmcnt(2)
	v_mfma_f32_32x32x16_bf16 v[82:97], v[82:85], v[158:161], 0
	v_exp_f32_e32 v68, v68
	v_exp_f32_e32 v69, v69
	v_exp_f32_e32 v70, v70
	v_exp_f32_e32 v71, v71
	v_exp_f32_e32 v72, v72
	v_exp_f32_e32 v73, v73
	v_exp_f32_e32 v74, v74
	s_waitcnt lgkmcnt(1)
	v_mfma_f32_32x32x16_bf16 v[82:97], v[106:109], v[154:157], v[82:97]
	ds_read_b128 v[110:113], v245 offset:32832
	ds_read_b128 v[106:109], v245 offset:45632
	v_exp_f32_e32 v75, v75
	v_exp_f32_e32 v76, v76
	v_exp_f32_e32 v77, v77
	v_exp_f32_e32 v78, v78
	v_exp_f32_e32 v79, v79
	v_exp_f32_e32 v80, v80
	s_waitcnt lgkmcnt(1)
	v_mfma_f32_32x32x16_bf16 v[82:97], v[110:113], v[150:153], v[82:97]
	ds_read_b128 v[162:165], v245 offset:32864
	ds_read_b128 v[110:113], v245 offset:45664
	v_exp_f32_e32 v81, v81
	s_waitcnt lgkmcnt(1)
	v_mfma_f32_32x32x16_bf16 v[82:97], v[162:165], v[146:149], v[82:97]
	ds_read_b128 v[166:169], v245 offset:32896
	ds_read_b128 v[162:165], v245 offset:45696
	s_waitcnt lgkmcnt(1)
	v_mfma_f32_32x32x16_bf16 v[82:97], v[166:169], v[142:145], v[82:97]
	ds_read_b128 v[170:173], v245 offset:32928
	ds_read_b128 v[166:169], v245 offset:45728
	s_waitcnt lgkmcnt(1)
	v_mfma_f32_32x32x16_bf16 v[82:97], v[170:173], v[138:141], v[82:97]
	ds_read_b128 v[174:177], v245 offset:32960
	ds_read_b128 v[170:173], v245 offset:45760
	s_waitcnt lgkmcnt(1)
	v_mfma_f32_32x32x16_bf16 v[82:97], v[174:177], v[134:137], v[82:97]
	ds_read_b128 v[178:181], v245 offset:32992
	ds_read_b128 v[174:177], v245 offset:45792
	s_waitcnt lgkmcnt(1)
; #define SBAR() __builtin_amdgcn_sched_barrier(0)
; #define SLOAD(i, k0) do { sv0[i] = *reinterpret_cast<const bf16x8*>(&Vh[(size_t)((k0) + sr) * ldv + sc]); sv1[i] = *reinterpret_cast<const bf16x8*>(&Vh[(size_t)((k0) + 32 + sr) * ldv + sc]); \
;     _Pragma("unroll") for (int _q = 0; _q < NKP; ++_q) sk[i][_q] = *reinterpret_cast<const bf16x8*>(&Kh[(size_t)(k0) * ldk + koff[_q]]); } while (0)
; #define PVD0(...) do { if constexpr (PV_PIPE != 0) pv_d0_pipe(__VA_ARGS__); else pv_d0(__VA_ARGS__); } while (0)
; #define SLOAD(k0) do { sv0 = *reinterpret_cast<const bf16x8*>(&Vh[(size_t)((k0) + sr) * ldv + sc]); sv1 = *reinterpret_cast<const bf16x8*>(&Vh[(size_t)((k0) + 32 + sr) * ldv + sc]); \
;     _Pragma("unroll") for (int _q = 0; _q < NKP; ++_q) sk[_q] = *reinterpret_cast<const bf16x8*>(&Kh[(size_t)(k0) * ldk + koff[_q]]); } while (0)
; template <int DQK, int SDEPTH, int QL, bool NOMAX, int ldq, int ldk, int ldv, int ldo> ...
;     ...
;         SBAR(); qkt<DQK, QL>(pA0, pA1, K_lds, qr, qpark, r32, hi);
;         finishSM(pB0, pB1, alB, l_reg, pa0, pa1, pa2, pa3); SBAR();
;         if (SDEPTH == 1 || j + 3 < NT) SLOAD(SE, (j + 1 + SDEPTH) * KVBLK); SBAR();
;         PVD0(o, vb0 + SHM_V, pa0, pa1, pa2, pa3); if constexpr (NOMAX) { partialSM_nm(pA0); alA = 1.f; } else partialSM(pA0, pA1, m_reg, mnA, alA, C, thr_raw);
	v_mfma_f32_32x32x16_bf16 v[82:97], v[178:181], v[130:133], v[82:97]
	ds_read_b128 v[178:181], v245 offset:33024
	ds_read_b128 v[186:189], v245 offset:45824
	s_waitcnt lgkmcnt(1)
	v_mfma_f32_32x32x16_bf16 v[82:97], v[178:181], v[126:129], v[82:97]
	ds_read_b128 v[178:181], v245 offset:33056
	ds_read_b128 v[182:185], v245 offset:45856
	s_waitcnt lgkmcnt(1)
	v_mfma_f32_32x32x16_bf16 v[82:97], v[178:181], v[122:125], v[82:97]
	ds_read_b128 v[190:193], v245 offset:33088
	ds_read_b128 v[178:181], v245 offset:45888
	s_waitcnt lgkmcnt(1)
	v_mfma_f32_32x32x16_bf16 v[82:97], v[190:193], v[118:121], v[82:97]
	ds_read_b128 v[194:197], v245 offset:33120
	ds_read_b128 v[190:193], v245 offset:45920
	s_waitcnt lgkmcnt(1)
	v_mfma_f32_32x32x16_bf16 v[82:97], v[194:197], v[114:117], v[82:97]
	v_add_f32_e32 v194, 0, v253
	v_add_f32_e32 v194, v237, v194
	v_add_f32_e32 v194, v238, v194
	v_add_f32_e32 v194, v236, v194
	v_add_f32_e32 v194, v198, v194
	v_add_f32_e32 v194, v199, v194
	v_add_f32_e32 v194, v214, v194
	v_add_f32_e32 v194, v215, v194
	v_add_f32_e32 v194, v210, v194
	v_add_f32_e32 v194, v211, v194
	v_add_f32_e32 v194, v212, v194
	v_add_f32_e32 v194, v204, v194
	v_add_f32_e32 v194, v200, v194
	v_add_f32_e32 v194, v201, v194
	v_add_f32_e32 v194, v202, v194
	v_add_f32_e32 v194, v203, v194
	v_add_f32_e32 v194, v194, v66
	v_add_f32_e32 v194, v67, v194
	v_add_f32_e32 v194, v68, v194
	v_add_f32_e32 v194, v69, v194
	v_add_f32_e32 v194, v70, v194
	v_add_f32_e32 v194, v71, v194
	v_add_f32_e32 v194, v72, v194
	v_add_f32_e32 v194, v73, v194
	v_add_f32_e32 v194, v74, v194
	v_add_f32_e32 v194, v75, v194
	v_add_f32_e32 v194, v76, v194
	v_add_f32_e32 v194, v77, v194
	v_add_f32_e32 v194, v78, v194
	v_add_f32_e32 v194, v79, v194
	v_add_f32_e32 v194, v80, v194
	v_add_f32_e32 v252, v81, v194
	v_cvt_pk_bf16_f32 v194, v253, v237
	v_cvt_pk_bf16_f32 v195, v238, v236
	v_cvt_pk_bf16_f32 v196, v198, v199
	v_cvt_pk_bf16_f32 v197, v214, v215
	v_cvt_pk_bf16_f32 v198, v210, v211
	v_cvt_pk_bf16_f32 v199, v212, v204
	v_cvt_pk_bf16_f32 v200, v200, v201
	v_cvt_pk_bf16_f32 v201, v202, v203
	v_cvt_pk_bf16_f32 v202, v66, v67
	v_cvt_pk_bf16_f32 v203, v68, v69
	v_cvt_pk_bf16_f32 v204, v70, v71
	v_cvt_pk_bf16_f32 v205, v72, v73
	v_cvt_pk_bf16_f32 v206, v74, v75
	v_cvt_pk_bf16_f32 v207, v76, v77
	v_cvt_pk_bf16_f32 v208, v78, v79
	v_cvt_pk_bf16_f32 v209, v80, v81
	s_nop 0
	v_permlane32_swap_b32_e32 v198, v200
	v_permlane32_swap_b32_e32 v199, v201
	v_permlane32_swap_b32_e32 v202, v204
	v_permlane32_swap_b32_e32 v203, v205
	v_permlane32_swap_b32_e32 v206, v208
	v_permlane32_swap_b32_e32 v207, v209
	v_permlane32_swap_b32_e32 v194, v196
	v_permlane32_swap_b32_e32 v195, v197
	v_mfma_f32_32x32x16_bf16 v[66:81], v[98:101], v[158:161], 0
	v_mfma_f32_32x32x16_bf16 v[66:81], v[102:105], v[154:157], v[66:81]
	global_load_dwordx4 v[98:101], v219, s[98:99] offset:256
	global_load_dwordx4 v[102:105], v217, s[98:99] offset:256
	v_mfma_f32_32x32x16_bf16 v[66:81], v[106:109], v[150:153], v[66:81]
	v_mfma_f32_32x32x16_bf16 v[66:81], v[110:113], v[146:149], v[66:81]
	global_load_dwordx4 v[106:109], v216, s[100:101] offset:256
	global_load_dwordx4 v[110:113], v216, s[100:101] offset:384
	v_mfma_f32_32x32x16_bf16 v[66:81], v[162:165], v[142:145], v[66:81]
	global_load_dwordx4 v[162:165], v216, s[100:101] offset:512
	s_add_u32 s98, s98, 0x20000
	s_addc_u32 s99, s99, 0
	s_add_u32 s100, s100, 0x30000
	s_addc_u32 s101, s101, 0
	v_mfma_f32_32x32x16_bf16 v[66:81], v[166:169], v[138:141], v[66:81]
	v_mfma_f32_32x32x16_bf16 v[66:81], v[170:173], v[134:137], v[66:81]
	v_mfma_f32_32x32x16_bf16 v[66:81], v[174:177], v[130:133], v[66:81]
	v_mfma_f32_32x32x16_bf16 v[66:81], v[186:189], v[126:129], v[66:81]
	v_mfma_f32_32x32x16_bf16 v[66:81], v[182:185], v[122:125], v[66:81]
	v_mfma_f32_32x32x16_bf16 v[66:81], v[178:181], v[118:121], v[66:81]
	s_waitcnt lgkmcnt(0)
	v_mfma_f32_32x32x16_bf16 v[66:81], v[190:193], v[114:117], v[66:81]
	ds_read_b64_tr_b16 v[166:167], v242 offset:0
	ds_read_b64_tr_b16 v[168:169], v242 offset:0x800
	ds_read_b64_tr_b16 v[170:171], v242 offset:0x1000
	ds_read_b64_tr_b16 v[172:173], v242 offset:0x1800
	ds_read_b64_tr_b16 v[174:175], v242 offset:0x2000
	ds_read_b64_tr_b16 v[176:177], v242 offset:0x2800
	ds_read_b64_tr_b16 v[178:179], v242 offset:0x3000
	ds_read_b64_tr_b16 v[180:181], v242 offset:0x3800
	s_waitcnt lgkmcnt(6)
	s_nop 0
	v_mfma_f32_32x32x16_bf16 v[50:65], v[194:197], v[166:169], v[50:65]
	ds_read_b64_tr_b16 v[166:167], v242 offset:0x200
	ds_read_b64_tr_b16 v[168:169], v242 offset:0xa00
	s_waitcnt lgkmcnt(6)
	v_mfma_f32_32x32x16_bf16 v[50:65], v[198:201], v[170:173], v[50:65]
	ds_read_b64_tr_b16 v[170:171], v242 offset:0x1200
	ds_read_b64_tr_b16 v[172:173], v242 offset:0x1a00
	s_waitcnt lgkmcnt(6)
	v_mfma_f32_32x32x16_bf16 v[50:65], v[202:205], v[174:177], v[50:65]
	ds_read_b64_tr_b16 v[174:175], v242 offset:0x2200
	ds_read_b64_tr_b16 v[176:177], v242 offset:0x2a00
	s_waitcnt lgkmcnt(6)
	v_mfma_f32_32x32x16_bf16 v[50:65], v[206:209], v[178:181], v[50:65]
	ds_read_b64_tr_b16 v[178:179], v242 offset:0x3200
	ds_read_b64_tr_b16 v[180:181], v242 offset:0x3a00
	s_waitcnt lgkmcnt(6)
	v_mfma_f32_32x32x16_bf16 v[34:49], v[194:197], v[166:169], v[34:49]
	ds_read_b64_tr_b16 v[166:167], v242 offset:0x400
	ds_read_b64_tr_b16 v[168:169], v242 offset:0xc00
	s_waitcnt lgkmcnt(6)
	v_mfma_f32_32x32x16_bf16 v[34:49], v[198:201], v[170:173], v[34:49]
	ds_read_b64_tr_b16 v[170:171], v242 offset:0x1400
	ds_read_b64_tr_b16 v[172:173], v242 offset:0x1c00
	s_waitcnt lgkmcnt(6)
	v_mfma_f32_32x32x16_bf16 v[34:49], v[202:205], v[174:177], v[34:49]
	ds_read_b64_tr_b16 v[174:175], v242 offset:0x2400
	ds_read_b64_tr_b16 v[176:177], v242 offset:0x2c00
	s_waitcnt lgkmcnt(6)
	v_mfma_f32_32x32x16_bf16 v[34:49], v[206:209], v[178:181], v[34:49]
	ds_read_b64_tr_b16 v[178:179], v242 offset:0x3400
	ds_read_b64_tr_b16 v[180:181], v242 offset:0x3c00
	s_waitcnt lgkmcnt(6)
	v_mfma_f32_32x32x16_bf16 v[16:31], v[194:197], v[166:169], v[16:31]
	ds_read_b64_tr_b16 v[166:167], v242 offset:0x600
	ds_read_b64_tr_b16 v[168:169], v242 offset:0xe00
	s_waitcnt lgkmcnt(6)
	v_mfma_f32_32x32x16_bf16 v[16:31], v[198:201], v[170:173], v[16:31]
	ds_read_b64_tr_b16 v[170:171], v242 offset:0x1600
	ds_read_b64_tr_b16 v[172:173], v242 offset:0x1e00
	s_waitcnt lgkmcnt(6)
	v_mfma_f32_32x32x16_bf16 v[16:31], v[202:205], v[174:177], v[16:31]
	ds_read_b64_tr_b16 v[174:175], v242 offset:0x2600
	ds_read_b64_tr_b16 v[176:177], v242 offset:0x2e00
	s_waitcnt lgkmcnt(6)
	v_mfma_f32_32x32x16_bf16 v[16:31], v[206:209], v[178:181], v[16:31]
	ds_read_b64_tr_b16 v[178:179], v242 offset:0x3600
	ds_read_b64_tr_b16 v[180:181], v242 offset:0x3e00
	s_waitcnt lgkmcnt(0)
	v_mfma_f32_32x32x16_bf16 v[0:15], v[194:197], v[166:169], v[0:15]
	v_exp_f32_e32 v190, v82
	v_exp_f32_e32 v191, v84
	v_exp_f32_e32 v192, v86
	v_exp_f32_e32 v193, v88
	s_barrier
; #define SBAR() __builtin_amdgcn_sched_barrier(0)
; #define SLOAD(i, k0) do { sv0[i] = *reinterpret_cast<const bf16x8*>(&Vh[(size_t)((k0) + sr) * ldv + sc]); sv1[i] = *reinterpret_cast<const bf16x8*>(&Vh[(size_t)((k0) + 32 + sr) * ldv + sc]); \
;     _Pragma("unroll") for (int _q = 0; _q < NKP; ++_q) sk[i][_q] = *reinterpret_cast<const bf16x8*>(&Kh[(size_t)(k0) * ldk + koff[_q]]); } while (0)
; #define SWRITE(b, i) do { *(bf16x8*)(V_lds + (b) * SHM_V + vst0) = sv0[i]; *(bf16x8*)(V_lds + (b) * SHM_V + vst1) = sv1[i]; \
;     _Pragma("unroll") for (int _q = 0; _q < NKP; ++_q) *(bf16x8*)(K_lds + (b) * SHM_K + klds[_q]) = sk[i][_q]; } while (0)
; #define SWAIT() do { if constexpr (SDEPTH == 2) { if constexpr (NKP == 1) asm volatile("s_waitcnt vmcnt(3)" ::: "memory"); else if constexpr (NKP == 2) asm volatile("s_waitcnt vmcnt(4)" ::: "memory"); else asm volatile("s_waitcnt vmcnt(5)" ::: "memory"); } \
;     else asm volatile("s_waitcnt vmcnt(0)" ::: "memory"); } while (0)
; #define PVD0(...) do { if constexpr (PV_PIPE != 0) pv_d0_pipe(__VA_ARGS__); else pv_d0(__VA_ARGS__); } while (0)
; #define RESC(a) do { if constexpr (!NOMAX) if (__any((a) < 1.f)) { if (hi == 0) al_l[r32] = (a); asm volatile("s_waitcnt lgkmcnt(0)" ::: "memory"); \
;     _Pragma("unroll") for (int d = 0; d < 4; ++d) _Pragma("unroll") for (int r = 0; r < 16; ++r) o[d][r] *= al_l[crow(r, hi)]; } } while (0)
; #define SLOAD(k0) do { sv0 = *reinterpret_cast<const bf16x8*>(&Vh[(size_t)((k0) + sr) * ldv + sc]); sv1 = *reinterpret_cast<const bf16x8*>(&Vh[(size_t)((k0) + 32 + sr) * ldv + sc]); \
;     _Pragma("unroll") for (int _q = 0; _q < NKP; ++_q) sk[_q] = *reinterpret_cast<const bf16x8*>(&Kh[(size_t)(k0) * ldk + koff[_q]]); } while (0)
; template <int DQK, int SDEPTH, int QL, bool NOMAX, int ldq, int ldk, int ldv, int ldo> ...
;     ...
;         finishSM(pB0, pB1, alB, l_reg, pa0, pa1, pa2, pa3); SBAR();
;         if (SDEPTH == 1 || j + 3 < NT) SLOAD(SE, (j + 1 + SDEPTH) * KVBLK); SBAR();
;         PVD0(o, vb0 + SHM_V, pa0, pa1, pa2, pa3); if constexpr (NOMAX) { partialSM_nm(pA0); alA = 1.f; } else partialSM(pA0, pA1, m_reg, mnA, alA, C, thr_raw);
;         __syncthreads(); SWAIT(); SWRITE(1, SO);
;         RESC(alA); __syncthreads();
;     }
;     SBAR(); qkt<DQK, QL>(pB0, pB1, K_lds + SHM_K, qr, qpark, r32, hi);
;     finishSM(pA0, pA1, alA, l_reg, pa0, pa1, pa2, pa3); SBAR();
	v_mfma_f32_32x32x16_bf16 v[0:15], v[198:201], v[170:173], v[0:15]
	v_exp_f32_e32 v198, v90
	v_exp_f32_e32 v199, v92
	v_exp_f32_e32 v200, v94
	v_exp_f32_e32 v201, v96
	s_waitcnt vmcnt(0)
	v_add_f32_e32 v82, v243, v251
	s_add_i32 s4, s4, 2
	v_mfma_f32_32x32x16_bf16 v[0:15], v[202:205], v[174:177], v[0:15]
	v_exp_f32_e32 v205, v91
	v_exp_f32_e32 v204, v93
	v_exp_f32_e32 v202, v95
	v_exp_f32_e32 v203, v97
	v_add_f32_e32 v243, v82, v252
	v_mfma_f32_32x32x16_bf16 v[0:15], v[206:209], v[178:181], v[0:15]
	v_exp_f32_e32 v209, v83
	v_exp_f32_e32 v208, v85
	v_exp_f32_e32 v207, v87
	v_exp_f32_e32 v206, v89
	s_cmp_ge_u32 s4, s51
	s_waitcnt vmcnt(4)
	ds_write_b128 v249, v[98:101] offset:16384
	s_waitcnt vmcnt(3)
	ds_write_b128 v250, v[102:105] offset:16384
	s_waitcnt vmcnt(2)
	ds_write_b128 v246, v[106:109] offset:58368
	s_waitcnt vmcnt(1)
	ds_write_b128 v247, v[110:113] offset:58368
	s_waitcnt vmcnt(0)
	ds_write_b128 v248, v[162:165] offset:58368
	s_waitcnt lgkmcnt(0)
	s_barrier
	s_cbranch_scc0 .LBB0_2012
	v_mov_b32_e32 v213, v243
	s_nop 1
	v_permlane32_swap_b32_e32 v243, v213
	v_add_f32_e32 v243, v243, v213
	ds_read_b128 v[82:85], v245 offset:58368
	ds_read_b128 v[162:165], v245 offset:58400
	v_exp_f32_e32 v67, v67
	v_exp_f32_e32 v69, v69
	s_waitcnt lgkmcnt(1)
	v_mfma_f32_32x32x16_bf16 v[98:113], v[82:85], v[158:161], 0
	ds_read_b128 v[82:85], v32 offset:12800
	ds_read_b128 v[166:169], v32 offset:12832
	s_waitcnt lgkmcnt(1)
	v_mfma_f32_32x32x16_bf16 v[82:97], v[82:85], v[158:161], 0
	v_mfma_f32_32x32x16_bf16 v[98:113], v[162:165], v[154:157], v[98:113]
	s_waitcnt lgkmcnt(0)
	v_mfma_f32_32x32x16_bf16 v[82:97], v[166:169], v[154:157], v[82:97]
	ds_read_b128 v[154:157], v245 offset:58432
	ds_read_b128 v[158:161], v32 offset:12864
	s_waitcnt lgkmcnt(1)
	v_mfma_f32_32x32x16_bf16 v[98:113], v[154:157], v[150:153], v[98:113]
	s_waitcnt lgkmcnt(0)
	v_mfma_f32_32x32x16_bf16 v[82:97], v[158:161], v[150:153], v[82:97]
	ds_read_b128 v[150:153], v245 offset:58464
	ds_read_b128 v[154:157], v32 offset:12896
	s_waitcnt lgkmcnt(1)
	v_mfma_f32_32x32x16_bf16 v[98:113], v[150:153], v[146:149], v[98:113]
	s_waitcnt lgkmcnt(0)
	v_mfma_f32_32x32x16_bf16 v[82:97], v[154:157], v[146:149], v[82:97]
	ds_read_b128 v[146:149], v245 offset:58496
	ds_read_b128 v[150:153], v32 offset:12928
	s_waitcnt lgkmcnt(1)
	v_mfma_f32_32x32x16_bf16 v[98:113], v[146:149], v[142:145], v[98:113]
	s_waitcnt lgkmcnt(0)
	v_mfma_f32_32x32x16_bf16 v[82:97], v[150:153], v[142:145], v[82:97]
	ds_read_b128 v[142:145], v245 offset:58528
	ds_read_b128 v[146:149], v32 offset:12960
	s_waitcnt lgkmcnt(1)
	v_mfma_f32_32x32x16_bf16 v[98:113], v[142:145], v[138:141], v[98:113]
	s_waitcnt lgkmcnt(0)
	v_mfma_f32_32x32x16_bf16 v[82:97], v[146:149], v[138:141], v[82:97]
	ds_read_b128 v[138:141], v245 offset:58560
	ds_read_b128 v[142:145], v32 offset:12992
	s_waitcnt lgkmcnt(1)
	v_mfma_f32_32x32x16_bf16 v[98:113], v[138:141], v[134:137], v[98:113]
	s_waitcnt lgkmcnt(0)
	v_mfma_f32_32x32x16_bf16 v[82:97], v[142:145], v[134:137], v[82:97]
	ds_read_b128 v[134:137], v245 offset:58592
	ds_read_b128 v[138:141], v32 offset:13024
	s_waitcnt lgkmcnt(1)
	v_mfma_f32_32x32x16_bf16 v[98:113], v[134:137], v[130:133], v[98:113]
	s_waitcnt lgkmcnt(0)
	v_mfma_f32_32x32x16_bf16 v[82:97], v[138:141], v[130:133], v[82:97]
	ds_read_b128 v[130:133], v245 offset:58624
	ds_read_b128 v[134:137], v32 offset:13056
	s_waitcnt lgkmcnt(1)
	v_mfma_f32_32x32x16_bf16 v[98:113], v[130:133], v[126:129], v[98:113]
	s_waitcnt lgkmcnt(0)
	v_mfma_f32_32x32x16_bf16 v[82:97], v[134:137], v[126:129], v[82:97]
	ds_read_b128 v[126:129], v245 offset:58656
	ds_read_b128 v[130:133], v32 offset:13088
	s_waitcnt lgkmcnt(1)
	v_mfma_f32_32x32x16_bf16 v[98:113], v[126:129], v[122:125], v[98:113]
	s_waitcnt lgkmcnt(0)
	v_mfma_f32_32x32x16_bf16 v[82:97], v[130:133], v[122:125], v[82:97]
	ds_read_b128 v[122:125], v245 offset:58688
	ds_read_b128 v[126:129], v32 offset:13120
	s_waitcnt lgkmcnt(1)
	v_mfma_f32_32x32x16_bf16 v[98:113], v[122:125], v[118:121], v[98:113]
	s_waitcnt lgkmcnt(0)
	v_mfma_f32_32x32x16_bf16 v[82:97], v[126:129], v[118:121], v[82:97]
	ds_read_b128 v[118:121], v245 offset:58720
	ds_read_b128 v[122:125], v32 offset:13152
	v_exp_f32_e32 v32, v66
	v_add_f32_e32 v66, 0, v190
	v_add_f32_e32 v66, v209, v66
	v_add_f32_e32 v66, v191, v66
	v_add_f32_e32 v66, v208, v66
	v_add_f32_e32 v66, v192, v66
	v_add_f32_e32 v66, v207, v66
	v_add_f32_e32 v66, v193, v66
	v_add_f32_e32 v66, v206, v66
	v_add_f32_e32 v66, v198, v66
	v_add_f32_e32 v66, v205, v66
	v_add_f32_e32 v66, v199, v66
	v_add_f32_e32 v66, v204, v66
	v_add_f32_e32 v66, v200, v66
	v_add_f32_e32 v66, v202, v66
	s_waitcnt lgkmcnt(1)
	v_mfma_f32_32x32x16_bf16 v[98:113], v[118:121], v[114:117], v[98:113]
	v_add_f32_e32 v66, v201, v66
	v_add_f32_e32 v66, v203, v66
	v_add_f32_e32 v66, v66, v32
	v_add_f32_e32 v66, v67, v66
	v_exp_f32_e32 v118, v73
	v_exp_f32_e32 v119, v74
	v_exp_f32_e32 v120, v75
	s_waitcnt lgkmcnt(0)
; #define SBAR() __builtin_amdgcn_sched_barrier(0)
; #define PVD0(...) do { if constexpr (PV_PIPE != 0) pv_d0_pipe(__VA_ARGS__); else pv_d0(__VA_ARGS__); } while (0)
; #define RESC(a) do { if constexpr (!NOMAX) if (__any((a) < 1.f)) { if (hi == 0) al_l[r32] = (a); asm volatile("s_waitcnt lgkmcnt(0)" ::: "memory"); \
;     _Pragma("unroll") for (int d = 0; d < 4; ++d) _Pragma("unroll") for (int r = 0; r < 16; ++r) o[d][r] *= al_l[crow(r, hi)]; } } while (0)
; #define RESC(a) do { if (__any((a) < 1.f)) { if (hi == 0) al_l[r32] = (a); asm volatile("s_waitcnt lgkmcnt(0)" ::: "memory"); \
;     _Pragma("unroll") for (int d = 0; d < 4; ++d) _Pragma("unroll") for (int r = 0; r < 16; ++r) o[d][r] *= al_l[crow(r, hi)]; } } while (0)
; template <int DQK, int SDEPTH, int QL, bool NOMAX, int ldq, int ldk, int ldv, int ldo> ...
;     ...
;     SBAR(); qkt<DQK, QL>(pB0, pB1, K_lds + SHM_K, qr, qpark, r32, hi);
;     finishSM(pA0, pA1, alA, l_reg, pa0, pa1, pa2, pa3); SBAR();
;     PVD0(o, vb0, pa0, pa1, pa2, pa3); if constexpr (NOMAX) { partialSM_nm(pB0); alB = 1.f; } else partialSM(pB0, pB1, m_reg, mnB, alB, C, thr_raw);
;     __syncthreads(); RESC(alB);
;     finishSM(pB0, pB1, alB, l_reg, pa0, pa1, pa2, pa3); SBAR();
	v_mfma_f32_32x32x16_bf16 v[82:97], v[122:125], v[114:117], v[82:97]
	v_exp_f32_e32 v114, v68
	v_exp_f32_e32 v115, v70
	v_exp_f32_e32 v116, v71
	v_exp_f32_e32 v117, v72
	v_add_f32_e32 v66, v114, v66
	v_add_f32_e32 v66, v69, v66
	v_add_f32_e32 v66, v115, v66
	v_add_f32_e32 v66, v116, v66
	v_exp_f32_e32 v121, v76
	v_add_f32_e32 v66, v117, v66
	v_exp_f32_e32 v122, v77
	v_add_f32_e32 v66, v118, v66
	v_exp_f32_e32 v123, v78
	v_add_f32_e32 v66, v119, v66
	v_exp_f32_e32 v124, v79
	v_add_f32_e32 v66, v120, v66
	v_exp_f32_e32 v125, v80
	v_add_f32_e32 v66, v121, v66
	v_exp_f32_e32 v126, v81
	v_add_f32_e32 v66, v122, v66
	v_add_f32_e32 v66, v123, v66
	v_add_f32_e32 v66, v124, v66
	v_add_f32_e32 v66, v125, v66
	v_add_f32_e32 v66, v126, v66
	v_mov_b32_e32 v68, v66
	s_nop 1
	v_permlane32_swap_b32_e32 v66, v68
	v_cvt_pk_bf16_f32 v70, v190, v209
	v_cvt_pk_bf16_f32 v71, v191, v208
	v_cvt_pk_bf16_f32 v72, v192, v207
	v_cvt_pk_bf16_f32 v73, v193, v206
	v_cvt_pk_bf16_f32 v74, v198, v205
	v_cvt_pk_bf16_f32 v75, v199, v204
	v_cvt_pk_bf16_f32 v76, v200, v202
	v_cvt_pk_bf16_f32 v77, v201, v203
	v_cvt_pk_bf16_f32 v78, v32, v67
	v_cvt_pk_bf16_f32 v79, v114, v69
	v_cvt_pk_bf16_f32 v80, v115, v116
	v_cvt_pk_bf16_f32 v81, v117, v118
	v_cvt_pk_bf16_f32 v114, v119, v120
	v_cvt_pk_bf16_f32 v115, v121, v122
	v_cvt_pk_bf16_f32 v116, v123, v124
	v_cvt_pk_bf16_f32 v117, v125, v126
	s_nop 0
	v_permlane32_swap_b32_e32 v70, v72
	v_permlane32_swap_b32_e32 v71, v73
	v_permlane32_swap_b32_e32 v74, v76
	v_permlane32_swap_b32_e32 v75, v77
	v_permlane32_swap_b32_e32 v78, v80
	v_permlane32_swap_b32_e32 v79, v81
	v_permlane32_swap_b32_e32 v114, v116
	v_permlane32_swap_b32_e32 v115, v117
	ds_read_b64_tr_b16 v[118:119], v244 offset:0
	ds_read_b64_tr_b16 v[120:121], v244 offset:0x800
	ds_read_b64_tr_b16 v[122:123], v244 offset:0x1000
	ds_read_b64_tr_b16 v[124:125], v244 offset:0x1800
	ds_read_b64_tr_b16 v[126:127], v244 offset:0x2000
	ds_read_b64_tr_b16 v[128:129], v244 offset:0x2800
	ds_read_b64_tr_b16 v[130:131], v244 offset:0x3000
	ds_read_b64_tr_b16 v[132:133], v244 offset:0x3800
	s_waitcnt lgkmcnt(0)
	s_nop 0
	v_mfma_f32_32x32x16_bf16 v[50:65], v[70:73], v[118:121], v[50:65]
	ds_read_b64_tr_b16 v[118:119], v244 offset:0x200
	ds_read_b64_tr_b16 v[120:121], v244 offset:0xa00
	v_mfma_f32_32x32x16_bf16 v[50:65], v[74:77], v[122:125], v[50:65]
	ds_read_b64_tr_b16 v[122:123], v244 offset:0x1200
	ds_read_b64_tr_b16 v[124:125], v244 offset:0x1a00
	v_mfma_f32_32x32x16_bf16 v[50:65], v[78:81], v[126:129], v[50:65]
	ds_read_b64_tr_b16 v[126:127], v244 offset:0x2200
	ds_read_b64_tr_b16 v[128:129], v244 offset:0x2a00
	v_mfma_f32_32x32x16_bf16 v[50:65], v[114:117], v[130:133], v[50:65]
	ds_read_b64_tr_b16 v[130:131], v244 offset:0x3200
	ds_read_b64_tr_b16 v[132:133], v244 offset:0x3a00
	s_waitcnt lgkmcnt(0)
	v_mfma_f32_32x32x16_bf16 v[34:49], v[70:73], v[118:121], v[34:49]
	ds_read_b64_tr_b16 v[118:119], v244 offset:0x400
	ds_read_b64_tr_b16 v[120:121], v244 offset:0xc00
	v_mfma_f32_32x32x16_bf16 v[34:49], v[74:77], v[122:125], v[34:49]
	ds_read_b64_tr_b16 v[122:123], v244 offset:0x1400
	ds_read_b64_tr_b16 v[124:125], v244 offset:0x1c00
	v_mfma_f32_32x32x16_bf16 v[34:49], v[78:81], v[126:129], v[34:49]
	ds_read_b64_tr_b16 v[126:127], v244 offset:0x2400
	ds_read_b64_tr_b16 v[128:129], v244 offset:0x2c00
	v_mfma_f32_32x32x16_bf16 v[34:49], v[114:117], v[130:133], v[34:49]
	ds_read_b64_tr_b16 v[130:131], v244 offset:0x3400
	ds_read_b64_tr_b16 v[132:133], v244 offset:0x3c00
	s_waitcnt lgkmcnt(0)
	v_mfma_f32_32x32x16_bf16 v[16:31], v[70:73], v[118:121], v[16:31]
	ds_read_b64_tr_b16 v[118:119], v244 offset:0x600
	ds_read_b64_tr_b16 v[120:121], v244 offset:0xe00
	v_mfma_f32_32x32x16_bf16 v[16:31], v[74:77], v[122:125], v[16:31]
	ds_read_b64_tr_b16 v[122:123], v244 offset:0x1600
	ds_read_b64_tr_b16 v[124:125], v244 offset:0x1e00
	v_mfma_f32_32x32x16_bf16 v[16:31], v[78:81], v[126:129], v[16:31]
	ds_read_b64_tr_b16 v[126:127], v244 offset:0x2600
	ds_read_b64_tr_b16 v[128:129], v244 offset:0x2e00
	v_mfma_f32_32x32x16_bf16 v[16:31], v[114:117], v[130:133], v[16:31]
	ds_read_b64_tr_b16 v[130:131], v244 offset:0x3600
	ds_read_b64_tr_b16 v[132:133], v244 offset:0x3e00
	s_waitcnt lgkmcnt(0)
	v_mfma_f32_32x32x16_bf16 v[0:15], v[70:73], v[118:121], v[0:15]
	v_exp_f32_e32 v32, v98
	v_exp_f32_e32 v70, v99
	v_exp_f32_e32 v71, v100
	v_exp_f32_e32 v72, v101
	v_exp_f32_e32 v73, v102
	v_add_f32_e32 v67, 0, v32
	v_add_f32_e32 v67, v70, v67
	v_mfma_f32_32x32x16_bf16 v[0:15], v[74:77], v[122:125], v[0:15]
	v_exp_f32_e32 v74, v103
	v_exp_f32_e32 v75, v104
	v_add_f32_e32 v67, v71, v67
	v_exp_f32_e32 v76, v105
	v_add_f32_e32 v67, v72, v67
	v_exp_f32_e32 v77, v106
	v_add_f32_e32 v67, v73, v67
	v_mfma_f32_32x32x16_bf16 v[0:15], v[78:81], v[126:129], v[0:15]
	v_exp_f32_e32 v78, v107
	v_add_f32_e32 v67, v74, v67
	v_exp_f32_e32 v79, v108
	v_add_f32_e32 v67, v75, v67
	v_exp_f32_e32 v80, v109
	v_add_f32_e32 v67, v76, v67
	v_exp_f32_e32 v81, v110
	v_add_f32_e32 v67, v77, v67
	v_exp_f32_e32 v98, v111
	v_add_f32_e32 v67, v78, v67
	v_exp_f32_e32 v99, v112
	v_add_f32_e32 v67, v79, v67
	v_exp_f32_e32 v100, v113
	v_add_f32_e32 v67, v80, v67
	v_exp_f32_e32 v82, v82
	v_add_f32_e32 v67, v81, v67
	v_exp_f32_e32 v83, v83
	v_add_f32_e32 v67, v98, v67
	v_exp_f32_e32 v84, v84
	v_add_f32_e32 v67, v99, v67
	v_exp_f32_e32 v85, v85
	v_add_f32_e32 v67, v100, v67
	v_exp_f32_e32 v86, v86
	v_add_f32_e32 v67, v82, v67
	v_exp_f32_e32 v87, v87
	v_add_f32_e32 v67, v83, v67
	v_exp_f32_e32 v88, v88
	v_add_f32_e32 v67, v84, v67
	v_exp_f32_e32 v89, v89
	v_add_f32_e32 v67, v85, v67
	v_exp_f32_e32 v90, v90
	v_add_f32_e32 v67, v86, v67
	v_exp_f32_e32 v91, v91
	v_add_f32_e32 v67, v87, v67
	v_exp_f32_e32 v92, v92
	v_add_f32_e32 v67, v88, v67
	v_exp_f32_e32 v93, v93
	v_add_f32_e32 v67, v89, v67
	v_exp_f32_e32 v94, v94
	v_add_f32_e32 v67, v90, v67
	v_exp_f32_e32 v95, v95
	v_add_f32_e32 v67, v91, v67
	v_mfma_f32_32x32x16_bf16 v[0:15], v[114:117], v[130:133], v[0:15]
	v_exp_f32_e32 v96, v96
	v_add_f32_e32 v67, v92, v67
	v_exp_f32_e32 v97, v97
	v_add_f32_e32 v67, v93, v67
	v_add_f32_e32 v67, v94, v67
	v_add_f32_e32 v67, v95, v67
	v_add_f32_e32 v67, v96, v67
	v_add_f32_e32 v67, v97, v67
	v_mov_b32_e32 v69, v67
	s_barrier
; template <int M> __device__ __forceinline__ float swz_xor(float v) { return __int_as_float(__builtin_amdgcn_ds_swizzle(__float_as_int(v), (M << 10) | 0x1f)); }
; #define SBAR() __builtin_amdgcn_sched_barrier(0)
; __device__ __forceinline__ int crow(int r, int hi) { return (r & 3) + 8 * (r >> 2) + 4 * hi; }
; template <int D0> __device__ __forceinline__ void pv_one(f32x16& od, int vb, bf16x8 pa0, bf16x8 pa1, bf16x8 pa2, bf16x8 pa3) {
;     const s16x4 l0 = tr_read<v_rd_off(D0, 0, 0)>(vb), h0 = tr_read<v_rd_off(D0, 0, 1)>(vb), l1 = tr_read<v_rd_off(D0, 1, 0)>(vb), h1 = tr_read<v_rd_off(D0, 1, 1)>(vb);
;     const s16x4 l2 = tr_read<v_rd_off(D0, 2, 0)>(vb), h2 = tr_read<v_rd_off(D0, 2, 1)>(vb), l3 = tr_read<v_rd_off(D0, 3, 0)>(vb), h3 = tr_read<v_rd_off(D0, 3, 1)>(vb);
;     asm volatile("s_waitcnt lgkmcnt(0)" ::: "memory"); SBAR();
;     ...
;     od = __builtin_amdgcn_mfma_f32_32x32x16_bf16(pa0, PK(l0, h0), od, 0, 0, 0);
;     od = __builtin_amdgcn_mfma_f32_32x32x16_bf16(pa1, PK(l1, h1), od, 0, 0, 0);
;     od = __builtin_amdgcn_mfma_f32_32x32x16_bf16(pa2, PK(l2, h2), od, 0, 0, 0);
;     od = __builtin_amdgcn_mfma_f32_32x32x16_bf16(pa3, PK(l3, h3), od, 0, 0, 0);
;     ...
; }
; __device__ __forceinline__ void pv_d0(f32x16* o, int vb, bf16x8 pa0, bf16x8 pa1, bf16x8 pa2, bf16x8 pa3) {
;     pv_one<0>(o[0], vb, pa0, pa1, pa2, pa3); pv_one<1>(o[1], vb, pa0, pa1, pa2, pa3); pv_one<2>(o[2], vb, pa0, pa1, pa2, pa3); pv_one<3>(o[3], vb, pa0, pa1, pa2, pa3);
; template <int DQK, int SDEPTH, int QL, bool NOMAX, int ldq, int ldk, int ldv, int ldo> ...
;     ...
;     PVD0(o, vb0 + SHM_V, pa0, pa1, pa2, pa3);
;     if (ATT_PRIO) __builtin_amdgcn_s_setprio(0);
;     if (hi == 0) li_l[r32] = l_reg; asm volatile("s_waitcnt lgkmcnt(0)" ::: "memory");
;     float rli[16];
; #pragma unroll
;     for (int r = 0; r < 16; ++r) rli[r] = __builtin_amdgcn_rcpf(li_l[crow(r, hi)]);
;     bf16_t* Ow = Ob + (size_t)(wid * QBLK) * ldo + (r32 & ~1);
;     const bool odd = (r32 & 1) != 0;
; #pragma unroll
;     for (int r = 0; r < 16; r += 2) { const int orow = crow(r, hi) + (odd ? 1 : 0);
; #pragma unroll
;         for (int d0 = 0; d0 < 4; ++d0) { const float a = o[d0][r] * rli[r], b = o[d0][r + 1] * rli[r + 1];
;             const float recv = swz_xor<1>(odd ? a : b);
;             const unsigned w = odd ? cvtpk(recv, b) : cvtpk(a, recv);
	s_nop 0
	v_permlane32_swap_b32_e32 v67, v69
	v_cvt_pk_bf16_f32 v70, v32, v70
	v_cvt_pk_bf16_f32 v71, v71, v72
	v_cvt_pk_bf16_f32 v72, v73, v74
	v_cvt_pk_bf16_f32 v73, v75, v76
	v_cvt_pk_bf16_f32 v74, v77, v78
	v_cvt_pk_bf16_f32 v75, v79, v80
	v_cvt_pk_bf16_f32 v76, v81, v98
	v_cvt_pk_bf16_f32 v77, v99, v100
	v_cvt_pk_bf16_f32 v78, v82, v83
	v_cvt_pk_bf16_f32 v79, v84, v85
	v_cvt_pk_bf16_f32 v80, v86, v87
	v_cvt_pk_bf16_f32 v81, v88, v89
	v_cvt_pk_bf16_f32 v82, v90, v91
	v_cvt_pk_bf16_f32 v83, v92, v93
	v_cvt_pk_bf16_f32 v84, v94, v95
	v_cvt_pk_bf16_f32 v85, v96, v97
	s_nop 0
	v_permlane32_swap_b32_e32 v70, v72
	v_permlane32_swap_b32_e32 v71, v73
	v_permlane32_swap_b32_e32 v74, v76
	v_permlane32_swap_b32_e32 v75, v77
	v_permlane32_swap_b32_e32 v78, v80
	v_permlane32_swap_b32_e32 v79, v81
	v_permlane32_swap_b32_e32 v82, v84
	v_permlane32_swap_b32_e32 v83, v85
	ds_read_b64_tr_b16 v[86:87], v242 offset:0
	ds_read_b64_tr_b16 v[88:89], v242 offset:0x800
	ds_read_b64_tr_b16 v[90:91], v242 offset:0x1000
	ds_read_b64_tr_b16 v[92:93], v242 offset:0x1800
	ds_read_b64_tr_b16 v[94:95], v242 offset:0x2000
	ds_read_b64_tr_b16 v[96:97], v242 offset:0x2800
	ds_read_b64_tr_b16 v[98:99], v242 offset:0x3000
	ds_read_b64_tr_b16 v[100:101], v242 offset:0x3800
	s_waitcnt lgkmcnt(0)
	s_nop 0
	v_mfma_f32_32x32x16_bf16 v[50:65], v[70:73], v[86:89], v[50:65]
	ds_read_b64_tr_b16 v[86:87], v242 offset:0x200
	ds_read_b64_tr_b16 v[88:89], v242 offset:0xa00
	v_mfma_f32_32x32x16_bf16 v[50:65], v[74:77], v[90:93], v[50:65]
	ds_read_b64_tr_b16 v[90:91], v242 offset:0x1200
	ds_read_b64_tr_b16 v[92:93], v242 offset:0x1a00
	v_mfma_f32_32x32x16_bf16 v[50:65], v[78:81], v[94:97], v[50:65]
	ds_read_b64_tr_b16 v[94:95], v242 offset:0x2200
	ds_read_b64_tr_b16 v[96:97], v242 offset:0x2a00
	v_mfma_f32_32x32x16_bf16 v[50:65], v[82:85], v[98:101], v[50:65]
	ds_read_b64_tr_b16 v[98:99], v242 offset:0x3200
	ds_read_b64_tr_b16 v[100:101], v242 offset:0x3a00
	s_waitcnt lgkmcnt(0)
	v_mfma_f32_32x32x16_bf16 v[34:49], v[70:73], v[86:89], v[34:49]
	ds_read_b64_tr_b16 v[86:87], v242 offset:0x400
	ds_read_b64_tr_b16 v[88:89], v242 offset:0xc00
	v_mfma_f32_32x32x16_bf16 v[34:49], v[74:77], v[90:93], v[34:49]
	ds_read_b64_tr_b16 v[90:91], v242 offset:0x1400
	ds_read_b64_tr_b16 v[92:93], v242 offset:0x1c00
	v_mfma_f32_32x32x16_bf16 v[34:49], v[78:81], v[94:97], v[34:49]
	ds_read_b64_tr_b16 v[94:95], v242 offset:0x2400
	ds_read_b64_tr_b16 v[96:97], v242 offset:0x2c00
	v_mfma_f32_32x32x16_bf16 v[34:49], v[82:85], v[98:101], v[34:49]
	ds_read_b64_tr_b16 v[98:99], v242 offset:0x3400
	ds_read_b64_tr_b16 v[100:101], v242 offset:0x3c00
	s_waitcnt lgkmcnt(0)
	v_mfma_f32_32x32x16_bf16 v[16:31], v[70:73], v[86:89], v[16:31]
	ds_read_b64_tr_b16 v[86:87], v242 offset:0x600
	ds_read_b64_tr_b16 v[88:89], v242 offset:0xe00
	v_mfma_f32_32x32x16_bf16 v[16:31], v[74:77], v[90:93], v[16:31]
	ds_read_b64_tr_b16 v[90:91], v242 offset:0x1600
	ds_read_b64_tr_b16 v[92:93], v242 offset:0x1e00
	v_mfma_f32_32x32x16_bf16 v[16:31], v[78:81], v[94:97], v[16:31]
	ds_read_b64_tr_b16 v[94:95], v242 offset:0x2600
	ds_read_b64_tr_b16 v[96:97], v242 offset:0x2e00
	v_mfma_f32_32x32x16_bf16 v[16:31], v[82:85], v[98:101], v[16:31]
	ds_read_b64_tr_b16 v[98:99], v242 offset:0x3600
	ds_read_b64_tr_b16 v[100:101], v242 offset:0x3e00
	s_waitcnt lgkmcnt(0)
	v_mfma_f32_32x32x16_bf16 v[0:15], v[70:73], v[86:89], v[0:15]
	v_mfma_f32_32x32x16_bf16 v[0:15], v[74:77], v[90:93], v[0:15]
	v_mfma_f32_32x32x16_bf16 v[0:15], v[78:81], v[94:97], v[0:15]
	v_mfma_f32_32x32x16_bf16 v[0:15], v[82:85], v[98:101], v[0:15]
	s_setprio 0
	v_cmp_gt_u32_e32 vcc, 32, v241
	s_and_saveexec_b64 s[4:5], vcc
	v_pk_add_f32 v[66:67], v[66:67], v[68:69]
	v_lshl_add_u32 v32, v240, 2, s48
	v_add_f32_e32 v66, v243, v66
	v_add_f32_e32 v66, v66, v67
	ds_write_b32 v32, v66
	s_or_b64 exec, exec, s[4:5]
	s_waitcnt lgkmcnt(0)
	v_lshl_add_u32 v32, v233, 4, s48
	ds_read_b128 v[78:81], v32
	ds_read_b128 v[74:77], v32 offset:32
	v_and_b32_e32 v82, 1, v232
	ds_read_b128 v[70:73], v32 offset:64
	ds_read_b128 v[66:69], v32 offset:96
	v_cmp_eq_u32_e64 s[6:7], 0, v82
	s_waitcnt lgkmcnt(3)
	v_rcp_f32_e32 v78, v78
	v_rcp_f32_e32 v79, v79
	v_cmp_eq_u32_e64 s[4:5], 1, v82
	v_mul_f32_e32 v32, v50, v78
	v_mul_f32_e32 v51, v51, v79
	v_cndmask_b32_e64 v50, v32, v51, s[6:7]
	ds_swizzle_b32 v50, v50 offset:swizzle(SWAP,1)
	s_mov_b64 s[14:15], exec
	s_and_b64 s[20:21], s[14:15], s[4:5]
	s_xor_b64 s[14:15], s[20:21], s[14:15]
	v_mov_b64_e32 v[244:245], 0x210
	v_mov_b64_e32 v[246:247], 0x20f
	s_mov_b64 exec, s[20:21]
	s_cbranch_execz .LBB0_2017
	s_waitcnt lgkmcnt(0)
	v_cvt_pk_bf16_f32 v83, v50, v51

; __device__ __forceinline__ int v_st(int k, int c) { const int kk = (k & ~0xC) | ((k & 4) << 1) | ((k & 8) >> 1); return ((kk >> 3) * 4 + (c >> 5)) * 512 + ((kk & 7) * 32 + (c & 31)) * 2; }
; __device__ __forceinline__ int v_rd_base(int lane) { return ((lane & 3) << 3) | (((lane >> 2) & 3) << 6) | (((lane >> 4) & 1) << 5) | (((lane >> 5) & 1) << 8); }
; #define SLOAD(i, k0) do { sv0[i] = *reinterpret_cast<const bf16x8*>(&Vh[(size_t)((k0) + sr) * ldv + sc]); sv1[i] = *reinterpret_cast<const bf16x8*>(&Vh[(size_t)((k0) + 32 + sr) * ldv + sc]); \
;     _Pragma("unroll") for (int _q = 0; _q < NKP; ++_q) sk[i][_q] = *reinterpret_cast<const bf16x8*>(&Kh[(size_t)(k0) * ldk + koff[_q]]); } while (0)
; template <int DQK, int SDEPTH, int QL, bool NOMAX, int ldq, int ldk, int ldv, int ldo> ...
;     ...
;     const bf16_t* Qw = Qb + (size_t)(wid * QBLK + r32) * ldq + hi * 8;
; #pragma unroll
;     for (int d0 = 0; d0 < NQR; ++d0) qr[d0] = *reinterpret_cast<const bf16x8*>(Qw + d0 * 16);
; #pragma unroll
;     for (int d0 = 0; d0 < QL; ++d0) *(bf16x8*)(qpark + d0 * 1024) = *reinterpret_cast<const bf16x8*>(Qw + (NQR + d0) * 16);
;     const int sr = tid >> 4, sc = (tid & 15) * 8, vst0 = v_st(sr, sc), vst1 = v_st(32 + sr, sc);
;     int koff[NKP], klds[NKP];
; #pragma unroll
;     for (int i = 0; i < NKP; ++i) { const int row = tid >> 3, c8 = (tid & 7) + 8 * i; koff[i] = row * ldk + c8 * 8; klds[i] = row * RS + c8 * 16; }
;     const int vb0 = (int)(uintptr_t)V_lds + v_rd_base(lane);
;     bf16x8 sv0[SDEPTH], sv1[SDEPTH], sk[SDEPTH][NKP];
;     ...
;     f32x16 pA0, pA1, pB0, pB1; float mnA, mnB, alA, alB; bf16x8 pa0, pa1, pa2, pa3; const int NT = seq / KVBLK;
;     if (ATT_PRIO && wid >= 4) __builtin_amdgcn_s_setprio(1);
;     constexpr int SE = 0, SO = SDEPTH - 1;
;     SLOAD(SE, 0); asm volatile("s_waitcnt vmcnt(0)" ::: "memory"); SWRITE(0, SE); __syncthreads();
;     qkt<DQK, QL>(pA0, pA1, K_lds, qr, qpark, r32, hi); if constexpr (NOMAX) { partialSM_nm(pA0); alA = 1.f; } else partialSM(pA0, pA1, m_reg, mnA, alA, C, thr_raw);
;     SLOAD(SO, KVBLK); if constexpr (SDEPTH == 2) { if (2 < NT) SLOAD(SE, 2 * KVBLK); }
;     SWAIT(); SWRITE(1, SO); __syncthreads();
.LBB0_2297:
	v_add_u32_e32 v0, s39, v162
	v_ashrrev_i32_e32 v14, 4, v0
	v_lshlrev_b32_e32 v18, 3, v162
	v_ashrrev_i32_e32 v15, 31, v14
	v_and_b32_e32 v1, 0x78, v18
	v_add_u32_e32 v16, 32, v14
	v_lshlrev_b64 v[82:83], 11, v[14:15]
	v_and_b32_e32 v20, 7, v162
	v_lshl_add_u64 v[2:3], s[26:27], 0, v[82:83]
	v_lshlrev_b32_e32 v4, 1, v1
	v_mov_b32_e32 v5, v33
	v_ashrrev_i32_e32 v17, 31, v16
	v_ashrrev_i32_e32 v19, 3, v0
	v_lshlrev_b32_e32 v0, 3, v20
	v_lshl_add_u64 v[54:55], v[2:3], 0, v[4:5]
	v_lshlrev_b64 v[2:3], 11, v[16:17]
	v_lshl_or_b32 v0, v19, 10, v0
	v_lshl_add_u64 v[2:3], s[26:27], 0, v[2:3]
	v_lshl_add_u64 v[6:7], v[2:3], 0, v[4:5]
	v_ashrrev_i32_e32 v1, 31, v0
	global_load_dwordx4 v[2:5], v[54:55], off
	s_nop 0
	global_load_dwordx4 v[6:9], v[6:7], off
	v_lshlrev_b64 v[30:31], 1, v[0:1]
	v_lshl_add_u64 v[56:57], s[24:25], 0, v[30:31]
	global_load_dwordx4 v[10:13], v[56:57], off
	s_movk_i32 s4, 0x90
	v_mad_u32_u24 v15, v164, s4, 0
	v_bfe_u32 v17, v18, 5, 2
	v_add_u32_e32 v168, v15, v32
	v_and_b32_e32 v15, 0xfffff0, v14
	v_lshlrev_b32_e32 v18, 1, v14
	v_lshrrev_b32_e32 v21, 1, v14
	v_and_b32_e32 v14, 3, v14
	v_mul_lo_u32 v19, v19, s4
	v_and_or_b32 v15, v18, 8, v15
	v_and_or_b32 v14, v21, 4, v14
	v_and_b32_e32 v18, 0xfffff0, v16
	v_lshlrev_b32_e32 v16, 1, v16
	v_lshl_add_u32 v19, v20, 4, v19
	v_lshrrev_b32_e32 v15, 1, v15
	v_lshlrev_b32_e32 v20, 6, v14
	v_and_or_b32 v14, v16, 8, v18
	v_lshlrev_b32_e32 v1, 4, v162
	v_or_b32_e32 v15, v15, v17
	v_lshrrev_b32_e32 v14, 1, v14
	v_and_b32_e32 v1, 48, v1
	v_add_u32_e32 v170, 0, v19
	v_lshlrev_b32_e32 v18, 9, v15
	v_or_b32_e32 v19, v14, v17
	v_or3_b32 v18, v18, v20, v1
	v_lshlrev_b32_e32 v19, 9, v19
	v_or3_b32 v1, v19, v20, v1
	v_add_u32_e32 v171, 0, v18
	s_waitcnt vmcnt(0)
	v_add_u32_e32 v172, 0, v1
	v_add_co_u32_e32 v14, vcc, s66, v54
	s_mov_b32 s4, 0x30000
	s_nop 0
	v_addc_co_u32_e32 v15, vcc, 0, v55, vcc
	v_add_co_u32_e32 v16, vcc, s4, v54
	v_and_b32_e32 v46, 15, v162
	s_nop 0
	v_addc_co_u32_e32 v17, vcc, 0, v55, vcc
	s_cmp_lg_u32 0, -1
	v_lshlrev_b32_e32 v32, 4, v46
	s_cselect_b32 s14, 0, 0
	s_add_i32 s7, s53, -3
	s_add_i32 s15, s14, 0x4000
	s_add_u32 s4, s0, s20
	s_addc_u32 s5, s1, s21
	s_mov_b32 s21, 0x40000
	v_and_b32_e32 v165, 63, v162
	s_mov_b32 s20, 0x50000
	v_lshlrev_b32_e32 v51, 4, v165
	v_lshlrev_b32_e32 v50, 3, v165
	v_lshlrev_b32_e32 v52, 1, v165
	v_and_b32_e32 v51, 0xc0, v51
	v_and_b32_e32 v52, 32, v52
	v_mov_b32_e32 v166, 0
	s_mov_b32 s6, 1
	v_mov_b32_e32 v0, 0
	v_mov_b32_e32 v1, v166
	v_lshl_add_u64 v[154:155], s[4:5], 0, v[30:31]
	v_mov_b32_e32 v30, v166
	v_mov_b32_e32 v31, v166
	s_waitcnt vmcnt(2)
	ds_write_b128 v171, v[2:5]
	s_waitcnt vmcnt(1)
	ds_write_b128 v172, v[6:9]
	s_waitcnt vmcnt(0)
	ds_write_b128 v170, v[10:13] offset:32768
	s_waitcnt lgkmcnt(0)
	s_barrier
	ds_read_b128 v[2:5], v168 offset:32768
	ds_read_b128 v[6:9], v168 offset:37376
	v_add_co_u32_e32 v10, vcc, s66, v56
	s_waitcnt lgkmcnt(0)
	v_mfma_f32_32x32x16_bf16 v[66:81], v[6:9], v[126:129], 0
	v_addc_co_u32_e32 v11, vcc, 0, v57, vcc
	global_load_dwordx4 v[34:37], v[14:15], off
	global_load_dwordx4 v[38:41], v[16:17], off
	global_load_dwordx4 v[42:45], v[10:11], off
	ds_read_b128 v[10:13], v168 offset:32800
	ds_read_b128 v[58:61], v168 offset:32832
	ds_read_b128 v[46:49], v168 offset:37408
	v_mov_b32_e32 v6, v166
	v_mfma_f32_32x32x16_bf16 v[14:29], v[2:5], v[126:129], 0
	v_mov_b32_e32 v2, v166
	v_mov_b32_e32 v3, v166
	v_mov_b32_e32 v4, v166
	v_mov_b32_e32 v5, v166
	v_mov_b32_e32 v7, v166
	v_mov_b32_e32 v8, v166
	v_mov_b32_e32 v9, v166
	s_waitcnt lgkmcnt(2)
	v_mfma_f32_32x32x16_bf16 v[14:29], v[10:13], v[122:125], v[14:29]
	v_mov_b32_e32 v10, v166
	v_mov_b32_e32 v11, v166
	v_mov_b32_e32 v12, v166
	v_mov_b32_e32 v13, v166
	s_waitcnt lgkmcnt(1)
	v_mfma_f32_32x32x16_bf16 v[14:29], v[58:61], v[118:121], v[14:29]
	v_add_co_u32_e32 v60, vcc, s21, v54
	v_lshl_add_u64 v[58:59], v[82:83], 0, s[22:23]
	s_nop 0
	v_addc_co_u32_e32 v61, vcc, 0, v55, vcc
	v_add_co_u32_e32 v54, vcc, s20, v54
	s_waitcnt lgkmcnt(0)
	v_mfma_f32_32x32x16_bf16 v[66:81], v[46:49], v[122:125], v[66:81]
	v_addc_co_u32_e32 v55, vcc, 0, v55, vcc
	v_and_b32_e32 v46, 0x100, v50
	v_and_or_b32 v47, v50, 24, v51
	v_add_co_u32_e32 v56, vcc, s21, v56
	v_or3_b32 v84, v47, v52, v46
	ds_read_b128 v[62:65], v168 offset:37440
	ds_read_b128 v[50:53], v168 offset:32864
	ds_read_b128 v[46:49], v168 offset:37472
	v_addc_co_u32_e32 v57, vcc, 0, v57, vcc
	global_load_dwordx4 v[130:133], v[60:61], off
	global_load_dwordx4 v[134:137], v[54:55], off
	global_load_dwordx4 v[138:141], v[56:57], off
	s_waitcnt lgkmcnt(2)
	v_mfma_f32_32x32x16_bf16 v[66:81], v[62:65], v[118:121], v[66:81]
	s_waitcnt vmcnt(3)
	v_add_u32_e32 v169, s14, v84
	v_add_u32_e32 v167, s15, v84
	v_mov_b32_e32 v54, v166
	v_mov_b32_e32 v55, v166
	v_mov_b32_e32 v56, v166
	v_mov_b32_e32 v57, v166
	s_waitcnt lgkmcnt(1)
	v_mfma_f32_32x32x16_bf16 v[14:29], v[50:53], v[114:117], v[14:29]
	v_lshl_add_u64 v[50:51], v[58:59], 0, v[32:33]
	v_lshl_add_u64 v[156:157], s[0:1], 0, v[50:51]
	s_waitcnt vmcnt(5)
	ds_write_b128 v171, v[34:37] offset:16384
	s_waitcnt vmcnt(4)
	ds_write_b128 v172, v[38:41] offset:16384
	s_waitcnt vmcnt(3)
	ds_write_b128 v170, v[42:45] offset:41984
	s_waitcnt lgkmcnt(3)
; #define SBAR() __builtin_amdgcn_sched_barrier(0)
; #define SLOAD(i, k0) do { sv0[i] = *reinterpret_cast<const bf16x8*>(&Vh[(size_t)((k0) + sr) * ldv + sc]); sv1[i] = *reinterpret_cast<const bf16x8*>(&Vh[(size_t)((k0) + 32 + sr) * ldv + sc]); \
;     _Pragma("unroll") for (int _q = 0; _q < NKP; ++_q) sk[i][_q] = *reinterpret_cast<const bf16x8*>(&Kh[(size_t)(k0) * ldk + koff[_q]]); } while (0)
; #define SWRITE(b, i) do { *(bf16x8*)(V_lds + (b) * SHM_V + vst0) = sv0[i]; *(bf16x8*)(V_lds + (b) * SHM_V + vst1) = sv1[i]; \
;     _Pragma("unroll") for (int _q = 0; _q < NKP; ++_q) *(bf16x8*)(K_lds + (b) * SHM_K + klds[_q]) = sk[i][_q]; } while (0)
; #define SWAIT() do { if constexpr (SDEPTH == 2) { if constexpr (NKP == 1) asm volatile("s_waitcnt vmcnt(3)" ::: "memory"); else if constexpr (NKP == 2) asm volatile("s_waitcnt vmcnt(4)" ::: "memory"); else asm volatile("s_waitcnt vmcnt(5)" ::: "memory"); } \
;     else asm volatile("s_waitcnt vmcnt(0)" ::: "memory"); } while (0)
; template <int DQK, int SDEPTH, int QL, bool NOMAX, int ldq, int ldk, int ldv, int ldo> ...
;     ...
;     qkt<DQK, QL>(pA0, pA1, K_lds, qr, qpark, r32, hi); if constexpr (NOMAX) { partialSM_nm(pA0); alA = 1.f; } else partialSM(pA0, pA1, m_reg, mnA, alA, C, thr_raw);
;     SLOAD(SO, KVBLK); if constexpr (SDEPTH == 2) { if (2 < NT) SLOAD(SE, 2 * KVBLK); }
;     SWAIT(); SWRITE(1, SO); __syncthreads();
;     for (int j = 1; j + 1 < NT; j += 2) {
;         SBAR(); qkt<DQK, QL>(pB0, pB1, K_lds + SHM_K, qr, qpark, r32, hi);
;         finishSM(pA0, pA1, alA, l_reg, pa0, pa1, pa2, pa3); SBAR();
;         SLOAD(SO, (j + SDEPTH) * KVBLK); SBAR();
;         PVD0(o, vb0, pa0, pa1, pa2, pa3); if constexpr (NOMAX) { partialSM_nm(pB0); alB = 1.f; } else partialSM(pB0, pB1, m_reg, mnB, alB, C, thr_raw);
;         __syncthreads(); SWAIT(); SWRITE(0, SE);
;         RESC(alB); __syncthreads();
;         SBAR(); qkt<DQK, QL>(pA0, pA1, K_lds, qr, qpark, r32, hi);
;         finishSM(pB0, pB1, alB, l_reg, pa0, pa1, pa2, pa3); SBAR();
;         if (SDEPTH == 1 || j + 3 < NT) SLOAD(SE, (j + 1 + SDEPTH) * KVBLK); SBAR();
;         PVD0(o, vb0 + SHM_V, pa0, pa1, pa2, pa3); if constexpr (NOMAX) { partialSM_nm(pA0); alA = 1.f; } else partialSM(pA0, pA1, m_reg, mnA, alA, C, thr_raw);
;         __syncthreads(); SWAIT(); SWRITE(1, SO);
;         RESC(alA); __syncthreads();
	v_mfma_f32_32x32x16_bf16 v[66:81], v[46:49], v[114:117], v[66:81]
	s_nop 1
	v_exp_f32_e32 v180, v14
	v_exp_f32_e32 v183, v15
	v_exp_f32_e32 v177, v16
	v_exp_f32_e32 v181, v17
	v_exp_f32_e32 v176, v18
	v_exp_f32_e32 v178, v19
	v_exp_f32_e32 v179, v20
	v_exp_f32_e32 v182, v21
	v_exp_f32_e32 v160, v22
	v_exp_f32_e32 v174, v23
	v_exp_f32_e32 v158, v24
	v_exp_f32_e32 v161, v25
	v_exp_f32_e32 v32, v26
	v_exp_f32_e32 v175, v27
	v_exp_f32_e32 v159, v28
	v_exp_f32_e32 v173, v29
	v_mov_b32_e32 v14, v166
	v_mov_b32_e32 v15, v166
	v_mov_b32_e32 v50, 0
	v_mov_b32_e32 v51, v166
	v_mov_b32_e32 v52, v166
	v_mov_b32_e32 v53, v166
	v_mov_b32_e32 v58, v166
	v_mov_b32_e32 v59, v166
	v_mov_b32_e32 v60, v166
	v_mov_b32_e32 v61, v166
	v_mov_b32_e32 v62, v166
	v_mov_b32_e32 v63, v166
	v_mov_b32_e32 v64, v166
	v_mov_b32_e32 v65, v166
	v_mov_b32_e32 v34, 0
	v_mov_b32_e32 v35, v166
	v_mov_b32_e32 v36, v166
	v_mov_b32_e32 v37, v166
	v_mov_b32_e32 v38, v166
	v_mov_b32_e32 v39, v166
	v_mov_b32_e32 v40, v166
	v_mov_b32_e32 v41, v166
	v_mov_b32_e32 v42, v166
	v_mov_b32_e32 v43, v166
	v_mov_b32_e32 v44, v166
	v_mov_b32_e32 v45, v166
	v_mov_b32_e32 v46, v166
	v_mov_b32_e32 v47, v166
	v_mov_b32_e32 v48, v166
	v_mov_b32_e32 v49, v166
	v_mov_b32_e32 v16, 0
	v_mov_b32_e32 v17, v166
	v_mov_b32_e32 v18, v166
	v_mov_b32_e32 v19, v166
	v_mov_b32_e32 v20, v166
	v_mov_b32_e32 v21, v166
	v_mov_b32_e32 v22, v166
	v_mov_b32_e32 v23, v166
	v_mov_b32_e32 v24, v166
	v_mov_b32_e32 v25, v166
	v_mov_b32_e32 v26, v166
	v_mov_b32_e32 v27, v166
	v_mov_b32_e32 v28, v166
	v_mov_b32_e32 v29, v166
	s_mov_b64 s[14:15], 0x40000
	v_readfirstlane_b32 s98, v156
	v_readfirstlane_b32 s99, v157
	v_readfirstlane_b32 s100, v154
	v_readfirstlane_b32 s101, v155
	s_nop 1
	v_subrev_u32_e32 v224, s98, v156
	v_subrev_u32_e32 v226, s100, v154
	v_add_u32_e32 v225, 0x10000, v224
	s_add_u32 s98, s98, s18
	s_addc_u32 s99, s99, s19
	s_add_u32 s100, s100, s18
	s_addc_u32 s101, s101, s19
	s_add_u32 s98, s98, 0x42d7c000
	s_addc_u32 s99, s99, 0
	s_add_u32 s100, s100, 0x40c7c000
	s_addc_u32 s101, s101, 0
	s_waitcnt lgkmcnt(0)
	s_barrier
	s_branch .LBB0_2299
.LBB0_2298:
	v_add_f32_e32 v158, v166, v184
	s_add_i32 s6, s6, 2
	v_add_f32_e32 v166, v158, v32
	ds_read_b64_tr_b16 v[158:159], v167 offset:0
	ds_read_b64_tr_b16 v[160:161], v167 offset:0x800
	ds_read_b64_tr_b16 v[174:175], v167 offset:0x1000
	ds_read_b64_tr_b16 v[176:177], v167 offset:0x1800
	ds_read_b64_tr_b16 v[178:179], v167 offset:0x2000
	ds_read_b64_tr_b16 v[180:181], v167 offset:0x2800
	ds_read_b64_tr_b16 v[182:183], v167 offset:0x3000
	ds_read_b64_tr_b16 v[184:185], v167 offset:0x3800
	s_waitcnt lgkmcnt(6)
	s_nop 0
	v_mfma_f32_32x32x16_bf16 v[0:15], v[82:85], v[158:161], v[0:15]
	ds_read_b64_tr_b16 v[158:159], v167 offset:0x200
	ds_read_b64_tr_b16 v[160:161], v167 offset:0xa00
	s_waitcnt lgkmcnt(6)
	v_mfma_f32_32x32x16_bf16 v[0:15], v[86:89], v[174:177], v[0:15]
	ds_read_b64_tr_b16 v[174:175], v167 offset:0x1200
	ds_read_b64_tr_b16 v[176:177], v167 offset:0x1a00
	s_waitcnt lgkmcnt(6)
	v_mfma_f32_32x32x16_bf16 v[0:15], v[90:93], v[178:181], v[0:15]
	ds_read_b64_tr_b16 v[178:179], v167 offset:0x2200
	ds_read_b64_tr_b16 v[180:181], v167 offset:0x2a00
	s_waitcnt lgkmcnt(6)
	v_mfma_f32_32x32x16_bf16 v[0:15], v[94:97], v[182:185], v[0:15]
	ds_read_b64_tr_b16 v[182:183], v167 offset:0x3200
	ds_read_b64_tr_b16 v[184:185], v167 offset:0x3a00
	s_waitcnt lgkmcnt(6)
	v_mfma_f32_32x32x16_bf16 v[50:65], v[82:85], v[158:161], v[50:65]
	ds_read_b64_tr_b16 v[158:159], v167 offset:0x400
	ds_read_b64_tr_b16 v[160:161], v167 offset:0xc00
	s_waitcnt lgkmcnt(6)
	v_mfma_f32_32x32x16_bf16 v[50:65], v[86:89], v[174:177], v[50:65]
	ds_read_b64_tr_b16 v[174:175], v167 offset:0x1400
	ds_read_b64_tr_b16 v[176:177], v167 offset:0x1c00
	s_waitcnt lgkmcnt(6)
	v_mfma_f32_32x32x16_bf16 v[50:65], v[90:93], v[178:181], v[50:65]
	ds_read_b64_tr_b16 v[178:179], v167 offset:0x2400
	ds_read_b64_tr_b16 v[180:181], v167 offset:0x2c00
	s_waitcnt lgkmcnt(6)
	v_mfma_f32_32x32x16_bf16 v[50:65], v[94:97], v[182:185], v[50:65]
	ds_read_b64_tr_b16 v[182:183], v167 offset:0x3400
	ds_read_b64_tr_b16 v[184:185], v167 offset:0x3c00
	s_waitcnt lgkmcnt(6)
	v_mfma_f32_32x32x16_bf16 v[34:49], v[82:85], v[158:161], v[34:49]
	ds_read_b64_tr_b16 v[158:159], v167 offset:0x600
	ds_read_b64_tr_b16 v[160:161], v167 offset:0xe00
	s_waitcnt lgkmcnt(6)
	v_mfma_f32_32x32x16_bf16 v[34:49], v[86:89], v[174:177], v[34:49]
	ds_read_b64_tr_b16 v[174:175], v167 offset:0x1600
	ds_read_b64_tr_b16 v[176:177], v167 offset:0x1e00
	s_waitcnt lgkmcnt(6)
	v_mfma_f32_32x32x16_bf16 v[34:49], v[90:93], v[178:181], v[34:49]
	ds_read_b64_tr_b16 v[178:179], v167 offset:0x2600
	ds_read_b64_tr_b16 v[180:181], v167 offset:0x2e00
	s_waitcnt lgkmcnt(6)
	v_mfma_f32_32x32x16_bf16 v[34:49], v[94:97], v[182:185], v[34:49]
	ds_read_b64_tr_b16 v[182:183], v167 offset:0x3600
	ds_read_b64_tr_b16 v[184:185], v167 offset:0x3e00
	s_waitcnt lgkmcnt(0)
	v_mfma_f32_32x32x16_bf16 v[16:31], v[82:85], v[158:161], v[16:31]
	v_exp_f32_e32 v160, v106
	v_exp_f32_e32 v158, v108
	v_exp_f32_e32 v161, v109
	v_exp_f32_e32 v32, v110
	v_exp_f32_e32 v159, v112
	v_exp_f32_e32 v173, v113
	v_mfma_f32_32x32x16_bf16 v[16:31], v[86:89], v[174:177], v[16:31]
	v_exp_f32_e32 v177, v100
	v_exp_f32_e32 v176, v102
	v_exp_f32_e32 v174, v107
	v_exp_f32_e32 v175, v111
	s_barrier
	s_waitcnt vmcnt(3)
	v_mfma_f32_32x32x16_bf16 v[16:31], v[90:93], v[178:181], v[16:31]
	v_exp_f32_e32 v180, v98
	v_exp_f32_e32 v181, v101
	v_exp_f32_e32 v178, v103
	v_exp_f32_e32 v179, v104
	s_and_b64 vcc, exec, s[4:5]
	v_mfma_f32_32x32x16_bf16 v[16:31], v[94:97], v[182:185], v[16:31]
	v_exp_f32_e32 v183, v99
	v_exp_f32_e32 v182, v105
	s_waitcnt vmcnt(2)
	ds_write_b128 v171, v[142:145] offset:16384
	s_waitcnt vmcnt(1)
	ds_write_b128 v172, v[146:149] offset:16384
	s_waitcnt vmcnt(0)
	ds_write_b128 v170, v[150:153] offset:41984
	s_waitcnt lgkmcnt(0)
	s_barrier
	s_cbranch_vccnz .LBB0_2301
; #define SBAR() __builtin_amdgcn_sched_barrier(0)
; #define SLOAD(i, k0) do { sv0[i] = *reinterpret_cast<const bf16x8*>(&Vh[(size_t)((k0) + sr) * ldv + sc]); sv1[i] = *reinterpret_cast<const bf16x8*>(&Vh[(size_t)((k0) + 32 + sr) * ldv + sc]); \
;     _Pragma("unroll") for (int _q = 0; _q < NKP; ++_q) sk[i][_q] = *reinterpret_cast<const bf16x8*>(&Kh[(size_t)(k0) * ldk + koff[_q]]); } while (0)
; #define PVD0(...) do { if constexpr (PV_PIPE != 0) pv_d0_pipe(__VA_ARGS__); else pv_d0(__VA_ARGS__); } while (0)
; #define SLOAD(k0) do { sv0 = *reinterpret_cast<const bf16x8*>(&Vh[(size_t)((k0) + sr) * ldv + sc]); sv1 = *reinterpret_cast<const bf16x8*>(&Vh[(size_t)((k0) + 32 + sr) * ldv + sc]); \
;     _Pragma("unroll") for (int _q = 0; _q < NKP; ++_q) sk[_q] = *reinterpret_cast<const bf16x8*>(&Kh[(size_t)(k0) * ldk + koff[_q]]); } while (0)
; template <int DQK, int SDEPTH, int QL, bool NOMAX, int ldq, int ldk, int ldv, int ldo> ...
;     ...
;         SBAR(); qkt<DQK, QL>(pB0, pB1, K_lds + SHM_K, qr, qpark, r32, hi);
;         finishSM(pA0, pA1, alA, l_reg, pa0, pa1, pa2, pa3); SBAR();
;         SLOAD(SO, (j + SDEPTH) * KVBLK); SBAR();
;         PVD0(o, vb0, pa0, pa1, pa2, pa3); if constexpr (NOMAX) { partialSM_nm(pB0); alB = 1.f; } else partialSM(pB0, pB1, m_reg, mnB, alB, C, thr_raw);
.LBB0_2299:
	ds_read_b128 v[82:85], v168 offset:46592
	ds_read_b128 v[86:89], v168 offset:41984
	ds_read_b128 v[142:145], v168 offset:42016
	ds_read_b128 v[146:149], v168 offset:46624
	v_exp_f32_e32 v150, v74
	v_exp_f32_e32 v151, v75
	s_waitcnt lgkmcnt(2)
	v_mfma_f32_32x32x16_bf16 v[98:113], v[86:89], v[126:129], 0
	v_exp_f32_e32 v152, v76
	v_exp_f32_e32 v153, v77
	v_exp_f32_e32 v186, v78
	v_exp_f32_e32 v187, v79
	v_exp_f32_e32 v188, v80
	v_exp_f32_e32 v81, v81
	v_mfma_f32_32x32x16_bf16 v[82:97], v[82:85], v[126:129], 0
	s_waitcnt lgkmcnt(1)
	v_mfma_f32_32x32x16_bf16 v[98:113], v[142:145], v[122:125], v[98:113]
	s_waitcnt lgkmcnt(0)
	v_mfma_f32_32x32x16_bf16 v[82:97], v[146:149], v[122:125], v[82:97]
	ds_read_b128 v[142:145], v168 offset:42048
	ds_read_b128 v[146:149], v168 offset:46656
	s_waitcnt lgkmcnt(1)
	v_mfma_f32_32x32x16_bf16 v[98:113], v[142:145], v[118:121], v[98:113]
	s_waitcnt lgkmcnt(0)
	v_mfma_f32_32x32x16_bf16 v[82:97], v[146:149], v[118:121], v[82:97]
	ds_read_b128 v[142:145], v168 offset:42080
	ds_read_b128 v[146:149], v168 offset:46688
	s_waitcnt lgkmcnt(1)
	v_mfma_f32_32x32x16_bf16 v[98:113], v[142:145], v[114:117], v[98:113]
	v_exp_f32_e32 v142, v66
	v_add_f32_e32 v66, 0, v180
	v_add_f32_e32 v66, v183, v66
	v_add_f32_e32 v66, v177, v66
	v_add_f32_e32 v66, v181, v66
	v_add_f32_e32 v66, v176, v66
	v_add_f32_e32 v66, v178, v66
	v_add_f32_e32 v66, v179, v66
	v_add_f32_e32 v66, v182, v66
	v_add_f32_e32 v66, v160, v66
	v_add_f32_e32 v66, v174, v66
	v_add_f32_e32 v66, v158, v66
	v_add_f32_e32 v66, v161, v66
	v_add_f32_e32 v66, v32, v66
	v_exp_f32_e32 v143, v67
	v_add_f32_e32 v66, v175, v66
	v_exp_f32_e32 v144, v68
	v_add_f32_e32 v66, v159, v66
	v_exp_f32_e32 v145, v69
	v_add_f32_e32 v66, v173, v66
	s_waitcnt lgkmcnt(0)
	v_mfma_f32_32x32x16_bf16 v[82:97], v[146:149], v[114:117], v[82:97]
	v_exp_f32_e32 v146, v70
	v_add_f32_e32 v66, v142, v66
	v_exp_f32_e32 v147, v71
	v_add_f32_e32 v66, v143, v66
	v_exp_f32_e32 v148, v72
	v_add_f32_e32 v66, v144, v66
	v_exp_f32_e32 v149, v73
	v_add_f32_e32 v66, v145, v66
	v_add_f32_e32 v66, v146, v66
	v_add_f32_e32 v66, v147, v66
	v_add_f32_e32 v66, v148, v66
	v_add_f32_e32 v66, v149, v66
	v_add_f32_e32 v66, v150, v66
	v_add_f32_e32 v66, v151, v66
	v_add_f32_e32 v66, v152, v66
	v_add_f32_e32 v66, v153, v66
	v_add_f32_e32 v66, v186, v66
	v_add_f32_e32 v66, v187, v66
	v_add_f32_e32 v66, v188, v66
	v_add_f32_e32 v184, v81, v66
	v_cvt_pk_bf16_f32 v66, v180, v183
	v_cvt_pk_bf16_f32 v67, v177, v181
	v_cvt_pk_bf16_f32 v68, v176, v178
	v_cvt_pk_bf16_f32 v69, v179, v182
	v_cvt_pk_bf16_f32 v70, v160, v174
	v_cvt_pk_bf16_f32 v71, v158, v161
	v_cvt_pk_bf16_f32 v72, v32, v175
	v_cvt_pk_bf16_f32 v73, v159, v173
	v_cvt_pk_bf16_f32 v74, v142, v143
	v_cvt_pk_bf16_f32 v75, v144, v145
	v_cvt_pk_bf16_f32 v76, v146, v147
	v_cvt_pk_bf16_f32 v77, v148, v149
	v_cvt_pk_bf16_f32 v78, v150, v151
	v_cvt_pk_bf16_f32 v79, v152, v153
	v_cvt_pk_bf16_f32 v80, v186, v187
	v_cvt_pk_bf16_f32 v81, v188, v81
	s_nop 1
	v_permlane32_swap_b32_e32 v66, v68
	v_permlane32_swap_b32_e32 v67, v69
	v_permlane32_swap_b32_e32 v70, v72
	v_permlane32_swap_b32_e32 v71, v73
	v_permlane32_swap_b32_e32 v74, v76
	v_permlane32_swap_b32_e32 v75, v77
	v_permlane32_swap_b32_e32 v78, v80
	v_permlane32_swap_b32_e32 v79, v81
	global_load_dwordx4 v[142:145], v224, s[98:99] offset:256
	global_load_dwordx4 v[146:149], v225, s[98:99] offset:256
	global_load_dwordx4 v[150:153], v226, s[100:101] offset:256
	s_add_u32 s98, s98, 0x20000
	s_addc_u32 s99, s99, 0
	s_add_u32 s100, s100, 0x20000
	s_addc_u32 s101, s101, 0
	ds_read_b64_tr_b16 v[174:175], v169 offset:0
	ds_read_b64_tr_b16 v[176:177], v169 offset:0x800
	ds_read_b64_tr_b16 v[178:179], v169 offset:0x1000
	ds_read_b64_tr_b16 v[180:181], v169 offset:0x1800
	ds_read_b64_tr_b16 v[186:187], v169 offset:0x2000
	ds_read_b64_tr_b16 v[188:189], v169 offset:0x2800
	ds_read_b64_tr_b16 v[190:191], v169 offset:0x3000
	ds_read_b64_tr_b16 v[192:193], v169 offset:0x3800
	s_waitcnt lgkmcnt(6)
	s_nop 0
	v_mfma_f32_32x32x16_bf16 v[0:15], v[66:69], v[174:177], v[0:15]
	ds_read_b64_tr_b16 v[174:175], v169 offset:0x200
	ds_read_b64_tr_b16 v[176:177], v169 offset:0xa00
	s_waitcnt lgkmcnt(6)
	v_mfma_f32_32x32x16_bf16 v[0:15], v[70:73], v[178:181], v[0:15]
	ds_read_b64_tr_b16 v[178:179], v169 offset:0x1200
	ds_read_b64_tr_b16 v[180:181], v169 offset:0x1a00
	s_waitcnt lgkmcnt(6)
	v_mfma_f32_32x32x16_bf16 v[0:15], v[74:77], v[186:189], v[0:15]
	ds_read_b64_tr_b16 v[186:187], v169 offset:0x2200
	ds_read_b64_tr_b16 v[188:189], v169 offset:0x2a00
	s_waitcnt lgkmcnt(6)
	v_mfma_f32_32x32x16_bf16 v[0:15], v[78:81], v[190:193], v[0:15]
	ds_read_b64_tr_b16 v[190:191], v169 offset:0x3200
	ds_read_b64_tr_b16 v[192:193], v169 offset:0x3a00
	s_waitcnt lgkmcnt(6)
	v_mfma_f32_32x32x16_bf16 v[50:65], v[66:69], v[174:177], v[50:65]
	ds_read_b64_tr_b16 v[174:175], v169 offset:0x400
	ds_read_b64_tr_b16 v[176:177], v169 offset:0xc00
	s_waitcnt lgkmcnt(6)
	v_mfma_f32_32x32x16_bf16 v[50:65], v[70:73], v[178:181], v[50:65]
	ds_read_b64_tr_b16 v[178:179], v169 offset:0x1400
	ds_read_b64_tr_b16 v[180:181], v169 offset:0x1c00
	s_waitcnt lgkmcnt(6)
	v_mfma_f32_32x32x16_bf16 v[50:65], v[74:77], v[186:189], v[50:65]
	ds_read_b64_tr_b16 v[186:187], v169 offset:0x2400
	ds_read_b64_tr_b16 v[188:189], v169 offset:0x2c00
	s_waitcnt lgkmcnt(6)
	v_mfma_f32_32x32x16_bf16 v[50:65], v[78:81], v[190:193], v[50:65]
	ds_read_b64_tr_b16 v[190:191], v169 offset:0x3400
	ds_read_b64_tr_b16 v[192:193], v169 offset:0x3c00
	s_waitcnt lgkmcnt(6)
	v_mfma_f32_32x32x16_bf16 v[34:49], v[66:69], v[174:177], v[34:49]
	ds_read_b64_tr_b16 v[174:175], v169 offset:0x600
	ds_read_b64_tr_b16 v[176:177], v169 offset:0xe00
	s_waitcnt lgkmcnt(6)
	v_mfma_f32_32x32x16_bf16 v[34:49], v[70:73], v[178:181], v[34:49]
	ds_read_b64_tr_b16 v[178:179], v169 offset:0x1600
	ds_read_b64_tr_b16 v[180:181], v169 offset:0x1e00
	s_waitcnt lgkmcnt(6)
	v_mfma_f32_32x32x16_bf16 v[34:49], v[74:77], v[186:189], v[34:49]
	ds_read_b64_tr_b16 v[186:187], v169 offset:0x2600
	ds_read_b64_tr_b16 v[188:189], v169 offset:0x2e00
	s_waitcnt lgkmcnt(6)
	v_mfma_f32_32x32x16_bf16 v[34:49], v[78:81], v[190:193], v[34:49]
	ds_read_b64_tr_b16 v[190:191], v169 offset:0x3600
	ds_read_b64_tr_b16 v[192:193], v169 offset:0x3e00
	s_waitcnt lgkmcnt(0)
	v_mfma_f32_32x32x16_bf16 v[16:31], v[66:69], v[174:177], v[16:31]
	s_barrier
; #define SBAR() __builtin_amdgcn_sched_barrier(0)
; #define SLOAD(i, k0) do { sv0[i] = *reinterpret_cast<const bf16x8*>(&Vh[(size_t)((k0) + sr) * ldv + sc]); sv1[i] = *reinterpret_cast<const bf16x8*>(&Vh[(size_t)((k0) + 32 + sr) * ldv + sc]); \
;     _Pragma("unroll") for (int _q = 0; _q < NKP; ++_q) sk[i][_q] = *reinterpret_cast<const bf16x8*>(&Kh[(size_t)(k0) * ldk + koff[_q]]); } while (0)
; #define SWRITE(b, i) do { *(bf16x8*)(V_lds + (b) * SHM_V + vst0) = sv0[i]; *(bf16x8*)(V_lds + (b) * SHM_V + vst1) = sv1[i]; \
;     _Pragma("unroll") for (int _q = 0; _q < NKP; ++_q) *(bf16x8*)(K_lds + (b) * SHM_K + klds[_q]) = sk[i][_q]; } while (0)
; #define SWAIT() do { if constexpr (SDEPTH == 2) { if constexpr (NKP == 1) asm volatile("s_waitcnt vmcnt(3)" ::: "memory"); else if constexpr (NKP == 2) asm volatile("s_waitcnt vmcnt(4)" ::: "memory"); else asm volatile("s_waitcnt vmcnt(5)" ::: "memory"); } \
;     else asm volatile("s_waitcnt vmcnt(0)" ::: "memory"); } while (0)
; #define RESC(a) do { if constexpr (!NOMAX) if (__any((a) < 1.f)) { if (hi == 0) al_l[r32] = (a); asm volatile("s_waitcnt lgkmcnt(0)" ::: "memory"); \
;     _Pragma("unroll") for (int d = 0; d < 4; ++d) _Pragma("unroll") for (int r = 0; r < 16; ++r) o[d][r] *= al_l[crow(r, hi)]; } } while (0)
; #define SLOAD(k0) do { sv0 = *reinterpret_cast<const bf16x8*>(&Vh[(size_t)((k0) + sr) * ldv + sc]); sv1 = *reinterpret_cast<const bf16x8*>(&Vh[(size_t)((k0) + 32 + sr) * ldv + sc]); \
;     _Pragma("unroll") for (int _q = 0; _q < NKP; ++_q) sk[_q] = *reinterpret_cast<const bf16x8*>(&Kh[(size_t)(k0) * ldk + koff[_q]]); } while (0)
; #define SWRITE(b) do { *(bf16x8*)(V_lds + (b) * SHM_V + vst0) = sv0; *(bf16x8*)(V_lds + (b) * SHM_V + vst1) = sv1; \
;     _Pragma("unroll") for (int _q = 0; _q < NKP; ++_q) *(bf16x8*)(K_lds + (b) * SHM_K + klds[_q]) = sk[_q]; } while (0)
; template <int DQK, int SDEPTH, int QL, bool NOMAX, int ldq, int ldk, int ldv, int ldo> ...
;     ...
;         __syncthreads(); SWAIT(); SWRITE(0, SE);
;         RESC(alB); __syncthreads();
;         SBAR(); qkt<DQK, QL>(pA0, pA1, K_lds, qr, qpark, r32, hi);
;         finishSM(pB0, pB1, alB, l_reg, pa0, pa1, pa2, pa3); SBAR();
;         if (SDEPTH == 1 || j + 3 < NT) SLOAD(SE, (j + 1 + SDEPTH) * KVBLK); SBAR();
	s_waitcnt vmcnt(3)
	v_exp_f32_e32 v182, v98
	v_exp_f32_e32 v183, v99
	v_exp_f32_e32 v194, v108
	v_mfma_f32_32x32x16_bf16 v[16:31], v[70:73], v[178:181], v[16:31]
	v_exp_f32_e32 v195, v109
	v_exp_f32_e32 v196, v110
	v_exp_f32_e32 v197, v111
	v_exp_f32_e32 v198, v112
	v_exp_f32_e32 v199, v113
	s_waitcnt vmcnt(5)
	ds_write_b128 v171, v[130:133]
	s_waitcnt vmcnt(4)
	ds_write_b128 v172, v[134:137]
	s_waitcnt vmcnt(3)
	ds_write_b128 v170, v[138:141] offset:32768
	s_waitcnt lgkmcnt(0)
	v_mfma_f32_32x32x16_bf16 v[16:31], v[74:77], v[186:189], v[16:31]
	v_exp_f32_e32 v186, v100
	v_exp_f32_e32 v187, v101
	v_exp_f32_e32 v188, v102
	v_exp_f32_e32 v189, v103
	s_barrier
	v_mfma_f32_32x32x16_bf16 v[16:31], v[78:81], v[190:193], v[16:31]
	v_exp_f32_e32 v190, v104
	v_exp_f32_e32 v191, v105
	v_exp_f32_e32 v192, v106
	v_exp_f32_e32 v193, v107
	ds_read_b128 v[66:69], v168 offset:37376
	ds_read_b128 v[70:73], v168 offset:32768
	ds_read_b128 v[174:177], v168 offset:32800
	ds_read_b128 v[178:181], v168 offset:37408
	v_add_f32_e32 v32, 0, v182
	v_add_f32_e32 v32, v183, v32
	s_waitcnt lgkmcnt(2)
	v_mfma_f32_32x32x16_bf16 v[98:113], v[70:73], v[126:129], 0
	v_add_f32_e32 v32, v186, v32
	v_add_f32_e32 v32, v187, v32
	v_add_f32_e32 v32, v188, v32
	v_add_f32_e32 v32, v189, v32
	v_add_f32_e32 v32, v190, v32
	v_add_f32_e32 v32, v191, v32
	v_add_f32_e32 v32, v192, v32
	v_mfma_f32_32x32x16_bf16 v[66:81], v[66:69], v[126:129], 0
	v_add_f32_e32 v32, v193, v32
	v_add_f32_e32 v32, v194, v32
	v_add_f32_e32 v32, v195, v32
	v_add_f32_e32 v32, v196, v32
	v_add_f32_e32 v32, v197, v32
	v_add_f32_e32 v32, v198, v32
	v_add_f32_e32 v32, v199, v32
	s_waitcnt lgkmcnt(1)
	v_mfma_f32_32x32x16_bf16 v[98:113], v[174:177], v[122:125], v[98:113]
	v_exp_f32_e32 v200, v90
	v_exp_f32_e32 v201, v91
	v_exp_f32_e32 v202, v92
	v_exp_f32_e32 v203, v93
	v_exp_f32_e32 v204, v94
	v_exp_f32_e32 v205, v95
	v_exp_f32_e32 v206, v96
	s_waitcnt lgkmcnt(0)
	v_mfma_f32_32x32x16_bf16 v[66:81], v[178:181], v[122:125], v[66:81]
	ds_read_b128 v[174:177], v168 offset:32832
	ds_read_b128 v[178:181], v168 offset:37440
	v_exp_f32_e32 v97, v97
	s_waitcnt lgkmcnt(1)
	v_mfma_f32_32x32x16_bf16 v[98:113], v[174:177], v[118:121], v[98:113]
	s_waitcnt lgkmcnt(0)
	v_mfma_f32_32x32x16_bf16 v[66:81], v[178:181], v[118:121], v[66:81]
	ds_read_b128 v[174:177], v168 offset:32864
	ds_read_b128 v[178:181], v168 offset:37472
	s_waitcnt lgkmcnt(1)
	v_mfma_f32_32x32x16_bf16 v[98:113], v[174:177], v[114:117], v[98:113]
	v_exp_f32_e32 v174, v82
	v_exp_f32_e32 v175, v83
	v_exp_f32_e32 v176, v84
	v_exp_f32_e32 v177, v85
	v_add_f32_e32 v32, v174, v32
	v_add_f32_e32 v32, v175, v32
	v_add_f32_e32 v32, v176, v32
	s_waitcnt lgkmcnt(0)
	v_mfma_f32_32x32x16_bf16 v[66:81], v[178:181], v[114:117], v[66:81]
	v_exp_f32_e32 v178, v86
	v_exp_f32_e32 v179, v87
	v_exp_f32_e32 v180, v88
	v_exp_f32_e32 v181, v89
	v_add_f32_e32 v32, v177, v32
	v_add_f32_e32 v32, v178, v32
	v_add_f32_e32 v32, v179, v32
	v_add_f32_e32 v32, v180, v32
	v_add_f32_e32 v32, v181, v32
	v_add_f32_e32 v32, v200, v32
	v_add_f32_e32 v32, v201, v32
	v_add_f32_e32 v32, v202, v32
	v_add_f32_e32 v32, v203, v32
	v_add_f32_e32 v32, v204, v32
	v_add_f32_e32 v32, v205, v32
	v_add_f32_e32 v32, v206, v32
	v_add_f32_e32 v32, v97, v32
	v_cvt_pk_bf16_f32 v82, v182, v183
	v_cvt_pk_bf16_f32 v83, v186, v187
	v_cvt_pk_bf16_f32 v84, v188, v189
	v_cvt_pk_bf16_f32 v85, v190, v191
	v_cvt_pk_bf16_f32 v86, v192, v193
	v_cvt_pk_bf16_f32 v87, v194, v195
	v_cvt_pk_bf16_f32 v88, v196, v197
	v_cvt_pk_bf16_f32 v89, v198, v199
	v_cvt_pk_bf16_f32 v90, v174, v175
	v_cvt_pk_bf16_f32 v91, v176, v177
	v_cvt_pk_bf16_f32 v92, v178, v179
	v_cvt_pk_bf16_f32 v93, v180, v181
	v_cvt_pk_bf16_f32 v94, v200, v201
	v_cvt_pk_bf16_f32 v95, v202, v203
	v_cvt_pk_bf16_f32 v96, v204, v205
	v_cvt_pk_bf16_f32 v97, v206, v97
	s_nop 1
	v_permlane32_swap_b32_e32 v82, v84
	v_permlane32_swap_b32_e32 v83, v85
	v_permlane32_swap_b32_e32 v86, v88
	v_permlane32_swap_b32_e32 v87, v89
	v_permlane32_swap_b32_e32 v90, v92
	v_permlane32_swap_b32_e32 v91, v93
	v_permlane32_swap_b32_e32 v94, v96
	v_permlane32_swap_b32_e32 v95, v97
	s_cmp_ge_u32 s6, s7
	s_cselect_b64 s[4:5], -1, 0
	s_and_b64 vcc, exec, s[4:5]
	s_cbranch_vccnz .LBB0_2298
	global_load_dwordx4 v[130:133], v224, s[98:99] offset:256
	global_load_dwordx4 v[134:137], v225, s[98:99] offset:256
	global_load_dwordx4 v[138:141], v226, s[100:101] offset:256
	s_add_u32 s98, s98, 0x20000
	s_addc_u32 s99, s99, 0
	s_add_u32 s100, s100, 0x20000
	s_addc_u32 s101, s101, 0
	s_branch .LBB0_2298
; #define SBAR() __builtin_amdgcn_sched_barrier(0)
; #define PVD0(...) do { if constexpr (PV_PIPE != 0) pv_d0_pipe(__VA_ARGS__); else pv_d0(__VA_ARGS__); } while (0)
; template <int DQK, int SDEPTH, int QL, bool NOMAX, int ldq, int ldk, int ldv, int ldo> ...
;     ...
;     SBAR(); qkt<DQK, QL>(pB0, pB1, K_lds + SHM_K, qr, qpark, r32, hi);
;     finishSM(pA0, pA1, alA, l_reg, pa0, pa1, pa2, pa3); SBAR();
;     PVD0(o, vb0, pa0, pa1, pa2, pa3); if constexpr (NOMAX) { partialSM_nm(pB0); alB = 1.f; } else partialSM(pB0, pB1, m_reg, mnB, alB, C, thr_raw);
.LBB0_2301:
	v_mov_b32_e32 v227, v166
	s_nop 1
	v_permlane32_swap_b32_e32 v166, v227
	v_add_f32_e32 v166, v166, v227
	ds_read_b128 v[82:85], v168 offset:46592
	ds_read_b128 v[86:89], v168 offset:41984
	ds_read_b128 v[130:133], v168 offset:42016
	v_exp_f32_e32 v67, v67
	v_exp_f32_e32 v69, v69
	s_waitcnt lgkmcnt(1)
	v_mfma_f32_32x32x16_bf16 v[98:113], v[86:89], v[126:129], 0
	v_mfma_f32_32x32x16_bf16 v[82:97], v[82:85], v[126:129], 0
	ds_read_b128 v[126:129], v168 offset:46624
	s_waitcnt lgkmcnt(1)
	v_mfma_f32_32x32x16_bf16 v[98:113], v[130:133], v[122:125], v[98:113]
	s_waitcnt lgkmcnt(0)
	v_mfma_f32_32x32x16_bf16 v[82:97], v[126:129], v[122:125], v[82:97]
	ds_read_b128 v[122:125], v168 offset:42048
	ds_read_b128 v[126:129], v168 offset:46656
	s_waitcnt lgkmcnt(1)
	v_mfma_f32_32x32x16_bf16 v[98:113], v[122:125], v[118:121], v[98:113]
	s_waitcnt lgkmcnt(0)
	v_mfma_f32_32x32x16_bf16 v[82:97], v[126:129], v[118:121], v[82:97]
	ds_read_b128 v[118:121], v168 offset:42080
	ds_read_b128 v[122:125], v168 offset:46688
	v_exp_f32_e32 v126, v80
	v_exp_f32_e32 v127, v81
	s_waitcnt lgkmcnt(1)
	v_mfma_f32_32x32x16_bf16 v[98:113], v[118:121], v[114:117], v[98:113]
	v_exp_f32_e32 v118, v72
	v_exp_f32_e32 v119, v73
	v_exp_f32_e32 v120, v74
	v_exp_f32_e32 v121, v75
	s_waitcnt lgkmcnt(0)
	v_mfma_f32_32x32x16_bf16 v[82:97], v[122:125], v[114:117], v[82:97]
	v_exp_f32_e32 v114, v66
	v_add_f32_e32 v66, 0, v180
	v_add_f32_e32 v66, v183, v66
	v_add_f32_e32 v66, v177, v66
	v_add_f32_e32 v66, v181, v66
	v_add_f32_e32 v66, v176, v66
	v_add_f32_e32 v66, v178, v66
	v_add_f32_e32 v66, v179, v66
	v_add_f32_e32 v66, v182, v66
	v_add_f32_e32 v66, v160, v66
	v_add_f32_e32 v66, v174, v66
	v_add_f32_e32 v66, v158, v66
	v_add_f32_e32 v66, v161, v66
	v_add_f32_e32 v66, v32, v66
	v_add_f32_e32 v66, v175, v66
	v_exp_f32_e32 v115, v68
	v_add_f32_e32 v66, v159, v66
	v_add_f32_e32 v66, v173, v66
	v_exp_f32_e32 v116, v70
	v_add_f32_e32 v66, v114, v66
	v_exp_f32_e32 v117, v71
	v_add_f32_e32 v66, v67, v66
	v_add_f32_e32 v66, v115, v66
	v_add_f32_e32 v66, v69, v66
	v_add_f32_e32 v66, v116, v66
	v_add_f32_e32 v66, v117, v66
	v_exp_f32_e32 v122, v76
	v_add_f32_e32 v66, v118, v66
	v_exp_f32_e32 v123, v77
	v_add_f32_e32 v66, v119, v66
	v_exp_f32_e32 v124, v78
	v_add_f32_e32 v66, v120, v66
	v_exp_f32_e32 v125, v79
	v_add_f32_e32 v66, v121, v66
	v_add_f32_e32 v66, v122, v66
	v_add_f32_e32 v66, v123, v66
	v_add_f32_e32 v66, v124, v66
	v_add_f32_e32 v66, v125, v66
	v_add_f32_e32 v66, v126, v66
	v_add_f32_e32 v66, v127, v66
	v_mov_b32_e32 v68, v66
	s_nop 1
	v_permlane32_swap_b32_e32 v66, v68
	v_cvt_pk_bf16_f32 v70, v180, v183
	v_cvt_pk_bf16_f32 v71, v177, v181
	v_cvt_pk_bf16_f32 v72, v176, v178
	v_cvt_pk_bf16_f32 v73, v179, v182
	v_cvt_pk_bf16_f32 v74, v160, v174
	v_cvt_pk_bf16_f32 v75, v158, v161
	v_cvt_pk_bf16_f32 v76, v32, v175
	v_cvt_pk_bf16_f32 v77, v159, v173
	v_cvt_pk_bf16_f32 v78, v114, v67
	v_cvt_pk_bf16_f32 v79, v115, v69
	v_cvt_pk_bf16_f32 v80, v116, v117
	v_cvt_pk_bf16_f32 v81, v118, v119
	v_cvt_pk_bf16_f32 v114, v120, v121
	v_cvt_pk_bf16_f32 v115, v122, v123
	v_cvt_pk_bf16_f32 v116, v124, v125
	v_cvt_pk_bf16_f32 v117, v126, v127
	s_nop 0
	v_permlane32_swap_b32_e32 v70, v72
	v_permlane32_swap_b32_e32 v71, v73
	v_permlane32_swap_b32_e32 v74, v76
	v_permlane32_swap_b32_e32 v75, v77
	v_permlane32_swap_b32_e32 v78, v80
	v_permlane32_swap_b32_e32 v79, v81
	v_permlane32_swap_b32_e32 v114, v116
	v_permlane32_swap_b32_e32 v115, v117
	ds_read_b64_tr_b16 v[118:119], v169 offset:0
	ds_read_b64_tr_b16 v[120:121], v169 offset:0x800
	ds_read_b64_tr_b16 v[122:123], v169 offset:0x1000
	ds_read_b64_tr_b16 v[124:125], v169 offset:0x1800
	ds_read_b64_tr_b16 v[126:127], v169 offset:0x2000
	ds_read_b64_tr_b16 v[128:129], v169 offset:0x2800
	ds_read_b64_tr_b16 v[130:131], v169 offset:0x3000
	ds_read_b64_tr_b16 v[132:133], v169 offset:0x3800
	s_waitcnt lgkmcnt(0)
	s_nop 0
	v_mfma_f32_32x32x16_bf16 v[0:15], v[70:73], v[118:121], v[0:15]
	ds_read_b64_tr_b16 v[118:119], v169 offset:0x200
	ds_read_b64_tr_b16 v[120:121], v169 offset:0xa00
	v_mfma_f32_32x32x16_bf16 v[0:15], v[74:77], v[122:125], v[0:15]
	ds_read_b64_tr_b16 v[122:123], v169 offset:0x1200
	ds_read_b64_tr_b16 v[124:125], v169 offset:0x1a00
	v_mfma_f32_32x32x16_bf16 v[0:15], v[78:81], v[126:129], v[0:15]
	ds_read_b64_tr_b16 v[126:127], v169 offset:0x2200
	ds_read_b64_tr_b16 v[128:129], v169 offset:0x2a00
	v_mfma_f32_32x32x16_bf16 v[0:15], v[114:117], v[130:133], v[0:15]
	ds_read_b64_tr_b16 v[130:131], v169 offset:0x3200
	ds_read_b64_tr_b16 v[132:133], v169 offset:0x3a00
	s_waitcnt lgkmcnt(0)
	v_mfma_f32_32x32x16_bf16 v[50:65], v[70:73], v[118:121], v[50:65]
	ds_read_b64_tr_b16 v[118:119], v169 offset:0x400
	ds_read_b64_tr_b16 v[120:121], v169 offset:0xc00
	v_mfma_f32_32x32x16_bf16 v[50:65], v[74:77], v[122:125], v[50:65]
	ds_read_b64_tr_b16 v[122:123], v169 offset:0x1400
	ds_read_b64_tr_b16 v[124:125], v169 offset:0x1c00
	v_mfma_f32_32x32x16_bf16 v[50:65], v[78:81], v[126:129], v[50:65]
	ds_read_b64_tr_b16 v[126:127], v169 offset:0x2400
	ds_read_b64_tr_b16 v[128:129], v169 offset:0x2c00
	v_mfma_f32_32x32x16_bf16 v[50:65], v[114:117], v[130:133], v[50:65]
	ds_read_b64_tr_b16 v[130:131], v169 offset:0x3400
	ds_read_b64_tr_b16 v[132:133], v169 offset:0x3c00
	s_waitcnt lgkmcnt(0)
	v_mfma_f32_32x32x16_bf16 v[34:49], v[70:73], v[118:121], v[34:49]
	ds_read_b64_tr_b16 v[118:119], v169 offset:0x600
	ds_read_b64_tr_b16 v[120:121], v169 offset:0xe00
	v_mfma_f32_32x32x16_bf16 v[34:49], v[74:77], v[122:125], v[34:49]
	ds_read_b64_tr_b16 v[122:123], v169 offset:0x1600
	ds_read_b64_tr_b16 v[124:125], v169 offset:0x1e00
	v_mfma_f32_32x32x16_bf16 v[34:49], v[78:81], v[126:129], v[34:49]
	ds_read_b64_tr_b16 v[126:127], v169 offset:0x2600
	ds_read_b64_tr_b16 v[128:129], v169 offset:0x2e00
	v_mfma_f32_32x32x16_bf16 v[34:49], v[114:117], v[130:133], v[34:49]
	ds_read_b64_tr_b16 v[130:131], v169 offset:0x3600
	ds_read_b64_tr_b16 v[132:133], v169 offset:0x3e00
	s_waitcnt lgkmcnt(0)
; template <int M> __device__ __forceinline__ float swz_xor(float v) { return __int_as_float(__builtin_amdgcn_ds_swizzle(__float_as_int(v), (M << 10) | 0x1f)); }
; #define SBAR() __builtin_amdgcn_sched_barrier(0)
; __device__ __forceinline__ int crow(int r, int hi) { return (r & 3) + 8 * (r >> 2) + 4 * hi; }
; __device__ __forceinline__ unsigned cvtpk(float lo, float hi) { unsigned r; asm volatile("v_cvt_pk_bf16_f32 %0, %1, %2" : "=v"(r) : "v"(lo), "v"(hi)); return r; }
; #define PVD0(...) do { if constexpr (PV_PIPE != 0) pv_d0_pipe(__VA_ARGS__); else pv_d0(__VA_ARGS__); } while (0)
; #define RESC(a) do { if constexpr (!NOMAX) if (__any((a) < 1.f)) { if (hi == 0) al_l[r32] = (a); asm volatile("s_waitcnt lgkmcnt(0)" ::: "memory"); \
;     _Pragma("unroll") for (int d = 0; d < 4; ++d) _Pragma("unroll") for (int r = 0; r < 16; ++r) o[d][r] *= al_l[crow(r, hi)]; } } while (0)
; #define RESC(a) do { if (__any((a) < 1.f)) { if (hi == 0) al_l[r32] = (a); asm volatile("s_waitcnt lgkmcnt(0)" ::: "memory"); \
;     _Pragma("unroll") for (int d = 0; d < 4; ++d) _Pragma("unroll") for (int r = 0; r < 16; ++r) o[d][r] *= al_l[crow(r, hi)]; } } while (0)
; template <int DQK, int SDEPTH, int QL, bool NOMAX, int ldq, int ldk, int ldv, int ldo> ...
;     ...
;     PVD0(o, vb0, pa0, pa1, pa2, pa3); if constexpr (NOMAX) { partialSM_nm(pB0); alB = 1.f; } else partialSM(pB0, pB1, m_reg, mnB, alB, C, thr_raw);
;     __syncthreads(); RESC(alB);
;     finishSM(pB0, pB1, alB, l_reg, pa0, pa1, pa2, pa3); SBAR();
;     PVD0(o, vb0 + SHM_V, pa0, pa1, pa2, pa3);
;     if (ATT_PRIO) __builtin_amdgcn_s_setprio(0);
;     if (hi == 0) li_l[r32] = l_reg; asm volatile("s_waitcnt lgkmcnt(0)" ::: "memory");
;     float rli[16];
; #pragma unroll
;     for (int r = 0; r < 16; ++r) rli[r] = __builtin_amdgcn_rcpf(li_l[crow(r, hi)]);
;     bf16_t* Ow = Ob + (size_t)(wid * QBLK) * ldo + (r32 & ~1);
;     const bool odd = (r32 & 1) != 0;
; #pragma unroll
;     for (int r = 0; r < 16; r += 2) { const int orow = crow(r, hi) + (odd ? 1 : 0);
; #pragma unroll
;         for (int d0 = 0; d0 < 4; ++d0) { const float a = o[d0][r] * rli[r], b = o[d0][r + 1] * rli[r + 1];
;             const float recv = swz_xor<1>(odd ? a : b);
;             const unsigned w = odd ? cvtpk(recv, b) : cvtpk(a, recv);
;             *(unsigned*)(Ow + (size_t)orow * ldo + d0 * 32) = w; } }
	v_mfma_f32_32x32x16_bf16 v[16:31], v[70:73], v[118:121], v[16:31]
	v_exp_f32_e32 v32, v98
	v_exp_f32_e32 v70, v99
	v_exp_f32_e32 v71, v100
	v_exp_f32_e32 v72, v101
	v_exp_f32_e32 v73, v102
	v_add_f32_e32 v67, 0, v32
	v_add_f32_e32 v67, v70, v67
	v_mfma_f32_32x32x16_bf16 v[16:31], v[74:77], v[122:125], v[16:31]
	v_exp_f32_e32 v74, v103
	v_exp_f32_e32 v75, v104
	v_add_f32_e32 v67, v71, v67
	v_exp_f32_e32 v76, v105
	v_add_f32_e32 v67, v72, v67
	v_exp_f32_e32 v77, v106
	v_add_f32_e32 v67, v73, v67
	v_mfma_f32_32x32x16_bf16 v[16:31], v[78:81], v[126:129], v[16:31]
	v_exp_f32_e32 v78, v107
	v_add_f32_e32 v67, v74, v67
	v_exp_f32_e32 v79, v108
	v_add_f32_e32 v67, v75, v67
	v_exp_f32_e32 v80, v109
	v_add_f32_e32 v67, v76, v67
	v_exp_f32_e32 v81, v110
	v_add_f32_e32 v67, v77, v67
	v_exp_f32_e32 v98, v111
	v_add_f32_e32 v67, v78, v67
	v_exp_f32_e32 v99, v112
	v_add_f32_e32 v67, v79, v67
	v_exp_f32_e32 v100, v113
	v_add_f32_e32 v67, v80, v67
	v_exp_f32_e32 v82, v82
	v_add_f32_e32 v67, v81, v67
	v_exp_f32_e32 v83, v83
	v_add_f32_e32 v67, v98, v67
	v_exp_f32_e32 v84, v84
	v_add_f32_e32 v67, v99, v67
	v_exp_f32_e32 v85, v85
	v_add_f32_e32 v67, v100, v67
	v_exp_f32_e32 v86, v86
	v_add_f32_e32 v67, v82, v67
	v_exp_f32_e32 v87, v87
	v_add_f32_e32 v67, v83, v67
	v_exp_f32_e32 v88, v88
	v_add_f32_e32 v67, v84, v67
	v_exp_f32_e32 v89, v89
	v_add_f32_e32 v67, v85, v67
	v_exp_f32_e32 v90, v90
	v_add_f32_e32 v67, v86, v67
	v_exp_f32_e32 v91, v91
	v_add_f32_e32 v67, v87, v67
	v_exp_f32_e32 v92, v92
	v_add_f32_e32 v67, v88, v67
	v_exp_f32_e32 v93, v93
	v_add_f32_e32 v67, v89, v67
	v_exp_f32_e32 v94, v94
	v_add_f32_e32 v67, v90, v67
	v_exp_f32_e32 v95, v95
	v_add_f32_e32 v67, v91, v67
	v_mfma_f32_32x32x16_bf16 v[16:31], v[114:117], v[130:133], v[16:31]
	v_exp_f32_e32 v96, v96
	v_add_f32_e32 v67, v92, v67
	v_exp_f32_e32 v97, v97
	v_add_f32_e32 v67, v93, v67
	v_add_f32_e32 v67, v94, v67
	v_add_f32_e32 v67, v95, v67
	v_add_f32_e32 v67, v96, v67
	v_add_f32_e32 v67, v97, v67
	v_mov_b32_e32 v69, v67
	s_barrier
	s_nop 0
	v_permlane32_swap_b32_e32 v67, v69
	v_cvt_pk_bf16_f32 v70, v32, v70
	v_cvt_pk_bf16_f32 v71, v71, v72
	v_cvt_pk_bf16_f32 v72, v73, v74
	v_cvt_pk_bf16_f32 v73, v75, v76
	v_cvt_pk_bf16_f32 v74, v77, v78
	v_cvt_pk_bf16_f32 v75, v79, v80
	v_cvt_pk_bf16_f32 v76, v81, v98
	v_cvt_pk_bf16_f32 v77, v99, v100
	v_cvt_pk_bf16_f32 v78, v82, v83
	v_cvt_pk_bf16_f32 v79, v84, v85
	v_cvt_pk_bf16_f32 v80, v86, v87
	v_cvt_pk_bf16_f32 v81, v88, v89
	v_cvt_pk_bf16_f32 v82, v90, v91
	v_cvt_pk_bf16_f32 v83, v92, v93
	v_cvt_pk_bf16_f32 v84, v94, v95
	v_cvt_pk_bf16_f32 v85, v96, v97
	s_nop 0
	v_permlane32_swap_b32_e32 v70, v72
	v_permlane32_swap_b32_e32 v71, v73
	v_permlane32_swap_b32_e32 v74, v76
	v_permlane32_swap_b32_e32 v75, v77
	v_permlane32_swap_b32_e32 v78, v80
	v_permlane32_swap_b32_e32 v79, v81
	v_permlane32_swap_b32_e32 v82, v84
	v_permlane32_swap_b32_e32 v83, v85
	ds_read_b64_tr_b16 v[86:87], v167 offset:0
	ds_read_b64_tr_b16 v[88:89], v167 offset:0x800
	ds_read_b64_tr_b16 v[90:91], v167 offset:0x1000
	ds_read_b64_tr_b16 v[92:93], v167 offset:0x1800
	ds_read_b64_tr_b16 v[94:95], v167 offset:0x2000
	ds_read_b64_tr_b16 v[96:97], v167 offset:0x2800
	ds_read_b64_tr_b16 v[98:99], v167 offset:0x3000
	ds_read_b64_tr_b16 v[100:101], v167 offset:0x3800
	s_waitcnt lgkmcnt(0)
	s_nop 0
	v_mfma_f32_32x32x16_bf16 v[0:15], v[70:73], v[86:89], v[0:15]
	ds_read_b64_tr_b16 v[86:87], v167 offset:0x200
	ds_read_b64_tr_b16 v[88:89], v167 offset:0xa00
	v_mfma_f32_32x32x16_bf16 v[0:15], v[74:77], v[90:93], v[0:15]
	ds_read_b64_tr_b16 v[90:91], v167 offset:0x1200
	ds_read_b64_tr_b16 v[92:93], v167 offset:0x1a00
	v_mfma_f32_32x32x16_bf16 v[0:15], v[78:81], v[94:97], v[0:15]
	ds_read_b64_tr_b16 v[94:95], v167 offset:0x2200
	ds_read_b64_tr_b16 v[96:97], v167 offset:0x2a00
	v_mfma_f32_32x32x16_bf16 v[0:15], v[82:85], v[98:101], v[0:15]
	ds_read_b64_tr_b16 v[98:99], v167 offset:0x3200
	ds_read_b64_tr_b16 v[100:101], v167 offset:0x3a00
	s_waitcnt lgkmcnt(0)
	v_mfma_f32_32x32x16_bf16 v[50:65], v[70:73], v[86:89], v[50:65]
	ds_read_b64_tr_b16 v[86:87], v167 offset:0x400
	ds_read_b64_tr_b16 v[88:89], v167 offset:0xc00
	v_mfma_f32_32x32x16_bf16 v[50:65], v[74:77], v[90:93], v[50:65]
	ds_read_b64_tr_b16 v[90:91], v167 offset:0x1400
	ds_read_b64_tr_b16 v[92:93], v167 offset:0x1c00
	v_mfma_f32_32x32x16_bf16 v[50:65], v[78:81], v[94:97], v[50:65]
	ds_read_b64_tr_b16 v[94:95], v167 offset:0x2400
	ds_read_b64_tr_b16 v[96:97], v167 offset:0x2c00
	v_mfma_f32_32x32x16_bf16 v[50:65], v[82:85], v[98:101], v[50:65]
	ds_read_b64_tr_b16 v[98:99], v167 offset:0x3400
	ds_read_b64_tr_b16 v[100:101], v167 offset:0x3c00
	s_waitcnt lgkmcnt(0)
	v_mfma_f32_32x32x16_bf16 v[34:49], v[70:73], v[86:89], v[34:49]
	ds_read_b64_tr_b16 v[86:87], v167 offset:0x600
	ds_read_b64_tr_b16 v[88:89], v167 offset:0xe00
	v_mfma_f32_32x32x16_bf16 v[34:49], v[74:77], v[90:93], v[34:49]
	ds_read_b64_tr_b16 v[90:91], v167 offset:0x1600
	ds_read_b64_tr_b16 v[92:93], v167 offset:0x1e00
	v_mfma_f32_32x32x16_bf16 v[34:49], v[78:81], v[94:97], v[34:49]
	ds_read_b64_tr_b16 v[94:95], v167 offset:0x2600
	ds_read_b64_tr_b16 v[96:97], v167 offset:0x2e00
	v_mfma_f32_32x32x16_bf16 v[34:49], v[82:85], v[98:101], v[34:49]
	ds_read_b64_tr_b16 v[98:99], v167 offset:0x3600
	ds_read_b64_tr_b16 v[100:101], v167 offset:0x3e00
	s_waitcnt lgkmcnt(0)
	v_mfma_f32_32x32x16_bf16 v[16:31], v[70:73], v[86:89], v[16:31]
	v_mfma_f32_32x32x16_bf16 v[16:31], v[74:77], v[90:93], v[16:31]
	v_mfma_f32_32x32x16_bf16 v[16:31], v[78:81], v[94:97], v[16:31]
	v_mfma_f32_32x32x16_bf16 v[16:31], v[82:85], v[98:101], v[16:31]
	s_setprio 0
	v_cmp_gt_u32_e32 vcc, 32, v165
	s_and_saveexec_b64 s[4:5], vcc
	v_pk_add_f32 v[66:67], v[66:67], v[68:69]
	v_lshl_add_u32 v32, v164, 2, s49
	v_add_f32_e32 v66, v166, v66
	v_add_f32_e32 v66, v66, v67
	ds_write_b32 v32, v66 offset:51200
	s_or_b64 exec, exec, s[4:5]
	s_waitcnt lgkmcnt(0)
	v_lshl_add_u32 v32, v163, 4, s49
	ds_read_b128 v[78:81], v32 offset:51200
	ds_read_b128 v[74:77], v32 offset:51232
	v_and_b32_e32 v82, 1, v162
	ds_read_b128 v[70:73], v32 offset:51264
	ds_read_b128 v[66:69], v32 offset:51296
	v_cmp_eq_u32_e64 s[6:7], 0, v82
	s_waitcnt lgkmcnt(3)
	v_rcp_f32_e32 v78, v78
	v_rcp_f32_e32 v79, v79
	v_cmp_eq_u32_e64 s[4:5], 1, v82
	v_mul_f32_e32 v0, v0, v78
	v_mul_f32_e32 v32, v1, v79
	v_cndmask_b32_e64 v1, v0, v32, s[6:7]
	ds_swizzle_b32 v1, v1 offset:swizzle(SWAP,1)
	s_and_saveexec_b64 s[14:15], s[4:5]
	s_xor_b64 s[14:15], exec, s[14:15]
	s_cbranch_execz .LBB0_2305
	s_waitcnt lgkmcnt(0)
	v_cvt_pk_bf16_f32 v83, v1, v32

;     __device__ bool next(int i, Unit& u) const { if (i != 0) return false; u.pm = pm; u.pn = pn; return true; }
; #define PG8_STAGE(bufoff, gbase, voff) do { _Pragma("unroll") for (int _i = 0; _i < 2; ++_i) \
;         __builtin_amdgcn_global_load_lds((const unsigned*)((const char*)(gbase) + (voff)[_i]), (LAS unsigned*)(lds + (bufoff) + ldsw + _i * 8192), 16, 0, 0); } while (0)
; #define PG8_WAIT_V(n) asm volatile("s_waitcnt vmcnt(" #n ")" ::: "memory")
; #define PG8_BAR __builtin_amdgcn_s_barrier()
; template <class Epi, class Sched>
; __device__ __forceinline__ void gemm_phase(LAS unsigned char* lds, const Gemm g, const Sched& S, const Epi& E, int tid_in) {
;     ...
;     for (int i = 0; i < 2; ++i) { int R, C; stage_rc(tid * 16 + i * 8192, R, C); const int Rb = Epi::PERM ? ((R & ~31) + perm32(R & 31)) : R;
;         voffA[i] = (unsigned)(R * lda + C) * 2u; voffB[i] = (unsigned)(Rb * K + C) * 2u; }
;     const size_t kstep = (size_t)(BK * 2);
;     const size_t hstepA = (size_t)HALF * lda * 2, hstepB = (size_t)HALF * K * 2;
;     const size_t tstepA = 2 * hstepA, tstepB = 2 * hstepB;
;     const unsigned ldsw = (unsigned)wid * 1024u;
;     const int aoff = lds_byte(wr * 64 + fr, fq * 8), boff = lds_byte(wc * 32 + fr, fq * 8);
;     ...
;     Unit cur, nxt; int ui = 0;
;     if (!S.next(0, cur)) return;
;     f32x4 acc[2][2][4][2];
; #pragma unroll
;     for (int a = 0; a < 2; ++a)
; #pragma unroll
;         for (int b = 0; b < 2; ++b)
; #pragma unroll
;             for (int m = 0; m < 4; ++m)
; #pragma unroll
;                 for (int n = 0; n < 2; ++n) acc[a][b][m][n] = (f32x4){0.f, 0.f, 0.f, 0.f};
;     bf16x8 At[4][2], B0[2][2], B1[2][2];
;     const char* cA = (const char*)g.A + (size_t)cur.pm * tstepA; const char* cB = (const char*)g.Bt + (size_t)cur.pn * tstepB;
;     S.a_ready(cur);
;     PG8_STAGE(PG8_SB(0, 0), cB, voffB); PG8_STAGE(PG8_SA(0, 0), cA, voffA); PG8_STAGE(PG8_SB(0, 1), cB + hstepB, voffB); PG8_STAGE(PG8_SA(0, 1), cA + hstepA, voffA);
;     if (wr == 1) PG8_BAR;
;     PG8_WAIT_V(4); PG8_BAR;
;     PG8_STAGE(PG8_SB(1, 0), cB + kstep, voffB); PG8_STAGE(PG8_SA(1, 0), cA + kstep, voffA); PG8_STAGE(PG8_SB(1, 1), cB + hstepB + kstep, voffB);
;     PG8_WAIT_V(6); PG8_BAR;
.LBB0_2563:
	v_bfe_u32 v16, v14, 4, 2
	v_and_b32_e32 v15, 15, v14
	v_lshlrev_b32_e32 v17, 4, v16
	v_lshlrev_b32_e32 v14, 2, v14
	v_lshl_or_b32 v240, s12, 6, v15
	v_lshl_or_b32 v15, v15, 6, v17
	s_lshl_b32 s5, s12, 13
	v_and_b32_e32 v14, 32, v14
	v_readlane_b32 s12, v254, 61
	v_bitop3_b32 v17, v15, s5, v14 bitop3:0xde
	s_lshl_b32 s5, s27, 5
	v_readlane_b32 s13, v254, 62
	s_and_b32 s5, s5, 0x60
	s_mul_i32 s12, s12, 0x9000
	s_mov_b32 s13, s67
	s_lshl_b32 s7, s5, 7
	s_lshl_b64 s[12:13], s[12:13], 2
	s_add_u32 s43, s2, s12
	s_addc_u32 s44, s3, s13
	s_add_i32 m0, s39, 0x18000
	v_lshl_add_u64 v[6:7], v[6:7], 0, s[76:77]
	s_waitcnt vmcnt(4)
	s_barrier
	global_load_lds_dwordx4 v[6:7], off
	v_lshl_add_u64 v[4:5], v[4:5], 0, s[76:77]
	s_add_i32 m0, s39, 0x1a000
	s_add_i32 s45, s39, 0x8000
	s_add_i32 s46, s39, 0xa000
	global_load_lds_dwordx4 v[4:5], off
	v_lshl_add_u64 v[2:3], v[2:3], 0, s[76:77]
	s_mov_b32 m0, s45
	s_add_u32 s2, s14, 0x80080
	global_load_lds_dwordx4 v[2:3], off
	v_lshl_add_u64 v[0:1], v[0:1], 0, s[76:77]
	s_mov_b32 m0, s46
	s_addc_u32 s3, s15, 0
	global_load_lds_dwordx4 v[0:1], off
	s_add_i32 m0, s39, 0x1c000
	global_load_lds_dwordx4 v32, s[2:3]
	v_lshl_add_u64 v[0:1], s[2:3], 0, v[216:217]
	s_add_i32 m0, s39, 0x1e000
	v_bitop3_b32 v241, v15, s7, v14 bitop3:0xde
	global_load_lds_dwordx4 v216, s[2:3]
	v_lshlrev_b32_e32 v0, 15, v11
	v_and_b32_e32 v0, 0xffff0000, v0
	v_lshl_add_u32 v0, v12, 12, v0
	v_and_b32_e32 v1, 1, v11
	v_lshl_or_b32 v0, v1, 6, v0
	v_lshl_add_u32 v218, v13, 1, v0
	v_lshlrev_b32_e32 v0, 15, v8
	v_and_b32_e32 v0, 0xffff0000, v0
	s_waitcnt vmcnt(6)
	v_lshl_add_u32 v0, v9, 12, v0
	v_and_b32_e32 v1, 1, v8
	v_lshl_or_b32 v0, v1, 6, v0
	s_ashr_i32 s47, s29, 31
	v_lshl_or_b32 v242, v16, 2, s5
	v_mov_b32_e32 v219, v33
	v_lshl_add_u32 v220, v10, 1, v0
	v_mov_b32_e32 v221, v33
	s_mov_b32 s48, 0
	v_add_u32_e32 v243, 0, v17
	s_barrier
	s_branch .LBB0_2565

; #define PG8_STAGE(bufoff, gbase, voff) do { _Pragma("unroll") for (int _i = 0; _i < 2; ++_i) \
;         __builtin_amdgcn_global_load_lds((const unsigned*)((const char*)(gbase) + (voff)[_i]), (LAS unsigned*)(lds + (bufoff) + ldsw + _i * 8192), 16, 0, 0); } while (0)
; #define PG8_LDA(dst, b, h) do { _Pragma("unroll") for (int m = 0; m < 4; ++m) _Pragma("unroll") for (int k = 0; k < 2; ++k) dst[m][k] = *(const LAS bf16x8*)(lds + PG8_SA(b, h) + aoff + m * 2048 + k * 1024); } while (0)
; #define PG8_LDB(dst, b, h) do { _Pragma("unroll") for (int n = 0; n < 2; ++n) _Pragma("unroll") for (int k = 0; k < 2; ++k) dst[n][k] = *(const LAS bf16x8*)(lds + PG8_SB(b, h) + boff + n * 2048 + k * 1024); } while (0)
; #define PG8_MMA(ai, bj, At, Bt) do { __builtin_amdgcn_s_setprio(1); _Pragma("unroll") for (int m = 0; m < 4; ++m) _Pragma("unroll") for (int n = 0; n < 2; ++n) _Pragma("unroll") for (int k = 0; k < 2; ++k) \
;         acc[ai][bj][m][n] = __builtin_amdgcn_mfma_f32_16x16x32_bf16(Bt[n][k], At[m][k], acc[ai][bj][m][n], 0, 0, 0); __builtin_amdgcn_s_setprio(0); } while (0)
; #define PG8_WAIT_L(n) asm volatile("s_waitcnt lgkmcnt(" #n ")" ::: "memory")
; #define PG8_BAR __builtin_amdgcn_s_barrier()
; #define PG8_SCHED __builtin_amdgcn_sched_barrier(0)
; template <class Epi, class Sched>
; __device__ __forceinline__ void gemm_phase(LAS unsigned char* lds, const Gemm g, const Sched& S, const Epi& E, int tid_in) {
;     ...
;             const char* a1 = cA + (size_t)(t + 1) * kstep;
;             const char* a2 = last ? nA : cA + (size_t)(t + 2) * kstep; const char* b2 = last ? nB : cB + (size_t)(t + 2) * kstep;
;             const char* a3 = a2 + kstep; const char* b3 = b2 + kstep;
;             if (last && has_next) S.a_ready(nxt);
;             PG8_LDB(B0, 0, 0); PG8_SCHED; PG8_LDA(At, 0, 0); PG8_STAGE(PG8_SA(1, 1), a1 + hstepA, voffA);
;             PG8_WAIT_L(8); PG8_BAR; PG8_WAIT_L(0); PG8_MMA(0, 0, At, B0); PG8_BAR; PG8_SCHED;
;             PG8_LDB(B1, 0, 1); PG8_STAGE(PG8_SB(0, 0), b2, voffB);
;             PG8_BAR; PG8_WAIT_L(0); PG8_MMA(0, 1, At, B1); PG8_BAR;
;             PG8_LDA(At, 0, 1); PG8_STAGE(PG8_SA(0, 0), a2, voffA);
;             PG8_BAR; PG8_WAIT_L(0); PG8_MMA(1, 0, At, B0); PG8_BAR; PG8_SCHED;
.LBB0_2568:
	s_add_u32 s14, s22, 0xfff80080
	s_addc_u32 s15, s23, -1
	s_add_i32 s52, 0, 0x10000
	v_add_u32_e32 v142, s52, v241
	ds_read_b128 v[130:133], v142
	ds_read_b128 v[134:137], v142 offset:1024
	ds_read_b128 v[138:141], v142 offset:2048
	ds_read_b128 v[142:145], v142 offset:3072
	s_cmp_eq_u32 s51, 28
	s_cselect_b32 s25, s5, s15
	s_cselect_b32 s24, s7, s14
	s_cselect_b32 s15, s13, s50
	s_cselect_b32 s14, s17, s49
	s_add_i32 m0, s39, 0xc000
	ds_read_b128 v[146:149], v243
	ds_read_b128 v[150:153], v243 offset:1024
	ds_read_b128 v[154:157], v243 offset:2048
	ds_read_b128 v[158:161], v243 offset:3072
	ds_read_b128 v[162:165], v243 offset:4096
	ds_read_b128 v[166:169], v243 offset:5120
	ds_read_b128 v[170:173], v243 offset:6144
	ds_read_b128 v[174:177], v243 offset:7168
	global_load_lds_dwordx4 v218, s[22:23]
	s_add_i32 m0, s39, 0xe000
	s_nop 0
	global_load_lds_dwordx4 v220, s[22:23]
	s_waitcnt lgkmcnt(8)
	s_barrier
	s_waitcnt lgkmcnt(0)
	s_setprio 1
	s_waitcnt lgkmcnt(0)
	v_mfma_f32_16x16x32_bf16 v[126:129], v[130:133], v[146:149], v[126:129]
	v_mfma_f32_16x16x32_bf16 v[122:125], v[138:141], v[146:149], v[122:125]
	v_mfma_f32_16x16x32_bf16 v[114:117], v[130:133], v[154:157], v[114:117]
	v_mfma_f32_16x16x32_bf16 v[106:109], v[138:141], v[154:157], v[106:109]
	v_mfma_f32_16x16x32_bf16 v[98:101], v[130:133], v[162:165], v[98:101]
	v_mfma_f32_16x16x32_bf16 v[90:93], v[138:141], v[162:165], v[90:93]
	v_mfma_f32_16x16x32_bf16 v[78:81], v[130:133], v[170:173], v[78:81]
	v_mfma_f32_16x16x32_bf16 v[74:77], v[138:141], v[170:173], v[74:77]
	v_mfma_f32_16x16x32_bf16 v[126:129], v[134:137], v[150:153], v[126:129]
	v_mfma_f32_16x16x32_bf16 v[122:125], v[142:145], v[150:153], v[122:125]
	v_mfma_f32_16x16x32_bf16 v[114:117], v[134:137], v[158:161], v[114:117]
	v_mfma_f32_16x16x32_bf16 v[106:109], v[142:145], v[158:161], v[106:109]
	v_mfma_f32_16x16x32_bf16 v[98:101], v[134:137], v[166:169], v[98:101]
	v_mfma_f32_16x16x32_bf16 v[90:93], v[142:145], v[166:169], v[90:93]
	v_mfma_f32_16x16x32_bf16 v[78:81], v[134:137], v[174:177], v[78:81]
	v_mfma_f32_16x16x32_bf16 v[74:77], v[142:145], v[174:177], v[74:77]
	s_setprio 0
	s_barrier
	s_add_i32 s54, 0, 0x14000
	s_add_i32 s52, s52, s31
	v_add_u32_e32 v190, s54, v241
	v_lshl_add_u64 v[194:195], s[14:15], 0, v[32:33]
	s_mov_b32 m0, s52
	ds_read_b128 v[178:181], v190
	ds_read_b128 v[182:185], v190 offset:1024
	ds_read_b128 v[186:189], v190 offset:2048
	ds_read_b128 v[190:193], v190 offset:3072
	global_load_lds_dwordx4 v32, s[14:15]
	v_lshl_add_u64 v[196:197], s[14:15], 0, v[216:217]
	s_add_i32 m0, s52, 0x2000
	s_nop 0
	global_load_lds_dwordx4 v216, s[14:15]
	s_barrier
	s_waitcnt lgkmcnt(0)
	s_setprio 1
	s_waitcnt lgkmcnt(0)
	v_mfma_f32_16x16x32_bf16 v[118:121], v[178:181], v[146:149], v[118:121]
	v_mfma_f32_16x16x32_bf16 v[110:113], v[186:189], v[146:149], v[110:113]
	v_mfma_f32_16x16x32_bf16 v[102:105], v[178:181], v[154:157], v[102:105]
	v_mfma_f32_16x16x32_bf16 v[94:97], v[186:189], v[154:157], v[94:97]
	v_mfma_f32_16x16x32_bf16 v[86:89], v[178:181], v[162:165], v[86:89]
	v_mfma_f32_16x16x32_bf16 v[82:85], v[186:189], v[162:165], v[82:85]
	v_mfma_f32_16x16x32_bf16 v[70:73], v[178:181], v[170:173], v[70:73]
	v_mfma_f32_16x16x32_bf16 v[66:69], v[186:189], v[170:173], v[66:69]
	v_mfma_f32_16x16x32_bf16 v[118:121], v[182:185], v[150:153], v[118:121]
	v_mfma_f32_16x16x32_bf16 v[110:113], v[190:193], v[150:153], v[110:113]
	v_mfma_f32_16x16x32_bf16 v[102:105], v[182:185], v[158:161], v[102:105]
	v_mfma_f32_16x16x32_bf16 v[94:97], v[190:193], v[158:161], v[94:97]
	v_mfma_f32_16x16x32_bf16 v[86:89], v[182:185], v[166:169], v[86:89]
	v_mfma_f32_16x16x32_bf16 v[82:85], v[190:193], v[166:169], v[82:85]
	v_mfma_f32_16x16x32_bf16 v[70:73], v[182:185], v[174:177], v[70:73]
	v_mfma_f32_16x16x32_bf16 v[66:69], v[190:193], v[174:177], v[66:69]
	s_setprio 0
	s_mov_b32 m0, s39
	v_lshl_add_u64 v[198:199], s[24:25], 0, v[32:33]
	s_barrier
	ds_read_b128 v[146:149], v243 offset:16384
	ds_read_b128 v[150:153], v243 offset:17408
	ds_read_b128 v[154:157], v243 offset:18432
	ds_read_b128 v[158:161], v243 offset:19456
	ds_read_b128 v[162:165], v243 offset:20480
	ds_read_b128 v[166:169], v243 offset:21504
	ds_read_b128 v[170:173], v243 offset:22528
	ds_read_b128 v[174:177], v243 offset:23552
	global_load_lds_dwordx4 v32, s[24:25]
	v_lshl_add_u64 v[200:201], s[24:25], 0, v[216:217]
	s_mov_b32 m0, s40
	s_nop 0
	global_load_lds_dwordx4 v216, s[24:25]
	s_barrier
	s_waitcnt lgkmcnt(0)
	s_setprio 1
	s_waitcnt lgkmcnt(0)
	v_mfma_f32_16x16x32_bf16 v[62:65], v[130:133], v[146:149], v[62:65]
	v_mfma_f32_16x16x32_bf16 v[58:61], v[138:141], v[146:149], v[58:61]
	v_mfma_f32_16x16x32_bf16 v[46:49], v[130:133], v[154:157], v[46:49]
	v_mfma_f32_16x16x32_bf16 v[42:45], v[138:141], v[154:157], v[42:45]
	v_mfma_f32_16x16x32_bf16 v[28:31], v[130:133], v[162:165], v[28:31]
	v_mfma_f32_16x16x32_bf16 v[24:27], v[138:141], v[162:165], v[24:27]
	v_mfma_f32_16x16x32_bf16 v[16:19], v[130:133], v[170:173], v[16:19]
	v_mfma_f32_16x16x32_bf16 v[12:15], v[138:141], v[170:173], v[12:15]
	v_mfma_f32_16x16x32_bf16 v[62:65], v[134:137], v[150:153], v[62:65]
	v_mfma_f32_16x16x32_bf16 v[58:61], v[142:145], v[150:153], v[58:61]
	v_mfma_f32_16x16x32_bf16 v[46:49], v[134:137], v[158:161], v[46:49]
	v_mfma_f32_16x16x32_bf16 v[42:45], v[142:145], v[158:161], v[42:45]
	v_mfma_f32_16x16x32_bf16 v[28:31], v[134:137], v[166:169], v[28:31]
	v_mfma_f32_16x16x32_bf16 v[24:27], v[142:145], v[166:169], v[24:27]
	v_mfma_f32_16x16x32_bf16 v[16:19], v[134:137], v[174:177], v[16:19]
	v_mfma_f32_16x16x32_bf16 v[12:15], v[142:145], v[174:177], v[12:15]
	s_setprio 0
	s_barrier
; #define PG8_STAGE(bufoff, gbase, voff) do { _Pragma("unroll") for (int _i = 0; _i < 2; ++_i) \
;         __builtin_amdgcn_global_load_lds((const unsigned*)((const char*)(gbase) + (voff)[_i]), (LAS unsigned*)(lds + (bufoff) + ldsw + _i * 8192), 16, 0, 0); } while (0)
; #define PG8_LDA(dst, b, h) do { _Pragma("unroll") for (int m = 0; m < 4; ++m) _Pragma("unroll") for (int k = 0; k < 2; ++k) dst[m][k] = *(const LAS bf16x8*)(lds + PG8_SA(b, h) + aoff + m * 2048 + k * 1024); } while (0)
; #define PG8_LDB(dst, b, h) do { _Pragma("unroll") for (int n = 0; n < 2; ++n) _Pragma("unroll") for (int k = 0; k < 2; ++k) dst[n][k] = *(const LAS bf16x8*)(lds + PG8_SB(b, h) + boff + n * 2048 + k * 1024); } while (0)
; #define PG8_MMA(ai, bj, At, Bt) do { __builtin_amdgcn_s_setprio(1); _Pragma("unroll") for (int m = 0; m < 4; ++m) _Pragma("unroll") for (int n = 0; n < 2; ++n) _Pragma("unroll") for (int k = 0; k < 2; ++k) \
;         acc[ai][bj][m][n] = __builtin_amdgcn_mfma_f32_16x16x32_bf16(Bt[n][k], At[m][k], acc[ai][bj][m][n], 0, 0, 0); __builtin_amdgcn_s_setprio(0); } while (0)
; #define PG8_WAIT_V(n) asm volatile("s_waitcnt vmcnt(" #n ")" ::: "memory")
; #define PG8_WAIT_L(n) asm volatile("s_waitcnt lgkmcnt(" #n ")" ::: "memory")
; #define PG8_BAR __builtin_amdgcn_s_barrier()
; #define PG8_SCHED __builtin_amdgcn_sched_barrier(0)
; template <class Epi, class Sched>
; __device__ __forceinline__ void gemm_phase(LAS unsigned char* lds, const Gemm g, const Sched& S, const Epi& E, int tid_in) {
;     ...
;             PG8_STAGE(PG8_SB(0, 1), b2 + hstepB, voffB);
;             PG8_WAIT_V(6); PG8_BAR; PG8_MMA(1, 1, At, B1); PG8_BAR;
;             PG8_LDB(B0, 1, 0); PG8_SCHED; PG8_LDA(At, 1, 0); PG8_STAGE(PG8_SA(0, 1), a2 + hstepA, voffA);
;             PG8_WAIT_L(8); PG8_BAR; PG8_WAIT_L(0); PG8_MMA(0, 0, At, B0); PG8_BAR; PG8_SCHED;
;             PG8_LDB(B1, 1, 1); PG8_STAGE(PG8_SB(1, 0), b3, voffB);
;             PG8_BAR; PG8_WAIT_L(0); PG8_MMA(0, 1, At, B1); PG8_BAR;
;             PG8_LDA(At, 1, 1); PG8_STAGE(PG8_SA(1, 0), a3, voffA);
	s_add_u32 s52, s14, 0x80000
	s_addc_u32 s53, s15, 0
	s_add_i32 s54, s54, s31
	s_mov_b32 m0, s54
	s_nop 0
	global_load_lds_dwordx4 v32, s[52:53]
	s_add_i32 m0, s54, 0x2000
	s_nop 0
	global_load_lds_dwordx4 v216, s[52:53]
	s_waitcnt vmcnt(6)
	s_barrier
	s_setprio 1
	v_mfma_f32_16x16x32_bf16 v[54:57], v[178:181], v[146:149], v[54:57]
	v_mfma_f32_16x16x32_bf16 v[50:53], v[186:189], v[146:149], v[50:53]
	v_mfma_f32_16x16x32_bf16 v[38:41], v[178:181], v[154:157], v[38:41]
	v_mfma_f32_16x16x32_bf16 v[34:37], v[186:189], v[154:157], v[34:37]
	v_mfma_f32_16x16x32_bf16 v[20:23], v[178:181], v[162:165], v[20:23]
	v_mfma_f32_16x16x32_bf16 v[8:11], v[186:189], v[162:165], v[8:11]
	v_mfma_f32_16x16x32_bf16 v[4:7], v[178:181], v[170:173], v[4:7]
	v_mfma_f32_16x16x32_bf16 v[0:3], v[186:189], v[170:173], v[0:3]
	v_mfma_f32_16x16x32_bf16 v[54:57], v[182:185], v[150:153], v[54:57]
	v_mfma_f32_16x16x32_bf16 v[50:53], v[190:193], v[150:153], v[50:53]
	v_mfma_f32_16x16x32_bf16 v[38:41], v[182:185], v[158:161], v[38:41]
	v_mfma_f32_16x16x32_bf16 v[34:37], v[190:193], v[158:161], v[34:37]
	v_mfma_f32_16x16x32_bf16 v[20:23], v[182:185], v[166:169], v[20:23]
	v_mfma_f32_16x16x32_bf16 v[8:11], v[190:193], v[166:169], v[8:11]
	v_mfma_f32_16x16x32_bf16 v[4:7], v[182:185], v[174:177], v[4:7]
	v_mfma_f32_16x16x32_bf16 v[0:3], v[190:193], v[174:177], v[0:3]
	s_setprio 0
	s_add_i32 s52, 0, 0x18000
	v_add_u32_e32 v142, s52, v241
	s_barrier
	ds_read_b128 v[130:133], v142
	ds_read_b128 v[134:137], v142 offset:1024
	ds_read_b128 v[138:141], v142 offset:2048
	ds_read_b128 v[142:145], v142 offset:3072
	s_add_u32 s24, s24, 0x80000
	s_addc_u32 s25, s25, 0
	s_mov_b32 m0, s41
	ds_read_b128 v[146:149], v243 offset:32768
	ds_read_b128 v[150:153], v243 offset:33792
	ds_read_b128 v[154:157], v243 offset:34816
	ds_read_b128 v[158:161], v243 offset:35840
	ds_read_b128 v[162:165], v243 offset:36864
	ds_read_b128 v[166:169], v243 offset:37888
	ds_read_b128 v[170:173], v243 offset:38912
	ds_read_b128 v[174:177], v243 offset:39936
	global_load_lds_dwordx4 v32, s[24:25]
	s_mov_b32 m0, s42
	s_nop 0
	global_load_lds_dwordx4 v216, s[24:25]
	s_waitcnt lgkmcnt(8)
	s_barrier
	s_waitcnt lgkmcnt(0)
	s_setprio 1
	s_waitcnt lgkmcnt(0)
	v_mfma_f32_16x16x32_bf16 v[126:129], v[130:133], v[146:149], v[126:129]
	v_mfma_f32_16x16x32_bf16 v[122:125], v[138:141], v[146:149], v[122:125]
	v_mfma_f32_16x16x32_bf16 v[114:117], v[130:133], v[154:157], v[114:117]
	v_mfma_f32_16x16x32_bf16 v[106:109], v[138:141], v[154:157], v[106:109]
	v_mfma_f32_16x16x32_bf16 v[98:101], v[130:133], v[162:165], v[98:101]
	v_mfma_f32_16x16x32_bf16 v[90:93], v[138:141], v[162:165], v[90:93]
	v_mfma_f32_16x16x32_bf16 v[78:81], v[130:133], v[170:173], v[78:81]
	v_mfma_f32_16x16x32_bf16 v[74:77], v[138:141], v[170:173], v[74:77]
	v_mfma_f32_16x16x32_bf16 v[126:129], v[134:137], v[150:153], v[126:129]
	v_mfma_f32_16x16x32_bf16 v[122:125], v[142:145], v[150:153], v[122:125]
	v_mfma_f32_16x16x32_bf16 v[114:117], v[134:137], v[158:161], v[114:117]
	v_mfma_f32_16x16x32_bf16 v[106:109], v[142:145], v[158:161], v[106:109]
	v_mfma_f32_16x16x32_bf16 v[98:101], v[134:137], v[166:169], v[98:101]
	v_mfma_f32_16x16x32_bf16 v[90:93], v[142:145], v[166:169], v[90:93]
	v_mfma_f32_16x16x32_bf16 v[78:81], v[134:137], v[174:177], v[78:81]
	v_mfma_f32_16x16x32_bf16 v[74:77], v[142:145], v[174:177], v[74:77]
	s_setprio 0
	s_barrier
	s_add_i32 s24, 0, 0x1c000
	s_add_i32 s25, s52, s31
	v_add_u32_e32 v190, s24, v241
	v_lshl_add_u64 v[194:195], v[194:195], 0, s[76:77]
	s_mov_b32 m0, s25
	ds_read_b128 v[178:181], v190
	ds_read_b128 v[182:185], v190 offset:1024
	ds_read_b128 v[186:189], v190 offset:2048
	ds_read_b128 v[190:193], v190 offset:3072
	global_load_lds_dwordx4 v[194:195], off
	v_lshl_add_u64 v[194:195], v[196:197], 0, s[76:77]
	s_add_i32 m0, s25, 0x2000
	s_nop 0
	global_load_lds_dwordx4 v[194:195], off
	s_barrier
	s_waitcnt lgkmcnt(0)
	s_setprio 1
	s_waitcnt lgkmcnt(0)
	v_mfma_f32_16x16x32_bf16 v[118:121], v[178:181], v[146:149], v[118:121]
	v_mfma_f32_16x16x32_bf16 v[110:113], v[186:189], v[146:149], v[110:113]
	v_mfma_f32_16x16x32_bf16 v[102:105], v[178:181], v[154:157], v[102:105]
	v_mfma_f32_16x16x32_bf16 v[94:97], v[186:189], v[154:157], v[94:97]
	v_mfma_f32_16x16x32_bf16 v[86:89], v[178:181], v[162:165], v[86:89]
	v_mfma_f32_16x16x32_bf16 v[82:85], v[186:189], v[162:165], v[82:85]
	v_mfma_f32_16x16x32_bf16 v[70:73], v[178:181], v[170:173], v[70:73]
	v_mfma_f32_16x16x32_bf16 v[66:69], v[186:189], v[170:173], v[66:69]
	v_mfma_f32_16x16x32_bf16 v[118:121], v[182:185], v[150:153], v[118:121]
	v_mfma_f32_16x16x32_bf16 v[110:113], v[190:193], v[150:153], v[110:113]
	v_mfma_f32_16x16x32_bf16 v[102:105], v[182:185], v[158:161], v[102:105]
	v_mfma_f32_16x16x32_bf16 v[94:97], v[190:193], v[158:161], v[94:97]
	v_mfma_f32_16x16x32_bf16 v[86:89], v[182:185], v[166:169], v[86:89]
	v_mfma_f32_16x16x32_bf16 v[82:85], v[190:193], v[166:169], v[82:85]
	v_mfma_f32_16x16x32_bf16 v[70:73], v[182:185], v[174:177], v[70:73]
	v_mfma_f32_16x16x32_bf16 v[66:69], v[190:193], v[174:177], v[66:69]
	s_setprio 0
	s_mov_b32 m0, s45
	v_lshl_add_u64 v[194:195], v[198:199], 0, s[76:77]
	s_barrier
	ds_read_b128 v[146:149], v243 offset:49152
	ds_read_b128 v[150:153], v243 offset:50176
	ds_read_b128 v[154:157], v243 offset:51200
	ds_read_b128 v[158:161], v243 offset:52224
	ds_read_b128 v[162:165], v243 offset:53248
	ds_read_b128 v[166:169], v243 offset:54272
	ds_read_b128 v[170:173], v243 offset:55296
	ds_read_b128 v[174:177], v243 offset:56320
	global_load_lds_dwordx4 v[194:195], off
	v_lshl_add_u64 v[194:195], v[200:201], 0, s[76:77]
	s_mov_b32 m0, s46
	s_nop 0
	global_load_lds_dwordx4 v[194:195], off
	s_barrier
; #define PG8_STAGE(bufoff, gbase, voff) do { _Pragma("unroll") for (int _i = 0; _i < 2; ++_i) \
;         __builtin_amdgcn_global_load_lds((const unsigned*)((const char*)(gbase) + (voff)[_i]), (LAS unsigned*)(lds + (bufoff) + ldsw + _i * 8192), 16, 0, 0); } while (0)
; #define PG8_MMA(ai, bj, At, Bt) do { __builtin_amdgcn_s_setprio(1); _Pragma("unroll") for (int m = 0; m < 4; ++m) _Pragma("unroll") for (int n = 0; n < 2; ++n) _Pragma("unroll") for (int k = 0; k < 2; ++k) \
;         acc[ai][bj][m][n] = __builtin_amdgcn_mfma_f32_16x16x32_bf16(Bt[n][k], At[m][k], acc[ai][bj][m][n], 0, 0, 0); __builtin_amdgcn_s_setprio(0); } while (0)
; #define PG8_WAIT_V(n) asm volatile("s_waitcnt vmcnt(" #n ")" ::: "memory")
; #define PG8_WAIT_L(n) asm volatile("s_waitcnt lgkmcnt(" #n ")" ::: "memory")
; #define PG8_BAR __builtin_amdgcn_s_barrier()
;     __device__ __forceinline__ void operator()(const f32x4 (&acc)[2][2][4][2], const Unit& u, int wr, int wc, int fr, int fq) const {
;         const int row0 = u.pm * BM + wr * 64 + fr, col0 = u.pn * BM + wc * 32 + 4 * fq;
;         const int vs = u.pm < 32 ? 0 : (u.pm < 64 ? 1 : 2);
;         const float* gate = modl + (size_t)vs * 12288 + chunk * 2048 + col0;
;         f32x4 gv[2][2];
; #pragma unroll
;         for (int bj = 0; bj < 2; ++bj)
; #pragma unroll
;             for (int n = 0; n < 2; ++n) gv[bj][n] = *(const f32x4*)(gate + bj * HALF + n * 16);
; #pragma unroll
;         for (int ai = 0; ai < 2; ++ai) {
;             f32x4 xo[4][2][2];
; #pragma unroll
;             for (int m = 0; m < 4; ++m) { const int row = row0 + ai * HALF + m * 16;
;                 const float* srcp = (vs < 2 ? Rlat + (size_t)row * DM : Rctx + (size_t)(row - TL) * DM) + col0;
; #pragma unroll
;                 for (int bj = 0; bj < 2; ++bj)
; #pragma unroll
;                     for (int n = 0; n < 2; ++n) xo[m][bj][n] = *(const f32x4*)(srcp + bj * HALF + n * 16); }
; template <class Epi, class Sched>
; __device__ __forceinline__ void gemm_phase(LAS unsigned char* lds, const Gemm g, const Sched& S, const Epi& E, int tid_in) {
;     ...
;             PG8_BAR; PG8_WAIT_L(0); PG8_MMA(1, 0, At, B0); PG8_BAR; PG8_SCHED;
;             PG8_STAGE(PG8_SB(1, 1), b3 + hstepB, voffB);
;             PG8_WAIT_V(6); PG8_BAR; PG8_MMA(1, 1, At, B1); PG8_BAR;
;         }
;         E(acc, cur, wr, wc, fr, fq); S.done(cur);
	s_waitcnt lgkmcnt(0)
	s_setprio 1
	s_waitcnt lgkmcnt(0)
	v_mfma_f32_16x16x32_bf16 v[62:65], v[130:133], v[146:149], v[62:65]
	v_mfma_f32_16x16x32_bf16 v[58:61], v[138:141], v[146:149], v[58:61]
	v_mfma_f32_16x16x32_bf16 v[46:49], v[130:133], v[154:157], v[46:49]
	v_mfma_f32_16x16x32_bf16 v[42:45], v[138:141], v[154:157], v[42:45]
	v_mfma_f32_16x16x32_bf16 v[28:31], v[130:133], v[162:165], v[28:31]
	v_mfma_f32_16x16x32_bf16 v[24:27], v[138:141], v[162:165], v[24:27]
	v_mfma_f32_16x16x32_bf16 v[16:19], v[130:133], v[170:173], v[16:19]
	v_mfma_f32_16x16x32_bf16 v[12:15], v[138:141], v[170:173], v[12:15]
	v_mfma_f32_16x16x32_bf16 v[62:65], v[134:137], v[150:153], v[62:65]
	v_mfma_f32_16x16x32_bf16 v[58:61], v[142:145], v[150:153], v[58:61]
	v_mfma_f32_16x16x32_bf16 v[46:49], v[134:137], v[158:161], v[46:49]
	v_mfma_f32_16x16x32_bf16 v[42:45], v[142:145], v[158:161], v[42:45]
	v_mfma_f32_16x16x32_bf16 v[28:31], v[134:137], v[166:169], v[28:31]
	v_mfma_f32_16x16x32_bf16 v[24:27], v[142:145], v[166:169], v[24:27]
	v_mfma_f32_16x16x32_bf16 v[16:19], v[134:137], v[174:177], v[16:19]
	v_mfma_f32_16x16x32_bf16 v[12:15], v[142:145], v[174:177], v[12:15]
	s_setprio 0
	s_barrier
	s_add_u32 s14, s14, 0x80080
	s_addc_u32 s15, s15, 0
	s_add_i32 s24, s24, s31
	s_mov_b32 m0, s24
	s_nop 0
	global_load_lds_dwordx4 v32, s[14:15]
	v_lshl_add_u64 v[130:131], s[14:15], 0, v[216:217]
	s_add_i32 m0, s24, 0x2000
	s_nop 0
	global_load_lds_dwordx4 v216, s[14:15]
	s_waitcnt vmcnt(6)
	s_barrier
	s_setprio 1
	v_mfma_f32_16x16x32_bf16 v[54:57], v[178:181], v[146:149], v[54:57]
	v_mfma_f32_16x16x32_bf16 v[50:53], v[186:189], v[146:149], v[50:53]
	v_mfma_f32_16x16x32_bf16 v[38:41], v[178:181], v[154:157], v[38:41]
	v_mfma_f32_16x16x32_bf16 v[34:37], v[186:189], v[154:157], v[34:37]
	v_mfma_f32_16x16x32_bf16 v[20:23], v[178:181], v[162:165], v[20:23]
	v_mfma_f32_16x16x32_bf16 v[8:11], v[186:189], v[162:165], v[8:11]
	v_mfma_f32_16x16x32_bf16 v[4:7], v[178:181], v[170:173], v[4:7]
	v_mfma_f32_16x16x32_bf16 v[0:3], v[186:189], v[170:173], v[0:3]
	v_mfma_f32_16x16x32_bf16 v[54:57], v[182:185], v[150:153], v[54:57]
	v_mfma_f32_16x16x32_bf16 v[50:53], v[190:193], v[150:153], v[50:53]
	v_mfma_f32_16x16x32_bf16 v[38:41], v[182:185], v[158:161], v[38:41]
	v_mfma_f32_16x16x32_bf16 v[34:37], v[190:193], v[158:161], v[34:37]
	v_mfma_f32_16x16x32_bf16 v[20:23], v[182:185], v[166:169], v[20:23]
	v_mfma_f32_16x16x32_bf16 v[8:11], v[190:193], v[166:169], v[8:11]
	v_mfma_f32_16x16x32_bf16 v[4:7], v[182:185], v[174:177], v[4:7]
	v_mfma_f32_16x16x32_bf16 v[0:3], v[190:193], v[174:177], v[0:3]
	s_setprio 0
	s_add_i32 s51, s51, 2
	s_add_u32 s22, s22, 0x100
	s_addc_u32 s23, s23, 0
	s_add_u32 s49, s49, 0x100
	s_addc_u32 s50, s50, 0
	s_cmp_gt_u32 s51, 29
	s_barrier
	s_cbranch_scc0 .LBB0_2568
	s_cmp_gt_i32 s6, 63
	s_cselect_b64 s[14:15], -1, 0
	s_cmp_lt_i32 s6, 64
	v_lshl_or_b32 v130, s4, 8, v242
	s_cselect_b64 s[4:5], -1, 0
	s_and_b64 vcc, s[4:5], exec
	s_cselect_b32 s7, s95, 0x6000
	s_cselect_b32 s22, s8, s10
	s_cselect_b32 s23, s9, s11
	s_cmp_gt_i32 s6, 31
	v_lshl_add_u32 v224, s6, 8, v240
	s_cselect_b32 s6, s7, 0
	v_add_u32_e32 v131, 0xffffc000, v224
	s_lshl_b32 s6, s6, 2
	v_cndmask_b32_e64 v146, v131, v224, s[4:5]
	s_add_u32 s6, s43, s6
	v_ashrrev_i32_e32 v131, 31, v130
	s_addc_u32 s7, s44, 0
	v_lshlrev_b64 v[222:223], 2, v[130:131]
	v_lshl_add_u64 v[130:131], s[6:7], 0, v[222:223]
	s_mov_b64 s[6:7], 0x104000
	v_ashrrev_i32_e32 v147, 31, v146
	v_lshl_add_u64 v[132:133], v[130:131], 0, s[6:7]
	s_mov_b32 s6, 0x104000
	v_lshlrev_b64 v[146:147], 13, v[146:147]
	v_add_co_u32_e64 v130, s[6:7], s6, v130
	v_lshl_add_u64 v[146:147], s[22:23], 0, v[146:147]
	s_nop 0
	v_addc_co_u32_e64 v131, s[6:7], 0, v131, s[6:7]
	v_lshl_add_u64 v[146:147], v[146:147], 0, v[222:223]
	global_load_dwordx4 v[138:141], v[132:133], off offset:64
	global_load_dwordx4 v[134:137], v[132:133], off offset:512
	global_load_dwordx4 v[142:145], v[130:131], off
	s_nop 0
	global_load_dwordx4 v[130:133], v[132:133], off offset:576
	s_nop 0
	global_load_dwordx4 v[206:209], v[146:147], off
	global_load_dwordx4 v[202:205], v[146:147], off offset:64
	global_load_dwordx4 v[198:201], v[146:147], off offset:512
	global_load_dwordx4 v[194:197], v[146:147], off offset:576
	v_or_b32_e32 v226, 16, v224
	v_add_u32_e32 v146, 0xffffc010, v224
	v_cndmask_b32_e64 v146, v146, v226, s[4:5]
	v_ashrrev_i32_e32 v147, 31, v146
	v_lshlrev_b64 v[146:147], 13, v[146:147]
	v_lshl_add_u64 v[146:147], s[22:23], 0, v[146:147]
	v_lshl_add_u64 v[146:147], v[146:147], 0, v[222:223]
	global_load_dwordx4 v[190:193], v[146:147], off
	global_load_dwordx4 v[186:189], v[146:147], off offset:64
	global_load_dwordx4 v[182:185], v[146:147], off offset:512
	global_load_dwordx4 v[178:181], v[146:147], off offset:576
	v_or_b32_e32 v230, 32, v224
	v_add_u32_e32 v146, 0xffffc020, v224
	v_cndmask_b32_e64 v146, v146, v230, s[4:5]
	v_ashrrev_i32_e32 v147, 31, v146
	v_lshlrev_b64 v[146:147], 13, v[146:147]
	v_lshl_add_u64 v[146:147], s[22:23], 0, v[146:147]
	v_lshl_add_u64 v[146:147], v[146:147], 0, v[222:223]
	global_load_dwordx4 v[174:177], v[146:147], off
	global_load_dwordx4 v[170:173], v[146:147], off offset:64
	global_load_dwordx4 v[166:169], v[146:147], off offset:512
	global_load_dwordx4 v[162:165], v[146:147], off offset:576
	v_or_b32_e32 v146, 48, v224
	s_mov_b64 s[6:7], -1
	v_ashrrev_i32_e32 v225, 31, v224
	v_ashrrev_i32_e32 v147, 31, v146
	s_cbranch_vccnz .LBB0_2571
	v_lshlrev_b64 v[148:149], 13, v[224:225]
	s_mov_b32 s6, 0xf8060000
	v_lshl_add_u64 v[148:149], s[10:11], 0, v[148:149]
	s_mov_b32 s7, -1
	v_lshl_add_u64 v[148:149], v[148:149], 0, s[6:7]
	v_lshlrev_b64 v[232:233], 13, v[146:147]
	s_mov_b64 s[6:7], 0

;     __device__ bool next(int i, Unit& u) const { if (i != 0) return false; u.pm = pm; u.pn = pn; return true; }
; #define PG8_STAGE(bufoff, gbase, voff) do { _Pragma("unroll") for (int _i = 0; _i < 2; ++_i) \
;         __builtin_amdgcn_global_load_lds((const unsigned*)((const char*)(gbase) + (voff)[_i]), (LAS unsigned*)(lds + (bufoff) + ldsw + _i * 8192), 16, 0, 0); } while (0)
; #define PG8_WAIT_V(n) asm volatile("s_waitcnt vmcnt(" #n ")" ::: "memory")
; #define PG8_BAR __builtin_amdgcn_s_barrier()
; template <class Epi, class Sched>
; __device__ __forceinline__ void gemm_phase(LAS unsigned char* lds, const Gemm g, const Sched& S, const Epi& E, int tid_in) {
;     ...
;     for (int i = 0; i < 2; ++i) { int R, C; stage_rc(tid * 16 + i * 8192, R, C); const int Rb = Epi::PERM ? ((R & ~31) + perm32(R & 31)) : R;
;         voffA[i] = (unsigned)(R * lda + C) * 2u; voffB[i] = (unsigned)(Rb * K + C) * 2u; }
;     const size_t kstep = (size_t)(BK * 2);
;     const size_t hstepA = (size_t)HALF * lda * 2, hstepB = (size_t)HALF * K * 2;
;     const size_t tstepA = 2 * hstepA, tstepB = 2 * hstepB;
;     const unsigned ldsw = (unsigned)wid * 1024u;
;     const int aoff = lds_byte(wr * 64 + fr, fq * 8), boff = lds_byte(wc * 32 + fr, fq * 8);
;     ...
;     Unit cur, nxt; int ui = 0;
;     if (!S.next(0, cur)) return;
;     f32x4 acc[2][2][4][2];
; #pragma unroll
;     for (int a = 0; a < 2; ++a)
; #pragma unroll
;         for (int b = 0; b < 2; ++b)
; #pragma unroll
;             for (int m = 0; m < 4; ++m)
; #pragma unroll
;                 for (int n = 0; n < 2; ++n) acc[a][b][m][n] = (f32x4){0.f, 0.f, 0.f, 0.f};
;     bf16x8 At[4][2], B0[2][2], B1[2][2];
;     const char* cA = (const char*)g.A + (size_t)cur.pm * tstepA; const char* cB = (const char*)g.Bt + (size_t)cur.pn * tstepB;
;     S.a_ready(cur);
;     PG8_STAGE(PG8_SB(0, 0), cB, voffB); PG8_STAGE(PG8_SA(0, 0), cA, voffA); PG8_STAGE(PG8_SB(0, 1), cB + hstepB, voffB); PG8_STAGE(PG8_SA(0, 1), cA + hstepA, voffA);
;     if (wr == 1) PG8_BAR;
;     PG8_WAIT_V(4); PG8_BAR;
;     PG8_STAGE(PG8_SB(1, 0), cB + kstep, voffB); PG8_STAGE(PG8_SA(1, 0), cA + kstep, voffA); PG8_STAGE(PG8_SB(1, 1), cB + hstepB + kstep, voffB);
;     PG8_WAIT_V(6); PG8_BAR;
.LBB0_2710:
	v_lshrrev_b32_e32 v16, 1, v14
	v_and_b32_e32 v16, 24, v16
	s_add_u32 s0, s0, 0x5561c100
	v_and_b32_e32 v15, 15, v14
	v_lshlrev_b32_e32 v17, 1, v16
	v_lshlrev_b32_e32 v14, 2, v14
	s_addc_u32 s1, s1, 0
	v_lshl_or_b32 v142, s2, 6, v15
	v_lshl_or_b32 v15, v15, 6, v17
	s_lshl_b32 s2, s2, 13
	v_and_b32_e32 v14, 32, v14
	v_bitop3_b32 v17, v15, s2, v14 bitop3:0xde
	s_lshl_b32 s2, s23, 5
	s_and_b32 s4, s2, 0x60
	s_add_i32 m0, s9, 0x18000
	v_lshl_add_u64 v[6:7], v[6:7], 0, s[76:77]
	s_lshl_b32 s2, s4, 7
	s_waitcnt vmcnt(4)
	s_barrier
	global_load_lds_dwordx4 v[6:7], off
	v_lshl_add_u64 v[4:5], v[4:5], 0, s[76:77]
	s_add_i32 m0, s9, 0x1a000
	s_add_i32 s37, s9, 0x8000
	s_add_i32 s38, s9, 0xa000
	v_bitop3_b32 v143, v15, s2, v14 bitop3:0xde
	global_load_lds_dwordx4 v[4:5], off
	v_lshl_add_u64 v[2:3], v[2:3], 0, s[76:77]
	s_mov_b32 m0, s37
	s_add_u32 s2, s14, 0x80080
	global_load_lds_dwordx4 v[2:3], off
	v_lshl_add_u64 v[0:1], v[0:1], 0, s[76:77]
	s_mov_b32 m0, s38
	s_addc_u32 s3, s15, 0
	global_load_lds_dwordx4 v[0:1], off
	s_add_i32 m0, s9, 0x1c000
	global_load_lds_dwordx4 v32, s[2:3]
	v_lshl_add_u64 v[0:1], s[2:3], 0, v[130:131]
	s_add_i32 m0, s9, 0x1e000
	s_ashr_i32 s39, s25, 31
	global_load_lds_dwordx4 v130, s[2:3]
	v_lshlrev_b32_e32 v0, 15, v11
	v_and_b32_e32 v0, 0xffff0000, v0
	v_lshl_add_u32 v0, v12, 12, v0
	v_and_b32_e32 v1, 1, v11
	v_lshl_or_b32 v0, v1, 6, v0
	v_lshl_add_u32 v136, v13, 1, v0
	v_lshlrev_b32_e32 v0, 15, v8
	v_and_b32_e32 v0, 0xffff0000, v0
	s_waitcnt vmcnt(6)
	v_lshl_add_u32 v0, v9, 12, v0
	v_and_b32_e32 v1, 1, v8
	v_lshl_or_b32 v0, v1, 6, v0
	v_or_b32_e32 v144, s4, v16
	v_mov_b32_e32 v137, v33
	v_lshl_add_u32 v138, v10, 1, v0
	v_mov_b32_e32 v139, v33
	s_mov_b32 s40, 0
	v_add_u32_e32 v145, 0, v17
	s_barrier

; #define PG8_STAGE(bufoff, gbase, voff) do { _Pragma("unroll") for (int _i = 0; _i < 2; ++_i) \
;         __builtin_amdgcn_global_load_lds((const unsigned*)((const char*)(gbase) + (voff)[_i]), (LAS unsigned*)(lds + (bufoff) + ldsw + _i * 8192), 16, 0, 0); } while (0)
; #define PG8_LDA(dst, b, h) do { _Pragma("unroll") for (int m = 0; m < 4; ++m) _Pragma("unroll") for (int k = 0; k < 2; ++k) dst[m][k] = *(const LAS bf16x8*)(lds + PG8_SA(b, h) + aoff + m * 2048 + k * 1024); } while (0)
; #define PG8_LDB(dst, b, h) do { _Pragma("unroll") for (int n = 0; n < 2; ++n) _Pragma("unroll") for (int k = 0; k < 2; ++k) dst[n][k] = *(const LAS bf16x8*)(lds + PG8_SB(b, h) + boff + n * 2048 + k * 1024); } while (0)
; #define PG8_MMA(ai, bj, At, Bt) do { __builtin_amdgcn_s_setprio(1); _Pragma("unroll") for (int m = 0; m < 4; ++m) _Pragma("unroll") for (int n = 0; n < 2; ++n) _Pragma("unroll") for (int k = 0; k < 2; ++k) \
;         acc[ai][bj][m][n] = __builtin_amdgcn_mfma_f32_16x16x32_bf16(Bt[n][k], At[m][k], acc[ai][bj][m][n], 0, 0, 0); __builtin_amdgcn_s_setprio(0); } while (0)
; #define PG8_WAIT_L(n) asm volatile("s_waitcnt lgkmcnt(" #n ")" ::: "memory")
; #define PG8_BAR __builtin_amdgcn_s_barrier()
; #define PG8_SCHED __builtin_amdgcn_sched_barrier(0)
; template <class Epi, class Sched>
; __device__ __forceinline__ void gemm_phase(LAS unsigned char* lds, const Gemm g, const Sched& S, const Epi& E, int tid_in) {
;     ...
;             const char* a1 = cA + (size_t)(t + 1) * kstep;
;             const char* a2 = last ? nA : cA + (size_t)(t + 2) * kstep; const char* b2 = last ? nB : cB + (size_t)(t + 2) * kstep;
;             const char* a3 = a2 + kstep; const char* b3 = b2 + kstep;
;             if (last && has_next) S.a_ready(nxt);
;             PG8_LDB(B0, 0, 0); PG8_SCHED; PG8_LDA(At, 0, 0); PG8_STAGE(PG8_SA(1, 1), a1 + hstepA, voffA);
;             PG8_WAIT_L(8); PG8_BAR; PG8_WAIT_L(0); PG8_MMA(0, 0, At, B0); PG8_BAR; PG8_SCHED;
;             PG8_LDB(B1, 0, 1); PG8_STAGE(PG8_SB(0, 0), b2, voffB);
;             PG8_BAR; PG8_WAIT_L(0); PG8_MMA(0, 1, At, B1); PG8_BAR;
;             PG8_LDA(At, 0, 1); PG8_STAGE(PG8_SA(0, 0), a2, voffA);
;             PG8_BAR; PG8_WAIT_L(0); PG8_MMA(1, 0, At, B0); PG8_BAR; PG8_SCHED;
.LBB0_2714:
	s_add_u32 s14, s18, 0xfff80080
	s_addc_u32 s15, s19, -1
	s_add_i32 s46, 0, 0x10000
	v_add_u32_e32 v140, s46, v143
	ds_read_b128 v[146:149], v140
	ds_read_b128 v[150:153], v140 offset:1024
	ds_read_b128 v[154:157], v140 offset:2048
	ds_read_b128 v[158:161], v140 offset:3072
	s_cmp_eq_u32 s45, 28
	s_cselect_b32 s21, s7, s15
	s_cselect_b32 s20, s41, s14
	s_cselect_b32 s15, s5, s44
	s_cselect_b32 s14, s42, s43
	s_add_i32 m0, s9, 0xc000
	ds_read_b128 v[162:165], v145
	ds_read_b128 v[166:169], v145 offset:1024
	ds_read_b128 v[170:173], v145 offset:2048
	ds_read_b128 v[174:177], v145 offset:3072
	ds_read_b128 v[178:181], v145 offset:4096
	ds_read_b128 v[182:185], v145 offset:5120
	ds_read_b128 v[186:189], v145 offset:6144
	ds_read_b128 v[190:193], v145 offset:7168
	global_load_lds_dwordx4 v136, s[18:19]
	v_lshl_add_u64 v[140:141], s[18:19], 0, v[138:139]
	s_add_i32 m0, s9, 0xe000
	s_nop 0
	global_load_lds_dwordx4 v138, s[18:19]
	s_waitcnt lgkmcnt(8)
	s_barrier
	s_waitcnt lgkmcnt(0)
	s_setprio 1
	s_waitcnt lgkmcnt(0)
	v_mfma_f32_16x16x32_bf16 v[126:129], v[146:149], v[162:165], v[126:129]
	v_mfma_f32_16x16x32_bf16 v[122:125], v[154:157], v[162:165], v[122:125]
	v_mfma_f32_16x16x32_bf16 v[118:121], v[146:149], v[170:173], v[118:121]
	v_mfma_f32_16x16x32_bf16 v[110:113], v[154:157], v[170:173], v[110:113]
	v_mfma_f32_16x16x32_bf16 v[102:105], v[146:149], v[178:181], v[102:105]
	v_mfma_f32_16x16x32_bf16 v[94:97], v[154:157], v[178:181], v[94:97]
	v_mfma_f32_16x16x32_bf16 v[86:89], v[146:149], v[186:189], v[86:89]
	v_mfma_f32_16x16x32_bf16 v[78:81], v[154:157], v[186:189], v[78:81]
	v_mfma_f32_16x16x32_bf16 v[126:129], v[150:153], v[166:169], v[126:129]
	v_mfma_f32_16x16x32_bf16 v[122:125], v[158:161], v[166:169], v[122:125]
	v_mfma_f32_16x16x32_bf16 v[118:121], v[150:153], v[174:177], v[118:121]
	v_mfma_f32_16x16x32_bf16 v[110:113], v[158:161], v[174:177], v[110:113]
	v_mfma_f32_16x16x32_bf16 v[102:105], v[150:153], v[182:185], v[102:105]
	v_mfma_f32_16x16x32_bf16 v[94:97], v[158:161], v[182:185], v[94:97]
	v_mfma_f32_16x16x32_bf16 v[86:89], v[150:153], v[190:193], v[86:89]
	v_mfma_f32_16x16x32_bf16 v[78:81], v[158:161], v[190:193], v[78:81]
	s_setprio 0
	s_barrier
	s_add_i32 s48, 0, 0x14000
	v_add_u32_e32 v140, s48, v143
	s_add_i32 s46, s46, s31
	ds_read_b128 v[194:197], v140
	ds_read_b128 v[198:201], v140 offset:1024
	ds_read_b128 v[202:205], v140 offset:2048
	ds_read_b128 v[206:209], v140 offset:3072
	v_lshl_add_u64 v[140:141], s[14:15], 0, v[32:33]
	s_mov_b32 m0, s46
	v_lshl_add_u64 v[216:217], s[14:15], 0, v[130:131]
	global_load_lds_dwordx4 v32, s[14:15]
	s_add_i32 m0, s46, 0x2000
	s_nop 0
	global_load_lds_dwordx4 v130, s[14:15]
	s_barrier
	s_waitcnt lgkmcnt(0)
	s_setprio 1
	s_waitcnt lgkmcnt(0)
	v_mfma_f32_16x16x32_bf16 v[114:117], v[194:197], v[162:165], v[114:117]
	v_mfma_f32_16x16x32_bf16 v[106:109], v[202:205], v[162:165], v[106:109]
	v_mfma_f32_16x16x32_bf16 v[98:101], v[194:197], v[170:173], v[98:101]
	v_mfma_f32_16x16x32_bf16 v[90:93], v[202:205], v[170:173], v[90:93]
	v_mfma_f32_16x16x32_bf16 v[82:85], v[194:197], v[178:181], v[82:85]
	v_mfma_f32_16x16x32_bf16 v[74:77], v[202:205], v[178:181], v[74:77]
	v_mfma_f32_16x16x32_bf16 v[70:73], v[194:197], v[186:189], v[70:73]
	v_mfma_f32_16x16x32_bf16 v[66:69], v[202:205], v[186:189], v[66:69]
	v_mfma_f32_16x16x32_bf16 v[114:117], v[198:201], v[166:169], v[114:117]
	v_mfma_f32_16x16x32_bf16 v[106:109], v[206:209], v[166:169], v[106:109]
	v_mfma_f32_16x16x32_bf16 v[98:101], v[198:201], v[174:177], v[98:101]
	v_mfma_f32_16x16x32_bf16 v[90:93], v[206:209], v[174:177], v[90:93]
	v_mfma_f32_16x16x32_bf16 v[82:85], v[198:201], v[182:185], v[82:85]
	v_mfma_f32_16x16x32_bf16 v[74:77], v[206:209], v[182:185], v[74:77]
	v_mfma_f32_16x16x32_bf16 v[70:73], v[198:201], v[190:193], v[70:73]
	v_mfma_f32_16x16x32_bf16 v[66:69], v[206:209], v[190:193], v[66:69]
	s_setprio 0
	s_mov_b32 m0, s9
	v_lshl_add_u64 v[218:219], s[20:21], 0, v[134:135]
	s_barrier
	ds_read_b128 v[162:165], v145 offset:16384
	ds_read_b128 v[166:169], v145 offset:17408
	ds_read_b128 v[170:173], v145 offset:18432
	ds_read_b128 v[174:177], v145 offset:19456
	ds_read_b128 v[178:181], v145 offset:20480
	ds_read_b128 v[182:185], v145 offset:21504
	ds_read_b128 v[186:189], v145 offset:22528
	ds_read_b128 v[190:193], v145 offset:23552
	global_load_lds_dwordx4 v134, s[20:21]
	v_lshl_add_u64 v[220:221], s[20:21], 0, v[132:133]
	s_mov_b32 m0, s11
	s_nop 0
	global_load_lds_dwordx4 v132, s[20:21]
	s_barrier
	s_waitcnt lgkmcnt(0)
	s_setprio 1
	s_waitcnt lgkmcnt(0)
	v_mfma_f32_16x16x32_bf16 v[62:65], v[146:149], v[162:165], v[62:65]
	v_mfma_f32_16x16x32_bf16 v[58:61], v[154:157], v[162:165], v[58:61]
	v_mfma_f32_16x16x32_bf16 v[54:57], v[146:149], v[170:173], v[54:57]
	v_mfma_f32_16x16x32_bf16 v[46:49], v[154:157], v[170:173], v[46:49]
	v_mfma_f32_16x16x32_bf16 v[38:41], v[146:149], v[178:181], v[38:41]
	v_mfma_f32_16x16x32_bf16 v[28:31], v[154:157], v[178:181], v[28:31]
	v_mfma_f32_16x16x32_bf16 v[20:23], v[146:149], v[186:189], v[20:23]
	v_mfma_f32_16x16x32_bf16 v[12:15], v[154:157], v[186:189], v[12:15]
	v_mfma_f32_16x16x32_bf16 v[62:65], v[150:153], v[166:169], v[62:65]
	v_mfma_f32_16x16x32_bf16 v[58:61], v[158:161], v[166:169], v[58:61]
	v_mfma_f32_16x16x32_bf16 v[54:57], v[150:153], v[174:177], v[54:57]
	v_mfma_f32_16x16x32_bf16 v[46:49], v[158:161], v[174:177], v[46:49]
	v_mfma_f32_16x16x32_bf16 v[38:41], v[150:153], v[182:185], v[38:41]
	v_mfma_f32_16x16x32_bf16 v[28:31], v[158:161], v[182:185], v[28:31]
	v_mfma_f32_16x16x32_bf16 v[20:23], v[150:153], v[190:193], v[20:23]
	v_mfma_f32_16x16x32_bf16 v[12:15], v[158:161], v[190:193], v[12:15]
	s_setprio 0
	s_barrier
; #define PG8_STAGE(bufoff, gbase, voff) do { _Pragma("unroll") for (int _i = 0; _i < 2; ++_i) \
;         __builtin_amdgcn_global_load_lds((const unsigned*)((const char*)(gbase) + (voff)[_i]), (LAS unsigned*)(lds + (bufoff) + ldsw + _i * 8192), 16, 0, 0); } while (0)
; #define PG8_LDA(dst, b, h) do { _Pragma("unroll") for (int m = 0; m < 4; ++m) _Pragma("unroll") for (int k = 0; k < 2; ++k) dst[m][k] = *(const LAS bf16x8*)(lds + PG8_SA(b, h) + aoff + m * 2048 + k * 1024); } while (0)
; #define PG8_LDB(dst, b, h) do { _Pragma("unroll") for (int n = 0; n < 2; ++n) _Pragma("unroll") for (int k = 0; k < 2; ++k) dst[n][k] = *(const LAS bf16x8*)(lds + PG8_SB(b, h) + boff + n * 2048 + k * 1024); } while (0)
; #define PG8_MMA(ai, bj, At, Bt) do { __builtin_amdgcn_s_setprio(1); _Pragma("unroll") for (int m = 0; m < 4; ++m) _Pragma("unroll") for (int n = 0; n < 2; ++n) _Pragma("unroll") for (int k = 0; k < 2; ++k) \
;         acc[ai][bj][m][n] = __builtin_amdgcn_mfma_f32_16x16x32_bf16(Bt[n][k], At[m][k], acc[ai][bj][m][n], 0, 0, 0); __builtin_amdgcn_s_setprio(0); } while (0)
; #define PG8_WAIT_V(n) asm volatile("s_waitcnt vmcnt(" #n ")" ::: "memory")
; #define PG8_WAIT_L(n) asm volatile("s_waitcnt lgkmcnt(" #n ")" ::: "memory")
; #define PG8_BAR __builtin_amdgcn_s_barrier()
; #define PG8_SCHED __builtin_amdgcn_sched_barrier(0)
; template <class Epi, class Sched>
; __device__ __forceinline__ void gemm_phase(LAS unsigned char* lds, const Gemm g, const Sched& S, const Epi& E, int tid_in) {
;     ...
;             PG8_STAGE(PG8_SB(0, 1), b2 + hstepB, voffB);
;             PG8_WAIT_V(6); PG8_BAR; PG8_MMA(1, 1, At, B1); PG8_BAR;
;             PG8_LDB(B0, 1, 0); PG8_SCHED; PG8_LDA(At, 1, 0); PG8_STAGE(PG8_SA(0, 1), a2 + hstepA, voffA);
;             PG8_WAIT_L(8); PG8_BAR; PG8_WAIT_L(0); PG8_MMA(0, 0, At, B0); PG8_BAR; PG8_SCHED;
;             PG8_LDB(B1, 1, 1); PG8_STAGE(PG8_SB(1, 0), b3, voffB);
;             PG8_BAR; PG8_WAIT_L(0); PG8_MMA(0, 1, At, B1); PG8_BAR;
;             PG8_LDA(At, 1, 1); PG8_STAGE(PG8_SA(1, 0), a3, voffA);
	s_add_u32 s46, s14, 0x80000
	s_addc_u32 s47, s15, 0
	s_add_i32 s48, s48, s31
	s_mov_b32 m0, s48
	s_nop 0
	global_load_lds_dwordx4 v32, s[46:47]
	s_add_i32 m0, s48, 0x2000
	s_nop 0
	global_load_lds_dwordx4 v130, s[46:47]
	s_waitcnt vmcnt(6)
	s_barrier
	s_setprio 1
	v_mfma_f32_16x16x32_bf16 v[50:53], v[194:197], v[162:165], v[50:53]
	v_mfma_f32_16x16x32_bf16 v[42:45], v[202:205], v[162:165], v[42:45]
	v_mfma_f32_16x16x32_bf16 v[34:37], v[194:197], v[170:173], v[34:37]
	v_mfma_f32_16x16x32_bf16 v[24:27], v[202:205], v[170:173], v[24:27]
	v_mfma_f32_16x16x32_bf16 v[16:19], v[194:197], v[178:181], v[16:19]
	v_mfma_f32_16x16x32_bf16 v[8:11], v[202:205], v[178:181], v[8:11]
	v_mfma_f32_16x16x32_bf16 v[4:7], v[194:197], v[186:189], v[4:7]
	v_mfma_f32_16x16x32_bf16 v[0:3], v[202:205], v[186:189], v[0:3]
	v_mfma_f32_16x16x32_bf16 v[50:53], v[198:201], v[166:169], v[50:53]
	v_mfma_f32_16x16x32_bf16 v[42:45], v[206:209], v[166:169], v[42:45]
	v_mfma_f32_16x16x32_bf16 v[34:37], v[198:201], v[174:177], v[34:37]
	v_mfma_f32_16x16x32_bf16 v[24:27], v[206:209], v[174:177], v[24:27]
	v_mfma_f32_16x16x32_bf16 v[16:19], v[198:201], v[182:185], v[16:19]
	v_mfma_f32_16x16x32_bf16 v[8:11], v[206:209], v[182:185], v[8:11]
	v_mfma_f32_16x16x32_bf16 v[4:7], v[198:201], v[190:193], v[4:7]
	v_mfma_f32_16x16x32_bf16 v[0:3], v[206:209], v[190:193], v[0:3]
	s_setprio 0
	s_add_i32 s46, 0, 0x18000
	v_add_u32_e32 v158, s46, v143
	s_barrier
	ds_read_b128 v[146:149], v158
	ds_read_b128 v[150:153], v158 offset:1024
	ds_read_b128 v[154:157], v158 offset:2048
	ds_read_b128 v[158:161], v158 offset:3072
	s_add_u32 s20, s20, 0x80000
	s_addc_u32 s21, s21, 0
	s_mov_b32 m0, s35
	ds_read_b128 v[162:165], v145 offset:32768
	ds_read_b128 v[166:169], v145 offset:33792
	ds_read_b128 v[170:173], v145 offset:34816
	ds_read_b128 v[174:177], v145 offset:35840
	ds_read_b128 v[178:181], v145 offset:36864
	ds_read_b128 v[182:185], v145 offset:37888
	ds_read_b128 v[186:189], v145 offset:38912
	ds_read_b128 v[190:193], v145 offset:39936
	global_load_lds_dwordx4 v134, s[20:21]
	s_mov_b32 m0, s36
	s_nop 0
	global_load_lds_dwordx4 v132, s[20:21]
	s_waitcnt lgkmcnt(8)
	s_barrier
	s_waitcnt lgkmcnt(0)
	s_setprio 1
	s_waitcnt lgkmcnt(0)
	v_mfma_f32_16x16x32_bf16 v[126:129], v[146:149], v[162:165], v[126:129]
	v_mfma_f32_16x16x32_bf16 v[122:125], v[154:157], v[162:165], v[122:125]
	v_mfma_f32_16x16x32_bf16 v[118:121], v[146:149], v[170:173], v[118:121]
	v_mfma_f32_16x16x32_bf16 v[110:113], v[154:157], v[170:173], v[110:113]
	v_mfma_f32_16x16x32_bf16 v[102:105], v[146:149], v[178:181], v[102:105]
	v_mfma_f32_16x16x32_bf16 v[94:97], v[154:157], v[178:181], v[94:97]
	v_mfma_f32_16x16x32_bf16 v[86:89], v[146:149], v[186:189], v[86:89]
	v_mfma_f32_16x16x32_bf16 v[78:81], v[154:157], v[186:189], v[78:81]
	v_mfma_f32_16x16x32_bf16 v[126:129], v[150:153], v[166:169], v[126:129]
	v_mfma_f32_16x16x32_bf16 v[122:125], v[158:161], v[166:169], v[122:125]
	v_mfma_f32_16x16x32_bf16 v[118:121], v[150:153], v[174:177], v[118:121]
	v_mfma_f32_16x16x32_bf16 v[110:113], v[158:161], v[174:177], v[110:113]
	v_mfma_f32_16x16x32_bf16 v[102:105], v[150:153], v[182:185], v[102:105]
	v_mfma_f32_16x16x32_bf16 v[94:97], v[158:161], v[182:185], v[94:97]
	v_mfma_f32_16x16x32_bf16 v[86:89], v[150:153], v[190:193], v[86:89]
	v_mfma_f32_16x16x32_bf16 v[78:81], v[158:161], v[190:193], v[78:81]
	s_setprio 0
	s_barrier
	s_add_i32 s20, 0, 0x1c000
	s_add_i32 s21, s46, s31
	v_add_u32_e32 v206, s20, v143
	v_lshl_add_u64 v[140:141], v[140:141], 0, s[76:77]
	s_mov_b32 m0, s21
	ds_read_b128 v[194:197], v206
	ds_read_b128 v[198:201], v206 offset:1024
	ds_read_b128 v[202:205], v206 offset:2048
	ds_read_b128 v[206:209], v206 offset:3072
	global_load_lds_dwordx4 v[140:141], off
	v_lshl_add_u64 v[140:141], v[216:217], 0, s[76:77]
	s_add_i32 m0, s21, 0x2000
	s_nop 0
	global_load_lds_dwordx4 v[140:141], off
	s_barrier
	s_waitcnt lgkmcnt(0)
	s_setprio 1
	s_waitcnt lgkmcnt(0)
	v_mfma_f32_16x16x32_bf16 v[114:117], v[194:197], v[162:165], v[114:117]
	v_mfma_f32_16x16x32_bf16 v[106:109], v[202:205], v[162:165], v[106:109]
	v_mfma_f32_16x16x32_bf16 v[98:101], v[194:197], v[170:173], v[98:101]
	v_mfma_f32_16x16x32_bf16 v[90:93], v[202:205], v[170:173], v[90:93]
	v_mfma_f32_16x16x32_bf16 v[82:85], v[194:197], v[178:181], v[82:85]
	v_mfma_f32_16x16x32_bf16 v[74:77], v[202:205], v[178:181], v[74:77]
	v_mfma_f32_16x16x32_bf16 v[70:73], v[194:197], v[186:189], v[70:73]
	v_mfma_f32_16x16x32_bf16 v[66:69], v[202:205], v[186:189], v[66:69]
	v_mfma_f32_16x16x32_bf16 v[114:117], v[198:201], v[166:169], v[114:117]
	v_mfma_f32_16x16x32_bf16 v[106:109], v[206:209], v[166:169], v[106:109]
	v_mfma_f32_16x16x32_bf16 v[98:101], v[198:201], v[174:177], v[98:101]
	v_mfma_f32_16x16x32_bf16 v[90:93], v[206:209], v[174:177], v[90:93]
	v_mfma_f32_16x16x32_bf16 v[82:85], v[198:201], v[182:185], v[82:85]
	v_mfma_f32_16x16x32_bf16 v[74:77], v[206:209], v[182:185], v[74:77]
	v_mfma_f32_16x16x32_bf16 v[70:73], v[198:201], v[190:193], v[70:73]
	v_mfma_f32_16x16x32_bf16 v[66:69], v[206:209], v[190:193], v[66:69]
	s_setprio 0
	s_mov_b32 m0, s37
	v_lshl_add_u64 v[140:141], v[218:219], 0, s[76:77]
	s_barrier
	ds_read_b128 v[162:165], v145 offset:49152
	ds_read_b128 v[166:169], v145 offset:50176
	ds_read_b128 v[170:173], v145 offset:51200
	ds_read_b128 v[174:177], v145 offset:52224
	ds_read_b128 v[178:181], v145 offset:53248
	ds_read_b128 v[182:185], v145 offset:54272
	ds_read_b128 v[186:189], v145 offset:55296
	ds_read_b128 v[190:193], v145 offset:56320
	global_load_lds_dwordx4 v[140:141], off
	v_lshl_add_u64 v[140:141], v[220:221], 0, s[76:77]
	s_mov_b32 m0, s38
	s_nop 0
	global_load_lds_dwordx4 v[140:141], off
	s_barrier
; #define PG8_STAGE(bufoff, gbase, voff) do { _Pragma("unroll") for (int _i = 0; _i < 2; ++_i) \
;         __builtin_amdgcn_global_load_lds((const unsigned*)((const char*)(gbase) + (voff)[_i]), (LAS unsigned*)(lds + (bufoff) + ldsw + _i * 8192), 16, 0, 0); } while (0)
; #define PG8_MMA(ai, bj, At, Bt) do { __builtin_amdgcn_s_setprio(1); _Pragma("unroll") for (int m = 0; m < 4; ++m) _Pragma("unroll") for (int n = 0; n < 2; ++n) _Pragma("unroll") for (int k = 0; k < 2; ++k) \
;         acc[ai][bj][m][n] = __builtin_amdgcn_mfma_f32_16x16x32_bf16(Bt[n][k], At[m][k], acc[ai][bj][m][n], 0, 0, 0); __builtin_amdgcn_s_setprio(0); } while (0)
; #define PG8_WAIT_V(n) asm volatile("s_waitcnt vmcnt(" #n ")" ::: "memory")
; #define PG8_WAIT_L(n) asm volatile("s_waitcnt lgkmcnt(" #n ")" ::: "memory")
; #define PG8_BAR __builtin_amdgcn_s_barrier()
; #define PG8_SCHED __builtin_amdgcn_sched_barrier(0)
; template <class Epi, class Sched>
; __device__ __forceinline__ void gemm_phase(LAS unsigned char* lds, const Gemm g, const Sched& S, const Epi& E, int tid_in) {
;     ...
;             PG8_BAR; PG8_WAIT_L(0); PG8_MMA(1, 0, At, B0); PG8_BAR; PG8_SCHED;
;             PG8_STAGE(PG8_SB(1, 1), b3 + hstepB, voffB);
;             PG8_WAIT_V(6); PG8_BAR; PG8_MMA(1, 1, At, B1); PG8_BAR;
;         }
	s_waitcnt lgkmcnt(0)
	s_setprio 1
	s_waitcnt lgkmcnt(0)
	v_mfma_f32_16x16x32_bf16 v[62:65], v[146:149], v[162:165], v[62:65]
	v_mfma_f32_16x16x32_bf16 v[58:61], v[154:157], v[162:165], v[58:61]
	v_mfma_f32_16x16x32_bf16 v[54:57], v[146:149], v[170:173], v[54:57]
	v_mfma_f32_16x16x32_bf16 v[46:49], v[154:157], v[170:173], v[46:49]
	v_mfma_f32_16x16x32_bf16 v[38:41], v[146:149], v[178:181], v[38:41]
	v_mfma_f32_16x16x32_bf16 v[28:31], v[154:157], v[178:181], v[28:31]
	v_mfma_f32_16x16x32_bf16 v[20:23], v[146:149], v[186:189], v[20:23]
	v_mfma_f32_16x16x32_bf16 v[12:15], v[154:157], v[186:189], v[12:15]
	v_mfma_f32_16x16x32_bf16 v[62:65], v[150:153], v[166:169], v[62:65]
	v_mfma_f32_16x16x32_bf16 v[58:61], v[158:161], v[166:169], v[58:61]
	v_mfma_f32_16x16x32_bf16 v[54:57], v[150:153], v[174:177], v[54:57]
	v_mfma_f32_16x16x32_bf16 v[46:49], v[158:161], v[174:177], v[46:49]
	v_mfma_f32_16x16x32_bf16 v[38:41], v[150:153], v[182:185], v[38:41]
	v_mfma_f32_16x16x32_bf16 v[28:31], v[158:161], v[182:185], v[28:31]
	v_mfma_f32_16x16x32_bf16 v[20:23], v[150:153], v[190:193], v[20:23]
	v_mfma_f32_16x16x32_bf16 v[12:15], v[158:161], v[190:193], v[12:15]
	s_setprio 0
	s_barrier
	s_add_u32 s14, s14, 0x80080
	s_addc_u32 s15, s15, 0
	s_add_i32 s20, s20, s31
	s_mov_b32 m0, s20
	s_nop 0
	global_load_lds_dwordx4 v32, s[14:15]
	v_lshl_add_u64 v[140:141], s[14:15], 0, v[130:131]
	s_add_i32 m0, s20, 0x2000
	s_nop 0
	global_load_lds_dwordx4 v130, s[14:15]
	s_waitcnt vmcnt(6)
	s_barrier
	s_setprio 1
	v_mfma_f32_16x16x32_bf16 v[50:53], v[194:197], v[162:165], v[50:53]
	v_mfma_f32_16x16x32_bf16 v[42:45], v[202:205], v[162:165], v[42:45]
	v_mfma_f32_16x16x32_bf16 v[34:37], v[194:197], v[170:173], v[34:37]
	v_mfma_f32_16x16x32_bf16 v[24:27], v[202:205], v[170:173], v[24:27]
	v_mfma_f32_16x16x32_bf16 v[16:19], v[194:197], v[178:181], v[16:19]
	v_mfma_f32_16x16x32_bf16 v[8:11], v[202:205], v[178:181], v[8:11]
	v_mfma_f32_16x16x32_bf16 v[4:7], v[194:197], v[186:189], v[4:7]
	v_mfma_f32_16x16x32_bf16 v[0:3], v[202:205], v[186:189], v[0:3]
	v_mfma_f32_16x16x32_bf16 v[50:53], v[198:201], v[166:169], v[50:53]
	v_mfma_f32_16x16x32_bf16 v[42:45], v[206:209], v[166:169], v[42:45]
	v_mfma_f32_16x16x32_bf16 v[34:37], v[198:201], v[174:177], v[34:37]
	v_mfma_f32_16x16x32_bf16 v[24:27], v[206:209], v[174:177], v[24:27]
	v_mfma_f32_16x16x32_bf16 v[16:19], v[198:201], v[182:185], v[16:19]
	v_mfma_f32_16x16x32_bf16 v[8:11], v[206:209], v[182:185], v[8:11]
	v_mfma_f32_16x16x32_bf16 v[4:7], v[198:201], v[190:193], v[4:7]
	v_mfma_f32_16x16x32_bf16 v[0:3], v[206:209], v[190:193], v[0:3]
	s_setprio 0
	s_add_i32 s45, s45, 2
	s_add_u32 s18, s18, 0x100
	s_addc_u32 s19, s19, 0
	s_add_u32 s43, s43, 0x100
	s_addc_u32 s44, s44, 0
	s_cmp_gt_u32 s45, 29
	s_barrier
	s_cbranch_scc0 .LBB0_2714
; __device__ __forceinline__ unsigned cvt_pk_bf16(float lo, float hi) { unsigned r; asm("v_cvt_pk_bf16_f32 %0, %1, %2" : "=v"(r) : "v"(lo), "v"(hi)); return r; }
;     __device__ __forceinline__ void operator()(const f32x4 (&acc)[2][2][4][2], const Unit& u, int wr, int wc, int fr, int fq) const {
;         const int row0 = u.pm * BM + wr * 64 + fr; const int col0 = u.pn * BM + wc * 32 + 8 * fq;
; #pragma unroll
;         for (int ai = 0; ai < 2; ++ai)
; #pragma unroll
;             for (int m = 0; m < 4; ++m) { bf16_t* rowp = O + (size_t)(row0 + ai * HALF + m * 16) * ldc + col0;
; #pragma unroll
;                 for (int bj = 0; bj < 2; ++bj) { const f32x4 v0 = acc[ai][bj][m][0], v1 = acc[ai][bj][m][1];
;                     u32x4 w; w.x = cvt_pk_bf16(v0[0], v0[1]); w.y = cvt_pk_bf16(v0[2], v0[3]); w.z = cvt_pk_bf16(v1[0], v1[1]); w.w = cvt_pk_bf16(v1[2], v1[3]);
;                     *(u32x4*)(rowp + bj * HALF) = w; } }
; template <class Epi, class Sched>
; __device__ __forceinline__ void gemm_phase(LAS unsigned char* lds, const Gemm g, const Sched& S, const Epi& E, int tid_in) {
;     ...
;         E(acc, cur, wr, wc, fr, fq); S.done(cur);
;         if (!has_next) break;
; #pragma unroll
;         for (int a = 0; a < 2; ++a)
; #pragma unroll
;             for (int b = 0; b < 2; ++b)
; #pragma unroll
;                 for (int m = 0; m < 4; ++m)
; #pragma unroll
;                     for (int n = 0; n < 2; ++n) acc[a][b][m][n] = (f32x4){0.f, 0.f, 0.f, 0.f};
;         cur = nxt; cA = nA; cB = nB; ++ui;
	v_lshl_add_u32 v146, s10, 8, v142
	v_lshl_or_b32 v140, s8, 8, v144
	v_ashrrev_i32_e32 v147, 31, v146
	v_ashrrev_i32_e32 v141, 31, v140
	v_lshlrev_b64 v[148:149], 12, v[146:147]
	v_lshl_add_u64 v[148:149], s[0:1], 0, v[148:149]
	v_lshlrev_b64 v[150:151], 1, v[140:141]
	v_lshl_add_u64 v[140:141], v[148:149], 0, v[150:151]
	v_cvt_pk_bf16_f32 v62, v62, v63
	v_cvt_pk_bf16_f32 v63, v64, v65
	v_cvt_pk_bf16_f32 v64, v58, v59
	v_add_co_u32_e32 v58, vcc, s49, v140
	v_cvt_pk_bf16_f32 v114, v114, v115
	v_cvt_pk_bf16_f32 v115, v116, v117
	v_cvt_pk_bf16_f32 v116, v106, v107
	v_or_b32_e32 v106, 16, v146
	s_nop 0
	v_addc_co_u32_e32 v59, vcc, 0, v141, vcc
	v_cvt_pk_bf16_f32 v50, v50, v51
	v_cvt_pk_bf16_f32 v51, v52, v53
	v_cvt_pk_bf16_f32 v53, v44, v45
	v_cvt_pk_bf16_f32 v44, v46, v47
	v_add_co_u32_e32 v46, vcc, s50, v140
	v_ashrrev_i32_e32 v107, 31, v106
	v_cvt_pk_bf16_f32 v98, v98, v99
	v_cvt_pk_bf16_f32 v99, v100, v101
	v_cvt_pk_bf16_f32 v100, v90, v91
	v_or_b32_e32 v90, 32, v146
	v_addc_co_u32_e32 v47, vcc, 0, v141, vcc
	v_lshlrev_b64 v[106:107], 12, v[106:107]
	v_ashrrev_i32_e32 v91, 31, v90
	v_cvt_pk_bf16_f32 v82, v82, v83
	v_cvt_pk_bf16_f32 v83, v84, v85
	v_cvt_pk_bf16_f32 v84, v74, v75
	v_or_b32_e32 v74, 48, v146
	s_mov_b64 s[14:15], 0x80000
	v_cvt_pk_bf16_f32 v34, v34, v35
	v_cvt_pk_bf16_f32 v35, v36, v37
	v_cvt_pk_bf16_f32 v37, v26, v27
	v_cvt_pk_bf16_f32 v26, v28, v29
	v_add_co_u32_e32 v28, vcc, s51, v140
	v_lshl_add_u64 v[106:107], s[0:1], 0, v[106:107]
	v_lshlrev_b64 v[90:91], 12, v[90:91]
	v_ashrrev_i32_e32 v75, 31, v74
	v_cvt_pk_bf16_f32 v70, v70, v71
	v_cvt_pk_bf16_f32 v71, v72, v73
	v_cvt_pk_bf16_f32 v72, v66, v67
	v_lshl_add_u64 v[66:67], v[140:141], 0, s[14:15]
	s_mov_b64 s[14:15], 0x90000
	v_addc_co_u32_e32 v29, vcc, 0, v141, vcc
	s_mov_b32 s5, 0xb0000
	v_cvt_pk_bf16_f32 v117, v108, v109
	global_store_dwordx4 v[140:141], v[114:117], off offset:256
	v_lshl_add_u64 v[90:91], s[0:1], 0, v[90:91]
	v_lshlrev_b64 v[74:75], 12, v[74:75]
	v_lshl_add_u64 v[114:115], v[106:107], 0, v[150:151]
	v_cvt_pk_bf16_f32 v52, v42, v43
	global_store_dwordx4 v[66:67], v[50:53], off offset:256
	v_cvt_pk_bf16_f32 v16, v16, v17
	v_cvt_pk_bf16_f32 v17, v18, v19
	v_cvt_pk_bf16_f32 v19, v10, v11
	v_cvt_pk_bf16_f32 v10, v12, v13
	v_add_co_u32_e32 v12, vcc, s5, v140
	s_nop 0
	v_lshl_add_u64 v[50:51], v[140:141], 0, s[14:15]
	s_mov_b64 s[14:15], 0xa0000
	v_cvt_pk_bf16_f32 v101, v92, v93
	global_store_dwordx4 v[114:115], v[98:101], off offset:256
	v_lshl_add_u64 v[74:75], s[0:1], 0, v[74:75]
	v_cvt_pk_bf16_f32 v36, v24, v25
	global_store_dwordx4 v[50:51], v[34:37], off offset:256
	v_lshl_add_u64 v[98:99], v[90:91], 0, v[150:151]
	v_addc_co_u32_e32 v13, vcc, 0, v141, vcc
	v_lshl_add_u64 v[34:35], v[140:141], 0, s[14:15]
	s_mov_b64 s[14:15], 0xb0000
	v_cvt_pk_bf16_f32 v85, v76, v77
	global_store_dwordx4 v[98:99], v[82:85], off offset:256
	v_cvt_pk_bf16_f32 v18, v8, v9
	global_store_dwordx4 v[34:35], v[16:19], off offset:256
	s_and_b64 vcc, exec, s[2:3]
	v_lshl_add_u64 v[82:83], v[74:75], 0, v[150:151]
	v_lshl_add_u64 v[16:17], v[140:141], 0, s[14:15]
	s_mov_b32 s8, s4
	s_mov_b32 s10, s6
	s_mov_b64 s[14:15], s[16:17]
	s_mov_b64 s[18:19], s[12:13]
	v_cvt_pk_bf16_f32 v126, v126, v127
	v_cvt_pk_bf16_f32 v127, v128, v129
	v_cvt_pk_bf16_f32 v128, v122, v123
	v_cvt_pk_bf16_f32 v129, v124, v125
	global_store_dwordx4 v[140:141], v[126:129], off
	v_cvt_pk_bf16_f32 v106, v118, v119
	v_cvt_pk_bf16_f32 v107, v120, v121
	v_cvt_pk_bf16_f32 v108, v110, v111
	v_cvt_pk_bf16_f32 v109, v112, v113
	global_store_dwordx4 v[114:115], v[106:109], off
	v_cvt_pk_bf16_f32 v90, v102, v103
	v_cvt_pk_bf16_f32 v91, v104, v105
	v_cvt_pk_bf16_f32 v92, v94, v95
	v_cvt_pk_bf16_f32 v93, v96, v97
	global_store_dwordx4 v[98:99], v[90:93], off
	v_cvt_pk_bf16_f32 v74, v86, v87
	v_cvt_pk_bf16_f32 v75, v88, v89
	v_cvt_pk_bf16_f32 v76, v78, v79
	v_cvt_pk_bf16_f32 v77, v80, v81
	global_store_dwordx4 v[82:83], v[74:77], off
	v_cvt_pk_bf16_f32 v73, v68, v69
	global_store_dwordx4 v[82:83], v[70:73], off offset:256
	v_cvt_pk_bf16_f32 v65, v60, v61
	global_store_dwordx4 v[58:59], v[62:65], off
	v_cvt_pk_bf16_f32 v42, v54, v55
	v_cvt_pk_bf16_f32 v43, v56, v57
	v_cvt_pk_bf16_f32 v45, v48, v49
	global_store_dwordx4 v[46:47], v[42:45], off
	v_cvt_pk_bf16_f32 v24, v38, v39
	v_cvt_pk_bf16_f32 v25, v40, v41
	v_cvt_pk_bf16_f32 v27, v30, v31
	global_store_dwordx4 v[28:29], v[24:27], off
	v_cvt_pk_bf16_f32 v8, v20, v21
	v_cvt_pk_bf16_f32 v9, v22, v23
	v_cvt_pk_bf16_f32 v11, v14, v15
	global_store_dwordx4 v[12:13], v[8:11], off
	v_cvt_pk_bf16_f32 v4, v4, v5
	v_cvt_pk_bf16_f32 v5, v6, v7
	v_cvt_pk_bf16_f32 v6, v0, v1
	v_cvt_pk_bf16_f32 v7, v2, v3
	global_store_dwordx4 v[16:17], v[4:7], off offset:256
	s_cbranch_vccz .LBB0_2711
	s_waitcnt vmcnt(0)
	v_readlane_b32 s40, v254, 35
	v_readlane_b32 s38, v254, 39
	s_cmp_gt_u32 s23, 3
	v_readlane_b32 s41, v254, 36
	v_readlane_b32 s39, v254, 40
	s_cbranch_scc1 .LBB0_2718
	s_barrier

; #define LAS __attribute__((address_space(3)))
; __global__ void __launch_bounds__(512, 2) mk_fwd(Params Pval) {
;     extern __shared__ __attribute__((aligned(16))) unsigned char lds_raw[];
;     LAS unsigned char* ldsl = (LAS unsigned char*)lds_raw;
;     volatile LAS unsigned* misc = (volatile LAS unsigned*)(ldsl + LDS_MISC);
;     if (threadIdx.x < 16) misc[threadIdx.x] = 0u;
;     __syncthreads();
;     XcdBarrier bar = xcd_barrier_post((unsigned*)(Pval.ws + WS_CTL) + 1024, misc);
;     const int wid0 = __builtin_amdgcn_readfirstlane((int)threadIdx.x >> 6);
;     const int lo = Pval.ph_lo, hi = Pval.ph_hi; int ph = 0;
	.amdhsa_kernel _Z6mk_fwd6Params
		.amdhsa_group_segment_fixed_size 0
		.amdhsa_private_segment_fixed_size 0
		.amdhsa_kernarg_size 504
		.amdhsa_user_sgpr_count 2
		.amdhsa_user_sgpr_dispatch_ptr 0
		.amdhsa_user_sgpr_queue_ptr 0
		.amdhsa_user_sgpr_kernarg_segment_ptr 1
		.amdhsa_user_sgpr_dispatch_id 0
		.amdhsa_user_sgpr_kernarg_preload_length 0
		.amdhsa_user_sgpr_kernarg_preload_offset 0
		.amdhsa_user_sgpr_private_segment_size 0
		.amdhsa_uses_dynamic_stack 0
		.amdhsa_enable_private_segment 0
		.amdhsa_system_sgpr_workgroup_id_x 1
		.amdhsa_system_sgpr_workgroup_id_y 0
		.amdhsa_system_sgpr_workgroup_id_z 0
		.amdhsa_system_sgpr_workgroup_info 0
		.amdhsa_system_vgpr_workitem_id 0
		.amdhsa_next_free_vgpr 256
		.amdhsa_next_free_sgpr 102
		.amdhsa_accum_offset 256
		.amdhsa_reserve_vcc 1
		.amdhsa_float_round_mode_32 0
		.amdhsa_float_round_mode_16_64 0
		.amdhsa_float_denorm_mode_32 3
		.amdhsa_float_denorm_mode_16_64 3
		.amdhsa_dx10_clamp 1
		.amdhsa_ieee_mode 1
		.amdhsa_fp16_overflow 0
		.amdhsa_tg_split 0
		.amdhsa_exception_fp_ieee_invalid_op 0
		.amdhsa_exception_fp_denorm_src 0
		.amdhsa_exception_fp_ieee_div_zero 0
		.amdhsa_exception_fp_ieee_overflow 0
		.amdhsa_exception_fp_ieee_underflow 0
		.amdhsa_exception_fp_ieee_inexact 0
		.amdhsa_exception_int_div_zero 0
	.end_amdhsa_kernel

; __global__ void __launch_bounds__(512, 2) mk_fwd(Params Pval) {
;     extern __shared__ __attribute__((aligned(16))) unsigned char lds_raw[];
amdhsa.kernels:
  - .agpr_count:     0
    .args:
      - .offset:         0
        .size:           248
        .value_kind:     by_value
      - .offset:         248
        .size:           4
        .value_kind:     hidden_block_count_x
      - .offset:         252
        .size:           4
        .value_kind:     hidden_block_count_y
      - .offset:         256
        .size:           4
        .value_kind:     hidden_block_count_z
      - .offset:         260
        .size:           2
        .value_kind:     hidden_group_size_x
      - .offset:         262
        .size:           2
        .value_kind:     hidden_group_size_y
      - .offset:         264
        .size:           2
        .value_kind:     hidden_group_size_z
      - .offset:         266
        .size:           2
        .value_kind:     hidden_remainder_x
      - .offset:         268
        .size:           2
        .value_kind:     hidden_remainder_y
      - .offset:         270
        .size:           2
        .value_kind:     hidden_remainder_z
      - .offset:         288
        .size:           8
        .value_kind:     hidden_global_offset_x
      - .offset:         296
        .size:           8
        .value_kind:     hidden_global_offset_y
      - .offset:         304
        .size:           8
        .value_kind:     hidden_global_offset_z
      - .offset:         312
        .size:           2
        .value_kind:     hidden_grid_dims
      - .offset:         368
        .size:           4
        .value_kind:     hidden_dynamic_lds_size
    .group_segment_fixed_size: 0
    .kernarg_segment_align: 8
    .kernarg_segment_size: 504
    .language:       OpenCL C
    .language_version:
      - 2
      - 0
    .max_flat_workgroup_size: 512
    .name:           _Z6mk_fwd6Params
    .private_segment_fixed_size: 0
    .sgpr_count:     108
    .sgpr_spill_count: 139
    .symbol:         _Z6mk_fwd6Params.kd
    .uniform_work_group_size: 1
    .uses_dynamic_stack: false
    .vgpr_count:     256
    .vgpr_spill_count: 0
    .wavefront_size: 64
